# P4 v2: consumer y via deferred 16-step transpose-reduce (26 instr/step), 4 aux waves each produce one pass + convert one 16x64 weight tile per block, exact vmcnt, swizzled LDS records, XCD-colocated s
# speedup vs baseline: 1.0923x; 1.0068x over previous
; #define WG_BAR() do { asm volatile("s_waitcnt lgkmcnt(0)" ::: "memory"); __builtin_amdgcn_s_barrier(); asm volatile("" ::: "memory"); } while (0)
; __global__ void __launch_bounds__(NTHR) hymba_fwd(Params P) {
;     ...
;         for (int unit = bid; unit < 256; unit += G) {
;             const int s = unit >> 2, b = s >> 4, h = s & 15, q = unit & 3;
;             const int wv = __builtin_amdgcn_readfirstlane(tid >> 6);
;             if (wv < 2) {
;     ...
;               const int pw = (wv & 1) + ((wv >> 2) << 1), ch = h * 64 + lane;
;               const float c_kk = k_k[ch], c_ka = k_a[ch], c_rk = r_k[ch], mu_r = mu_shift[ch], mu_k = mu_shift[CW + ch], mu_v = mu_shift[2 * CW + ch];
;               const bf16_t* pbase = Proj + (size_t)(b * TT) * PJP + PW + h * 64; const float* dbase = Dec + (size_t)(b * TT) * CW + h * 64; const bf16_t* abase = Ab + (size_t)(b * TT) * CW + h * 64;
;               constexpr int PD = 2;
;               unsigned short rr[PD][NPS + 1], kr_[PD][NPS + 1], vr[PD][NPS + 1], aa[PD][NPS]; float dd[PD][NPS];
;     ...
;               SCAN_LOAD(0, 0); SCAN_LOAD(1, 1);
;               SCAN_PRODUCE(0, 0); SCAN_LOAD(2, 0);
;               WG_BAR();
.LBB0_673:
	s_ashr_i32 s35, s34, 6
	s_and_b32 s92, s34, 7
	s_lshr_b32 s93, s34, 2
	s_and_b32 s93, s93, 8
	s_or_b32 s92, s92, s93
	s_bfe_u32 s93, s34, 0x20003
	v_readfirstlane_b32 s95, v137
	s_cmp_gt_i32 s95, 3
	s_mov_b64 s[4:5], -1
	s_cbranch_scc0 .LBB0_851
	s_add_i32 s15, s95, -4
	v_and_b32_e32 v210, 7, v136
	v_lshrrev_b32_e32 v211, 3, v136
	v_readlane_b32 s4, v234, 0
	v_readlane_b32 s5, v234, 1
	s_nop 3
	s_sub_u32 s4, s4, 0xe8
	s_subb_u32 s5, s5, 0
	s_load_dwordx2 s[22:23], s[4:5], 0x48
	s_load_dwordx4 s[8:11], s[4:5], 0x78
	s_load_dwordx2 s[26:27], s[4:5], 0x88
	s_lshl_b32 s33, s92, 8
	v_lshl_add_u32 v212, v210, 5, s33
	s_waitcnt lgkmcnt(0)
	s_add_u32 s60, s22, 0x1000
	s_addc_u32 s61, s23, 0
	s_add_u32 s62, s22, 0x2000
	s_addc_u32 s63, s23, 0
	global_load_dwordx4 v[2:5], v212, s[22:23]
	global_load_dwordx4 v[6:9], v212, s[22:23] offset:16
	global_load_dwordx4 v[10:13], v212, s[60:61]
	global_load_dwordx4 v[14:17], v212, s[60:61] offset:16
	global_load_dwordx4 v[18:21], v212, s[62:63]
	global_load_dwordx4 v[22:25], v212, s[62:63] offset:16
	global_load_dwordx4 v[26:29], v212, s[8:9]
	global_load_dwordx4 v[30:33], v212, s[8:9] offset:16
	global_load_dwordx4 v[34:37], v212, s[10:11]
	global_load_dwordx4 v[38:41], v212, s[10:11] offset:16
	global_load_dwordx4 v[50:53], v212, s[26:27]
	global_load_dwordx4 v[54:57], v212, s[26:27] offset:16
	s_load_dwordx4 s[8:11], s[4:5], 0xb0
	s_load_dwordx2 s[22:23], s[4:5], 0xc0
	s_load_dwordx2 s[26:27], s[4:5], 0xa0
	s_lshl_b32 s33, s34, 2
	s_add_i32 s33, s33, s15
	s_lshl_b32 s4, s35, 11
	s_lshl_b32 s5, s15, 3
	s_add_i32 s4, s4, s5
	s_mul_i32 s5, s4, 0x2400
	s_lshl_b32 s40, s92, 7
	s_add_i32 s40, s40, 0x800
	s_add_u32 s56, s90, 0x7f00000
	s_addc_u32 s57, s91, 0
	s_add_u32 s56, s56, s5
	s_addc_u32 s57, s57, 0
	s_add_u32 s56, s56, s40
	s_addc_u32 s57, s57, 0
	s_sub_u32 s56, s56, 0x2400
	s_subb_u32 s57, s57, 0
	s_add_u32 s58, s56, 0x1000
	s_addc_u32 s59, s57, 0
	s_lshl_b32 s5, s4, 11
	s_lshl_b32 s40, s92, 7
	s_add_u32 s60, s90, 0xc940000
	s_addc_u32 s61, s91, 0
	s_add_u32 s60, s60, s5
	s_addc_u32 s61, s61, 0
	s_add_u32 s60, s60, s40
	s_addc_u32 s61, s61, 0
	s_lshl_b32 s5, s4, 12
	s_lshl_b32 s40, s92, 8
	s_add_u32 s62, s88, 0x2000000
	s_addc_u32 s63, s89, 0
	s_add_u32 s62, s62, s5
	s_addc_u32 s63, s63, 0
	s_add_u32 s62, s62, s40
	s_addc_u32 s63, s63, 0
	s_lshl_b32 s5, s4, 6
	s_lshl_b32 s40, s92, 2
	s_add_u32 s64, s90, 0x10b50800
	s_addc_u32 s65, s91, 0
	s_add_u32 s64, s64, s5
	s_addc_u32 s65, s65, 0
	s_add_u32 s64, s64, s40
	s_addc_u32 s65, s65, 0
	s_mov_b32 s52, 0x1010101
	s_mov_b32 s53, 0x1010101
	v_mul_u32_u24_e32 v155, 0x2400, v211
	v_lshl_add_u32 v155, v210, 4, v155
	v_add_u32_e32 v0, 0x2400, v155
	v_lshlrev_b32_e32 v197, 11, v211
	v_lshl_add_u32 v197, v210, 4, v197
	v_lshlrev_b32_e32 v204, 12, v211
	v_lshl_add_u32 v204, v210, 5, v204
	v_lshlrev_b32_e32 v205, 6, v211
	v_lshl_add_u32 v206, s15, 3, v211
	v_mul_u32_u24_e32 v206, 0x700, v206
	v_lshrrev_b32_e32 v208, 2, v210
	v_lshlrev_b32_e32 v209, 1, v210
	v_xor_b32_e32 v207, v209, v208
	v_xor_b32_e32 v209, 1, v207
	v_lshl_add_u32 v207, v207, 4, v206
	v_lshl_add_u32 v209, v209, 4, v206
	v_mov_b32_e32 v206, v207
	v_mov_b32_e32 v207, v209
	v_add_u32_e32 v208, 0xe000, v206
	v_add_u32_e32 v209, 0xe000, v207
	v_mov_b32_e32 v229, v136
	v_lshlrev_b32_e32 v226, 2, v136
	global_load_dwordx4 v[58:61], v0, s[56:57]
	global_load_dwordx4 v[62:65], v0, s[56:57] offset:2048
	global_load_dwordx4 v[66:69], v0, s[58:59]
	global_load_dwordx4 v[70:73], v155, s[56:57]
	global_load_dwordx4 v[74:77], v155, s[56:57] offset:2048
	global_load_dwordx4 v[78:81], v155, s[58:59]
	global_load_dwordx4 v[82:85], v197, s[60:61]
	global_load_dwordx4 v[86:89], v204, s[62:63]
	global_load_dwordx4 v[90:93], v204, s[62:63] offset:16
	s_add_u32 s56, s56, 0x48000
	s_addc_u32 s57, s57, 0
	s_add_u32 s58, s58, 0x48000
	s_addc_u32 s59, s59, 0
	s_add_u32 s60, s60, 0x10000
	s_addc_u32 s61, s61, 0
	s_add_u32 s62, s62, 0x20000
	s_addc_u32 s63, s63, 0
	global_load_dwordx4 v[94:97], v0, s[56:57]
	global_load_dwordx4 v[98:101], v0, s[56:57] offset:2048
	global_load_dwordx4 v[102:105], v0, s[58:59]
	global_load_dwordx4 v[106:109], v155, s[56:57]
	global_load_dwordx4 v[110:113], v155, s[56:57] offset:2048
	global_load_dwordx4 v[114:117], v155, s[58:59]
	global_load_dwordx4 v[118:121], v197, s[60:61]
	global_load_dwordx4 v[122:125], v204, s[62:63]
	global_load_dwordx4 v[126:129], v204, s[62:63] offset:16
	s_add_u32 s56, s56, 0x48000
	s_addc_u32 s57, s57, 0
	s_add_u32 s58, s58, 0x48000
	s_addc_u32 s59, s59, 0
	s_add_u32 s60, s60, 0x10000
	s_addc_u32 s61, s61, 0
	s_add_u32 s62, s62, 0x20000
	s_addc_u32 s63, s63, 0
	s_waitcnt vmcnt(18)
	v_sub_f32_e32 v42, 1.0, v34
	v_sub_f32_e32 v43, 1.0, v35
	v_sub_f32_e32 v44, 1.0, v36
	v_sub_f32_e32 v45, 1.0, v37
	v_sub_f32_e32 v46, 1.0, v38
	v_sub_f32_e32 v47, 1.0, v39
	v_sub_f32_e32 v48, 1.0, v40
	v_sub_f32_e32 v49, 1.0, v41
	s_waitcnt lgkmcnt(0)
	s_movk_i32 s14, 0
	s_waitcnt vmcnt(9)
	s_cmp_eq_u32 s15, 0
	s_cbranch_scc0 .Lp4a_nofix
	s_mov_b64 exec, 0xff
	v_mov_b32_e32 v70, 0
	v_mov_b32_e32 v71, 0
	v_mov_b32_e32 v72, 0
	v_mov_b32_e32 v73, 0
	v_mov_b32_e32 v74, 0
	v_mov_b32_e32 v75, 0
	v_mov_b32_e32 v76, 0
	v_mov_b32_e32 v77, 0
	v_mov_b32_e32 v78, 0
	v_mov_b32_e32 v79, 0
	v_mov_b32_e32 v80, 0
	v_mov_b32_e32 v81, 0
	s_mov_b64 exec, -1
.Lp4a_nofix:
	v_mov_b32_e32 v134, 0
	v_mov_b32_e32 v135, 0
	v_mov_b32_e32 v148, 0
	v_mov_b32_e32 v149, 0
	v_mov_b32_e32 v192, 0
	v_mov_b32_e32 v193, 0
	v_mov_b32_e32 v194, 0
	v_mov_b32_e32 v195, 0
	v_lshlrev_b32_e32 v180, 16, v58
	v_and_b32_e32 v181, 0xffff0000, v58
	v_lshlrev_b32_e32 v182, 16, v59
	v_and_b32_e32 v183, 0xffff0000, v59
	v_lshlrev_b32_e32 v184, 16, v70
	v_and_b32_e32 v185, 0xffff0000, v70
	v_lshlrev_b32_e32 v186, 16, v71
	v_and_b32_e32 v187, 0xffff0000, v71
	v_pk_add_f32 v[184:185], v[184:185], v[180:181] neg_lo:[0,1] neg_hi:[0,1]
	v_pk_add_f32 v[186:187], v[186:187], v[182:183] neg_lo:[0,1] neg_hi:[0,1]
	v_pk_fma_f32 v[184:185], v[184:185], v[2:3], v[180:181]
	v_pk_fma_f32 v[186:187], v[186:187], v[4:5], v[182:183]
	v_lshlrev_b32_e32 v180, 16, v62
	v_and_b32_e32 v181, 0xffff0000, v62
	v_lshlrev_b32_e32 v182, 16, v63
	v_and_b32_e32 v183, 0xffff0000, v63
	v_lshlrev_b32_e32 v130, 16, v74
	v_and_b32_e32 v131, 0xffff0000, v74
	v_lshlrev_b32_e32 v132, 16, v75
	v_and_b32_e32 v133, 0xffff0000, v75
	v_pk_add_f32 v[130:131], v[130:131], v[180:181] neg_lo:[0,1] neg_hi:[0,1]
	v_pk_add_f32 v[132:133], v[132:133], v[182:183] neg_lo:[0,1] neg_hi:[0,1]
	v_pk_fma_f32 v[130:131], v[130:131], v[10:11], v[180:181]
	v_pk_fma_f32 v[132:133], v[132:133], v[12:13], v[182:183]
	v_lshlrev_b32_e32 v180, 16, v66
	v_and_b32_e32 v181, 0xffff0000, v66
	v_lshlrev_b32_e32 v182, 16, v67
	v_and_b32_e32 v183, 0xffff0000, v67
	v_lshlrev_b32_e32 v164, 16, v78
	v_and_b32_e32 v165, 0xffff0000, v78
	v_lshlrev_b32_e32 v166, 16, v79
	v_and_b32_e32 v167, 0xffff0000, v79
	v_pk_add_f32 v[164:165], v[164:165], v[180:181] neg_lo:[0,1] neg_hi:[0,1]
	v_pk_add_f32 v[166:167], v[166:167], v[182:183] neg_lo:[0,1] neg_hi:[0,1]
	v_pk_fma_f32 v[164:165], v[164:165], v[18:19], v[180:181]
	v_pk_fma_f32 v[166:167], v[166:167], v[20:21], v[182:183]
	ds_write_b128 v206, v[164:167] offset:1280
	v_lshlrev_b32_e32 v188, 16, v82
	v_and_b32_e32 v189, 0xffff0000, v82
	v_lshlrev_b32_e32 v190, 16, v83
	v_and_b32_e32 v191, 0xffff0000, v83
	v_pk_mul_f32 v[140:141], v[130:131], v[26:27]
	v_pk_mul_f32 v[142:143], v[132:133], v[28:29]
	v_pk_fma_f32 v[134:135], v[140:141], v[140:141], v[134:135]
	v_pk_fma_f32 v[134:135], v[142:143], v[142:143], v[134:135]
	v_pk_fma_f32 v[180:181], v[188:189], v[34:35], v[42:43]
	v_pk_fma_f32 v[182:183], v[190:191], v[36:37], v[44:45]
	v_pk_mul_f32 v[180:181], v[130:131], v[180:181]
	v_pk_mul_f32 v[182:183], v[132:133], v[182:183]
	ds_write_b128 v206, v[180:183] offset:768
	v_pk_mul_f32 v[130:131], v[180:181], v[184:185]
	v_pk_mul_f32 v[132:133], v[182:183], v[186:187]
	v_pk_add_f32 v[192:193], v[192:193], v[130:131]
	v_pk_add_f32 v[192:193], v[192:193], v[132:133]
	v_pk_fma_f32 v[194:195], v[130:131], v[50:51], v[194:195]
	v_pk_fma_f32 v[194:195], v[132:133], v[52:53], v[194:195]
	v_pk_mul_f32 v[156:157], v[140:141], v[188:189]
	v_pk_mul_f32 v[158:159], v[142:143], v[190:191]
	v_pk_fma_f32 v[148:149], v[156:157], v[184:185], v[148:149]
	v_pk_fma_f32 v[148:149], v[158:159], v[186:187], v[148:149]
	v_pk_mul_f32 v[172:173], v[86:87], v[184:185]
	v_pk_mul_f32 v[174:175], v[88:89], v[186:187]
	ds_write_b128 v206, v[86:89] offset:512
	v_lshlrev_b32_e32 v180, 16, v60
	v_and_b32_e32 v181, 0xffff0000, v60
	v_lshlrev_b32_e32 v182, 16, v61
	v_and_b32_e32 v183, 0xffff0000, v61
	v_lshlrev_b32_e32 v184, 16, v72
	v_and_b32_e32 v185, 0xffff0000, v72
	v_lshlrev_b32_e32 v186, 16, v73
	v_and_b32_e32 v187, 0xffff0000, v73
	v_pk_add_f32 v[184:185], v[184:185], v[180:181] neg_lo:[0,1] neg_hi:[0,1]
	v_pk_add_f32 v[186:187], v[186:187], v[182:183] neg_lo:[0,1] neg_hi:[0,1]
	v_pk_fma_f32 v[184:185], v[184:185], v[6:7], v[180:181]
	v_pk_fma_f32 v[186:187], v[186:187], v[8:9], v[182:183]
	v_lshlrev_b32_e32 v180, 16, v64
	v_and_b32_e32 v181, 0xffff0000, v64
	v_lshlrev_b32_e32 v182, 16, v65
	v_and_b32_e32 v183, 0xffff0000, v65
	v_lshlrev_b32_e32 v130, 16, v76
	v_and_b32_e32 v131, 0xffff0000, v76
	v_lshlrev_b32_e32 v132, 16, v77
	v_and_b32_e32 v133, 0xffff0000, v77
	v_pk_add_f32 v[130:131], v[130:131], v[180:181] neg_lo:[0,1] neg_hi:[0,1]
	v_pk_add_f32 v[132:133], v[132:133], v[182:183] neg_lo:[0,1] neg_hi:[0,1]
	v_pk_fma_f32 v[130:131], v[130:131], v[14:15], v[180:181]
	v_pk_fma_f32 v[132:133], v[132:133], v[16:17], v[182:183]
	v_lshlrev_b32_e32 v180, 16, v68
	v_and_b32_e32 v181, 0xffff0000, v68
	v_lshlrev_b32_e32 v182, 16, v69
	v_and_b32_e32 v183, 0xffff0000, v69
	v_lshlrev_b32_e32 v168, 16, v80
	v_and_b32_e32 v169, 0xffff0000, v80
	v_lshlrev_b32_e32 v170, 16, v81
	v_and_b32_e32 v171, 0xffff0000, v81
	v_pk_add_f32 v[168:169], v[168:169], v[180:181] neg_lo:[0,1] neg_hi:[0,1]
	v_pk_add_f32 v[170:171], v[170:171], v[182:183] neg_lo:[0,1] neg_hi:[0,1]
	v_pk_fma_f32 v[168:169], v[168:169], v[22:23], v[180:181]
	v_pk_fma_f32 v[170:171], v[170:171], v[24:25], v[182:183]
	ds_write_b128 v207, v[168:171] offset:1280
	v_lshlrev_b32_e32 v188, 16, v84
	v_and_b32_e32 v189, 0xffff0000, v84
	v_lshlrev_b32_e32 v190, 16, v85
	v_and_b32_e32 v191, 0xffff0000, v85
	v_pk_mul_f32 v[144:145], v[130:131], v[30:31]
	v_pk_mul_f32 v[146:147], v[132:133], v[32:33]
	v_pk_fma_f32 v[134:135], v[144:145], v[144:145], v[134:135]
	v_pk_fma_f32 v[134:135], v[146:147], v[146:147], v[134:135]
	v_pk_fma_f32 v[180:181], v[188:189], v[38:39], v[46:47]
	v_pk_fma_f32 v[182:183], v[190:191], v[40:41], v[48:49]
	v_pk_mul_f32 v[180:181], v[130:131], v[180:181]
	v_pk_mul_f32 v[182:183], v[132:133], v[182:183]
	ds_write_b128 v207, v[180:183] offset:768
	v_pk_mul_f32 v[130:131], v[180:181], v[184:185]
	v_pk_mul_f32 v[132:133], v[182:183], v[186:187]
	v_pk_add_f32 v[192:193], v[192:193], v[130:131]
	v_pk_add_f32 v[192:193], v[192:193], v[132:133]
; __global__ void __launch_bounds__(NTHR) hymba_fwd(Params P) {
;     ...
;               constexpr int CT_PER = 5632, CT_ALL = 3 * CT_PER + 2048;
;               float cvv[32]; int ctile = unit * 2 + (wv - 4), cph = 0;
	v_pk_fma_f32 v[194:195], v[130:131], v[54:55], v[194:195]
	v_pk_fma_f32 v[194:195], v[132:133], v[56:57], v[194:195]
	v_pk_mul_f32 v[160:161], v[144:145], v[188:189]
	v_pk_mul_f32 v[162:163], v[146:147], v[190:191]
	v_pk_fma_f32 v[148:149], v[160:161], v[184:185], v[148:149]
	v_pk_fma_f32 v[148:149], v[162:163], v[186:187], v[148:149]
	v_pk_mul_f32 v[176:177], v[90:91], v[184:185]
	v_pk_mul_f32 v[178:179], v[92:93], v[186:187]
	ds_write_b128 v207, v[90:93] offset:512
	v_add_f32_e32 v134, v134, v135
	v_add_f32_e32 v148, v148, v149
	v_add_f32_e32 v202, v192, v193
	v_add_f32_e32 v194, v194, v195
	v_add_f32_dpp v134, v134, v134 quad_perm:[1,0,3,2] row_mask:0xf bank_mask:0xf bound_ctrl:1
	v_add_f32_dpp v148, v148, v148 quad_perm:[1,0,3,2] row_mask:0xf bank_mask:0xf bound_ctrl:1
	v_add_f32_dpp v202, v202, v202 quad_perm:[1,0,3,2] row_mask:0xf bank_mask:0xf bound_ctrl:1
	v_add_f32_dpp v194, v194, v194 quad_perm:[1,0,3,2] row_mask:0xf bank_mask:0xf bound_ctrl:1
	v_add_f32_dpp v134, v134, v134 quad_perm:[2,3,0,1] row_mask:0xf bank_mask:0xf bound_ctrl:1
	v_add_f32_dpp v148, v148, v148 quad_perm:[2,3,0,1] row_mask:0xf bank_mask:0xf bound_ctrl:1
	v_add_f32_dpp v202, v202, v202 quad_perm:[2,3,0,1] row_mask:0xf bank_mask:0xf bound_ctrl:1
	v_add_f32_dpp v194, v194, v194 quad_perm:[2,3,0,1] row_mask:0xf bank_mask:0xf bound_ctrl:1
	v_add_f32_dpp v134, v134, v134 row_half_mirror row_mask:0xf bank_mask:0xf bound_ctrl:1
	v_add_f32_dpp v148, v148, v148 row_half_mirror row_mask:0xf bank_mask:0xf bound_ctrl:1
	v_add_f32_dpp v202, v202, v202 row_half_mirror row_mask:0xf bank_mask:0xf bound_ctrl:1
	v_add_f32_dpp v194, v194, v194 row_half_mirror row_mask:0xf bank_mask:0xf bound_ctrl:1
	v_max_f32_e32 v134, 0x179abe15, v134
	v_rsq_f32_e32 v198, v134
	s_nop 1
	v_mul_f32_e32 v200, v198, v148
	v_pk_mul_f32 v[180:181], v[140:141], v[198:199] op_sel_hi:[1,0] neg_lo:[0,1] neg_hi:[0,1]
	v_pk_mul_f32 v[182:183], v[142:143], v[198:199] op_sel_hi:[1,0] neg_lo:[0,1] neg_hi:[0,1]
	v_pk_mul_f32 v[184:185], v[144:145], v[198:199] op_sel_hi:[1,0] neg_lo:[0,1] neg_hi:[0,1]
	v_pk_mul_f32 v[186:187], v[146:147], v[198:199] op_sel_hi:[1,0] neg_lo:[0,1] neg_hi:[0,1]
	ds_write_b128 v206, v[180:183] offset:0
	ds_write_b128 v207, v[184:187] offset:0
	v_pk_fma_f32 v[172:173], v[180:181], v[200:201], v[172:173] op_sel_hi:[1,0,1]
	v_pk_fma_f32 v[174:175], v[182:183], v[200:201], v[174:175] op_sel_hi:[1,0,1]
	v_pk_fma_f32 v[176:177], v[184:185], v[200:201], v[176:177] op_sel_hi:[1,0,1]
	v_pk_fma_f32 v[178:179], v[186:187], v[200:201], v[178:179] op_sel_hi:[1,0,1]
	ds_write_b128 v206, v[172:175] offset:256
	ds_write_b128 v207, v[176:179] offset:256
	v_pk_mul_f32 v[156:157], v[156:157], v[198:199] op_sel_hi:[1,0]
	v_pk_mul_f32 v[158:159], v[158:159], v[198:199] op_sel_hi:[1,0]
	v_pk_mul_f32 v[160:161], v[160:161], v[198:199] op_sel_hi:[1,0]
	v_pk_mul_f32 v[162:163], v[162:163], v[198:199] op_sel_hi:[1,0]
	ds_write_b128 v206, v[156:159] offset:1024
	ds_write_b128 v207, v[160:163] offset:1024
	v_pk_mul_f32 v[164:165], v[164:165], v[202:203] op_sel_hi:[1,0]
	v_pk_mul_f32 v[166:167], v[166:167], v[202:203] op_sel_hi:[1,0]
	v_pk_mul_f32 v[168:169], v[168:169], v[202:203] op_sel_hi:[1,0]
	v_pk_mul_f32 v[170:171], v[170:171], v[202:203] op_sel_hi:[1,0]
	ds_write_b128 v206, v[164:167] offset:1536
	ds_write_b128 v207, v[168:171] offset:1536
	s_mov_b64 exec, s[52:53]
	global_store_dword v205, v194, s[64:65]
	s_mov_b64 exec, -1
	s_add_u32 s64, s64, 0x800
	s_addc_u32 s65, s65, 0
	s_cmp_gt_u32 s14, 36
	s_cbranch_scc1 .Lp4a_cl0
	s_lshl_b32 s4, s14, 10
	s_add_i32 s4, s4, s33
	s_and_b32 s94, s4, 1
	s_lshr_b32 s4, s4, 1
	s_lshl_b32 s94, s94, 4
	s_cmpk_lt_u32 s4, 0x2c00
	s_cbranch_scc0 .Lp4a_cl0_dn
	s_cmpk_ge_u32 s4, 0x1600
	s_cselect_b32 s5, 0x1600, 0
	s_cselect_b32 s0, s10, s8
	s_cselect_b32 s1, s11, s9
	s_cselect_b32 s40, 128, 0
	s_sub_i32 s4, s4, s5
	s_mul_i32 s5, s4, 0xba2f
	s_lshr_b32 s5, s5, 22
	s_mul_i32 s6, s5, 88
	s_sub_i32 s4, s4, s6
	s_lshl_b32 s5, s5, 5
	s_add_i32 s5, s5, s94
	s_mul_i32 s6, s5, 0x5800
	s_lshl_b32 s7, s4, 8
	s_add_i32 s6, s6, s7
	s_add_u32 s0, s0, s6
	s_addc_u32 s1, s1, 0
	s_lshr_b32 s6, s4, 1
	s_lshl_b32 s6, s6, 8
	s_and_b32 s7, s4, 1
	s_lshl_b32 s7, s7, 6
	s_add_i32 s6, s6, s7
	s_add_i32 s6, s6, s40
	s_lshl_b32 s6, s6, 12
	s_lshl_b32 s7, s5, 1
	s_add_i32 s4, s6, s7
	s_add_u32 s6, s90, 0x1a00000
	s_addc_u32 s7, s91, 0
	s_add_u32 s6, s6, s4
	s_addc_u32 s7, s7, 0
	s_movk_i32 s40, 0x5800
	v_lshlrev_b32_e32 v228, 12, v229
	s_branch .Lp4a_cl0_ld
.Lp4a_cl0_dn:
	s_cmpk_ge_u32 s4, 0x4200
	s_movk_i32 s5, 0x2c00
	s_cselect_b32 s5, 0x4200, s5
	s_cselect_b32 s0, s26, s22
	s_cselect_b32 s1, s27, s23
	s_movk_i32 s40, 0x2c00
	s_cselect_b32 s40, 0x1000, s40
	s_mov_b32 s7, 0x4600000
	s_cselect_b32 s7, 0x1200000, s7
	s_sub_i32 s4, s4, s5
	s_lshr_b32 s5, s4, 5
	s_and_b32 s4, s4, 31
	s_lshl_b32 s5, s5, 5
	s_add_i32 s5, s5, s94
	s_lshl_b32 s6, s5, 13
	s_lshl_b32 s94, s4, 8
	s_add_i32 s6, s6, s94
	s_add_u32 s0, s0, s6
	s_addc_u32 s1, s1, 0
	s_lshl_b32 s4, s4, 6
	s_mul_i32 s4, s4, s40
	s_lshl_b32 s5, s5, 1
	s_add_i32 s4, s4, s5
	s_add_u32 s6, s90, s7
	s_addc_u32 s7, s91, 0
	s_add_u32 s6, s6, s4
	s_addc_u32 s7, s7, 0
	v_mul_u32_u24_e32 v228, s40, v229
	s_movk_i32 s40, 0x2000
.Lp4a_cl0_ld:
	v_mov_b32_e32 v227, v226
	global_load_dword v210, v227, s[0:1]
	v_add_u32_e32 v227, s40, v227
	global_load_dword v211, v227, s[0:1]
	v_add_u32_e32 v227, s40, v227
	global_load_dword v212, v227, s[0:1]
	v_add_u32_e32 v227, s40, v227
	global_load_dword v213, v227, s[0:1]
	v_add_u32_e32 v227, s40, v227
	global_load_dword v214, v227, s[0:1]
	v_add_u32_e32 v227, s40, v227
	global_load_dword v215, v227, s[0:1]
	v_add_u32_e32 v227, s40, v227
	global_load_dword v216, v227, s[0:1]
	v_add_u32_e32 v227, s40, v227
	global_load_dword v217, v227, s[0:1]
	v_add_u32_e32 v227, s40, v227
	global_load_dword v218, v227, s[0:1]
	v_add_u32_e32 v227, s40, v227
	global_load_dword v219, v227, s[0:1]
	v_add_u32_e32 v227, s40, v227
	global_load_dword v220, v227, s[0:1]
	v_add_u32_e32 v227, s40, v227
	global_load_dword v221, v227, s[0:1]
	v_add_u32_e32 v227, s40, v227
	global_load_dword v222, v227, s[0:1]
	v_add_u32_e32 v227, s40, v227
	global_load_dword v223, v227, s[0:1]
	v_add_u32_e32 v227, s40, v227
	global_load_dword v224, v227, s[0:1]
	v_add_u32_e32 v227, s40, v227
	global_load_dword v225, v227, s[0:1]
.Lp4a_cl0:
	global_load_dwordx4 v[58:61], v0, s[56:57]
	global_load_dwordx4 v[62:65], v0, s[56:57] offset:2048
	global_load_dwordx4 v[66:69], v0, s[58:59]
	global_load_dwordx4 v[70:73], v155, s[56:57]
	global_load_dwordx4 v[74:77], v155, s[56:57] offset:2048
	global_load_dwordx4 v[78:81], v155, s[58:59]
	global_load_dwordx4 v[82:85], v197, s[60:61]
	global_load_dwordx4 v[86:89], v204, s[62:63]
	global_load_dwordx4 v[90:93], v204, s[62:63] offset:16
	s_add_u32 s56, s56, 0x48000
	s_addc_u32 s57, s57, 0
	s_add_u32 s58, s58, 0x48000
	s_addc_u32 s59, s59, 0
	s_add_u32 s60, s60, 0x10000
	s_addc_u32 s61, s61, 0
	s_add_u32 s62, s62, 0x20000
	s_addc_u32 s63, s63, 0
	s_waitcnt lgkmcnt(0)
	s_barrier
	s_movk_i32 s14, 1
	s_waitcnt vmcnt(26)
	v_mov_b32_e32 v134, 0
	v_mov_b32_e32 v135, 0
	v_mov_b32_e32 v148, 0
	v_mov_b32_e32 v149, 0
	v_mov_b32_e32 v192, 0
	v_mov_b32_e32 v193, 0
	v_mov_b32_e32 v194, 0
	v_mov_b32_e32 v195, 0
	v_lshlrev_b32_e32 v180, 16, v94
	v_and_b32_e32 v181, 0xffff0000, v94
	v_lshlrev_b32_e32 v182, 16, v95
	v_and_b32_e32 v183, 0xffff0000, v95
	v_lshlrev_b32_e32 v184, 16, v106
	v_and_b32_e32 v185, 0xffff0000, v106
	v_lshlrev_b32_e32 v186, 16, v107
	v_and_b32_e32 v187, 0xffff0000, v107
	v_pk_add_f32 v[184:185], v[184:185], v[180:181] neg_lo:[0,1] neg_hi:[0,1]
	v_pk_add_f32 v[186:187], v[186:187], v[182:183] neg_lo:[0,1] neg_hi:[0,1]
	v_pk_fma_f32 v[184:185], v[184:185], v[2:3], v[180:181]
	v_pk_fma_f32 v[186:187], v[186:187], v[4:5], v[182:183]
	v_lshlrev_b32_e32 v180, 16, v98
	v_and_b32_e32 v181, 0xffff0000, v98
	v_lshlrev_b32_e32 v182, 16, v99
	v_and_b32_e32 v183, 0xffff0000, v99
	v_lshlrev_b32_e32 v130, 16, v110
	v_and_b32_e32 v131, 0xffff0000, v110
	v_lshlrev_b32_e32 v132, 16, v111
	v_and_b32_e32 v133, 0xffff0000, v111
	v_pk_add_f32 v[130:131], v[130:131], v[180:181] neg_lo:[0,1] neg_hi:[0,1]
	v_pk_add_f32 v[132:133], v[132:133], v[182:183] neg_lo:[0,1] neg_hi:[0,1]
	v_pk_fma_f32 v[130:131], v[130:131], v[10:11], v[180:181]
	v_pk_fma_f32 v[132:133], v[132:133], v[12:13], v[182:183]
	v_lshlrev_b32_e32 v180, 16, v102
	v_and_b32_e32 v181, 0xffff0000, v102
	v_lshlrev_b32_e32 v182, 16, v103
	v_and_b32_e32 v183, 0xffff0000, v103
	v_lshlrev_b32_e32 v164, 16, v114
	v_and_b32_e32 v165, 0xffff0000, v114
	v_lshlrev_b32_e32 v166, 16, v115
	v_and_b32_e32 v167, 0xffff0000, v115
	v_pk_add_f32 v[164:165], v[164:165], v[180:181] neg_lo:[0,1] neg_hi:[0,1]
	v_pk_add_f32 v[166:167], v[166:167], v[182:183] neg_lo:[0,1] neg_hi:[0,1]
	v_pk_fma_f32 v[164:165], v[164:165], v[18:19], v[180:181]
	v_pk_fma_f32 v[166:167], v[166:167], v[20:21], v[182:183]
	ds_write_b128 v208, v[164:167] offset:1280
	v_lshlrev_b32_e32 v188, 16, v118
	v_and_b32_e32 v189, 0xffff0000, v118
	v_lshlrev_b32_e32 v190, 16, v119
	v_and_b32_e32 v191, 0xffff0000, v119
	v_pk_mul_f32 v[140:141], v[130:131], v[26:27]
	v_pk_mul_f32 v[142:143], v[132:133], v[28:29]
	v_pk_fma_f32 v[134:135], v[140:141], v[140:141], v[134:135]
	v_pk_fma_f32 v[134:135], v[142:143], v[142:143], v[134:135]
	v_pk_fma_f32 v[180:181], v[188:189], v[34:35], v[42:43]
	v_pk_fma_f32 v[182:183], v[190:191], v[36:37], v[44:45]
	v_pk_mul_f32 v[180:181], v[130:131], v[180:181]
	v_pk_mul_f32 v[182:183], v[132:133], v[182:183]
	ds_write_b128 v208, v[180:183] offset:768
	v_pk_mul_f32 v[130:131], v[180:181], v[184:185]
	v_pk_mul_f32 v[132:133], v[182:183], v[186:187]
	v_pk_add_f32 v[192:193], v[192:193], v[130:131]
	v_pk_add_f32 v[192:193], v[192:193], v[132:133]
	v_pk_fma_f32 v[194:195], v[130:131], v[50:51], v[194:195]
	v_pk_fma_f32 v[194:195], v[132:133], v[52:53], v[194:195]
	v_pk_mul_f32 v[156:157], v[140:141], v[188:189]
	v_pk_mul_f32 v[158:159], v[142:143], v[190:191]
	v_pk_fma_f32 v[148:149], v[156:157], v[184:185], v[148:149]
	v_pk_fma_f32 v[148:149], v[158:159], v[186:187], v[148:149]
	v_pk_mul_f32 v[172:173], v[122:123], v[184:185]
	v_pk_mul_f32 v[174:175], v[124:125], v[186:187]
	ds_write_b128 v208, v[122:125] offset:512
	v_lshlrev_b32_e32 v180, 16, v96
	v_and_b32_e32 v181, 0xffff0000, v96
	v_lshlrev_b32_e32 v182, 16, v97
	v_and_b32_e32 v183, 0xffff0000, v97
	v_lshlrev_b32_e32 v184, 16, v108
	v_and_b32_e32 v185, 0xffff0000, v108
	v_lshlrev_b32_e32 v186, 16, v109
	v_and_b32_e32 v187, 0xffff0000, v109
	v_pk_add_f32 v[184:185], v[184:185], v[180:181] neg_lo:[0,1] neg_hi:[0,1]
	v_pk_add_f32 v[186:187], v[186:187], v[182:183] neg_lo:[0,1] neg_hi:[0,1]
	v_pk_fma_f32 v[184:185], v[184:185], v[6:7], v[180:181]
	v_pk_fma_f32 v[186:187], v[186:187], v[8:9], v[182:183]
	v_lshlrev_b32_e32 v180, 16, v100
	v_and_b32_e32 v181, 0xffff0000, v100
	v_lshlrev_b32_e32 v182, 16, v101
	v_and_b32_e32 v183, 0xffff0000, v101
	v_lshlrev_b32_e32 v130, 16, v112
	v_and_b32_e32 v131, 0xffff0000, v112
	v_lshlrev_b32_e32 v132, 16, v113
	v_and_b32_e32 v133, 0xffff0000, v113
	v_pk_add_f32 v[130:131], v[130:131], v[180:181] neg_lo:[0,1] neg_hi:[0,1]
	v_pk_add_f32 v[132:133], v[132:133], v[182:183] neg_lo:[0,1] neg_hi:[0,1]
	v_pk_fma_f32 v[130:131], v[130:131], v[14:15], v[180:181]
	v_pk_fma_f32 v[132:133], v[132:133], v[16:17], v[182:183]
	v_lshlrev_b32_e32 v180, 16, v104
	v_and_b32_e32 v181, 0xffff0000, v104
	v_lshlrev_b32_e32 v182, 16, v105
	v_and_b32_e32 v183, 0xffff0000, v105
	v_lshlrev_b32_e32 v168, 16, v116
	v_and_b32_e32 v169, 0xffff0000, v116
	v_lshlrev_b32_e32 v170, 16, v117
	v_and_b32_e32 v171, 0xffff0000, v117
	v_pk_add_f32 v[168:169], v[168:169], v[180:181] neg_lo:[0,1] neg_hi:[0,1]
	v_pk_add_f32 v[170:171], v[170:171], v[182:183] neg_lo:[0,1] neg_hi:[0,1]
	v_pk_fma_f32 v[168:169], v[168:169], v[22:23], v[180:181]
	v_pk_fma_f32 v[170:171], v[170:171], v[24:25], v[182:183]
	ds_write_b128 v209, v[168:171] offset:1280
	v_lshlrev_b32_e32 v188, 16, v120
	v_and_b32_e32 v189, 0xffff0000, v120
	v_lshlrev_b32_e32 v190, 16, v121
	v_and_b32_e32 v191, 0xffff0000, v121
	v_pk_mul_f32 v[144:145], v[130:131], v[30:31]
	v_pk_mul_f32 v[146:147], v[132:133], v[32:33]
	v_pk_fma_f32 v[134:135], v[144:145], v[144:145], v[134:135]
	v_pk_fma_f32 v[134:135], v[146:147], v[146:147], v[134:135]
	v_pk_fma_f32 v[180:181], v[188:189], v[38:39], v[46:47]
	v_pk_fma_f32 v[182:183], v[190:191], v[40:41], v[48:49]
	v_pk_mul_f32 v[180:181], v[130:131], v[180:181]
	v_pk_mul_f32 v[182:183], v[132:133], v[182:183]
	ds_write_b128 v209, v[180:183] offset:768
	v_pk_mul_f32 v[130:131], v[180:181], v[184:185]
	v_pk_mul_f32 v[132:133], v[182:183], v[186:187]
	v_pk_add_f32 v[192:193], v[192:193], v[130:131]
	v_pk_add_f32 v[192:193], v[192:193], v[132:133]
	v_pk_fma_f32 v[194:195], v[130:131], v[54:55], v[194:195]
	v_pk_fma_f32 v[194:195], v[132:133], v[56:57], v[194:195]
	v_pk_mul_f32 v[160:161], v[144:145], v[188:189]
	v_pk_mul_f32 v[162:163], v[146:147], v[190:191]
	v_pk_fma_f32 v[148:149], v[160:161], v[184:185], v[148:149]
	v_pk_fma_f32 v[148:149], v[162:163], v[186:187], v[148:149]
	v_pk_mul_f32 v[176:177], v[126:127], v[184:185]
	v_pk_mul_f32 v[178:179], v[128:129], v[186:187]
	ds_write_b128 v209, v[126:129] offset:512
	v_add_f32_e32 v134, v134, v135
	v_add_f32_e32 v148, v148, v149
	v_add_f32_e32 v202, v192, v193
	v_add_f32_e32 v194, v194, v195
	v_add_f32_dpp v134, v134, v134 quad_perm:[1,0,3,2] row_mask:0xf bank_mask:0xf bound_ctrl:1
	v_add_f32_dpp v148, v148, v148 quad_perm:[1,0,3,2] row_mask:0xf bank_mask:0xf bound_ctrl:1
	v_add_f32_dpp v202, v202, v202 quad_perm:[1,0,3,2] row_mask:0xf bank_mask:0xf bound_ctrl:1
	v_add_f32_dpp v194, v194, v194 quad_perm:[1,0,3,2] row_mask:0xf bank_mask:0xf bound_ctrl:1
	v_add_f32_dpp v134, v134, v134 quad_perm:[2,3,0,1] row_mask:0xf bank_mask:0xf bound_ctrl:1
	v_add_f32_dpp v148, v148, v148 quad_perm:[2,3,0,1] row_mask:0xf bank_mask:0xf bound_ctrl:1
	v_add_f32_dpp v202, v202, v202 quad_perm:[2,3,0,1] row_mask:0xf bank_mask:0xf bound_ctrl:1
	v_add_f32_dpp v194, v194, v194 quad_perm:[2,3,0,1] row_mask:0xf bank_mask:0xf bound_ctrl:1
	v_add_f32_dpp v134, v134, v134 row_half_mirror row_mask:0xf bank_mask:0xf bound_ctrl:1
	v_add_f32_dpp v148, v148, v148 row_half_mirror row_mask:0xf bank_mask:0xf bound_ctrl:1
	v_add_f32_dpp v202, v202, v202 row_half_mirror row_mask:0xf bank_mask:0xf bound_ctrl:1
	v_add_f32_dpp v194, v194, v194 row_half_mirror row_mask:0xf bank_mask:0xf bound_ctrl:1
	v_max_f32_e32 v134, 0x179abe15, v134
	v_rsq_f32_e32 v198, v134
	s_nop 1
	v_mul_f32_e32 v200, v198, v148
	v_pk_mul_f32 v[180:181], v[140:141], v[198:199] op_sel_hi:[1,0] neg_lo:[0,1] neg_hi:[0,1]
	v_pk_mul_f32 v[182:183], v[142:143], v[198:199] op_sel_hi:[1,0] neg_lo:[0,1] neg_hi:[0,1]
	v_pk_mul_f32 v[184:185], v[144:145], v[198:199] op_sel_hi:[1,0] neg_lo:[0,1] neg_hi:[0,1]
	v_pk_mul_f32 v[186:187], v[146:147], v[198:199] op_sel_hi:[1,0] neg_lo:[0,1] neg_hi:[0,1]
	ds_write_b128 v208, v[180:183] offset:0
	ds_write_b128 v209, v[184:187] offset:0
	v_pk_fma_f32 v[172:173], v[180:181], v[200:201], v[172:173] op_sel_hi:[1,0,1]
	v_pk_fma_f32 v[174:175], v[182:183], v[200:201], v[174:175] op_sel_hi:[1,0,1]
	v_pk_fma_f32 v[176:177], v[184:185], v[200:201], v[176:177] op_sel_hi:[1,0,1]
	v_pk_fma_f32 v[178:179], v[186:187], v[200:201], v[178:179] op_sel_hi:[1,0,1]
	ds_write_b128 v208, v[172:175] offset:256
	ds_write_b128 v209, v[176:179] offset:256
	v_pk_mul_f32 v[156:157], v[156:157], v[198:199] op_sel_hi:[1,0]
	v_pk_mul_f32 v[158:159], v[158:159], v[198:199] op_sel_hi:[1,0]
	v_pk_mul_f32 v[160:161], v[160:161], v[198:199] op_sel_hi:[1,0]
	v_pk_mul_f32 v[162:163], v[162:163], v[198:199] op_sel_hi:[1,0]
	ds_write_b128 v208, v[156:159] offset:1024
	ds_write_b128 v209, v[160:163] offset:1024
	v_pk_mul_f32 v[164:165], v[164:165], v[202:203] op_sel_hi:[1,0]
	v_pk_mul_f32 v[166:167], v[166:167], v[202:203] op_sel_hi:[1,0]
	v_pk_mul_f32 v[168:169], v[168:169], v[202:203] op_sel_hi:[1,0]
	v_pk_mul_f32 v[170:171], v[170:171], v[202:203] op_sel_hi:[1,0]
	ds_write_b128 v208, v[164:167] offset:1536
	ds_write_b128 v209, v[168:171] offset:1536
	s_mov_b64 exec, s[52:53]
	global_store_dword v205, v194, s[64:65]
	s_mov_b64 exec, -1
	s_add_u32 s64, s64, 0x800
	s_addc_u32 s65, s65, 0
	s_cmp_eq_u32 s14, 0
	s_cbranch_scc1 .Lp4a_csp
	s_cmp_gt_u32 s14, 37
	s_cbranch_scc1 .Lp4a_csp
	s_waitcnt vmcnt(10)
	v_cvt_pk_bf16_f32 v180, v210, v211
	v_cvt_pk_bf16_f32 v181, v212, v213
	v_cvt_pk_bf16_f32 v182, v214, v215
	v_cvt_pk_bf16_f32 v183, v216, v217
	v_cvt_pk_bf16_f32 v184, v218, v219
	v_cvt_pk_bf16_f32 v185, v220, v221
	v_cvt_pk_bf16_f32 v186, v222, v223
	v_cvt_pk_bf16_f32 v187, v224, v225
	global_store_dwordx4 v228, v[180:183], s[6:7]
	global_store_dwordx4 v228, v[184:187], s[6:7] offset:16
.Lp4a_csp:
	s_cmp_gt_u32 s14, 36
	s_cbranch_scc1 .Lp4a_clp
	s_lshl_b32 s4, s14, 10
	s_add_i32 s4, s4, s33
	s_and_b32 s94, s4, 1
	s_lshr_b32 s4, s4, 1
	s_lshl_b32 s94, s94, 4
	s_cmpk_lt_u32 s4, 0x2c00
	s_cbranch_scc0 .Lp4a_clp_dn
	s_cmpk_ge_u32 s4, 0x1600
	s_cselect_b32 s5, 0x1600, 0
	s_cselect_b32 s0, s10, s8
	s_cselect_b32 s1, s11, s9
	s_cselect_b32 s40, 128, 0
	s_sub_i32 s4, s4, s5
	s_mul_i32 s5, s4, 0xba2f
	s_lshr_b32 s5, s5, 22
	s_mul_i32 s6, s5, 88
	s_sub_i32 s4, s4, s6
	s_lshl_b32 s5, s5, 5
	s_add_i32 s5, s5, s94
	s_mul_i32 s6, s5, 0x5800
	s_lshl_b32 s7, s4, 8
	s_add_i32 s6, s6, s7
	s_add_u32 s0, s0, s6
	s_addc_u32 s1, s1, 0
	s_lshr_b32 s6, s4, 1
	s_lshl_b32 s6, s6, 8
	s_and_b32 s7, s4, 1
	s_lshl_b32 s7, s7, 6
	s_add_i32 s6, s6, s7
	s_add_i32 s6, s6, s40
	s_lshl_b32 s6, s6, 12
	s_lshl_b32 s7, s5, 1
	s_add_i32 s4, s6, s7
	s_add_u32 s6, s90, 0x1a00000
	s_addc_u32 s7, s91, 0
	s_add_u32 s6, s6, s4
	s_addc_u32 s7, s7, 0
	s_movk_i32 s40, 0x5800
	v_lshlrev_b32_e32 v228, 12, v229
	s_branch .Lp4a_clp_ld

; #define WG_BAR() do { asm volatile("s_waitcnt lgkmcnt(0)" ::: "memory"); __builtin_amdgcn_s_barrier(); asm volatile("" ::: "memory"); } while (0)
; #define SCAN_ITER(D_, SET) do { const int blk = blk0 + (D_); if (blk + 1 < TT / TB) { SCAN_PRODUCE(blk + 1, SET); if (blk + 1 + PD < TT / TB) SCAN_LOAD(blk + 1 + PD, SET); } WG_BAR(); } while (0)
; __global__ void __launch_bounds__(NTHR) hymba_fwd(Params P) {
;     ...
;               SCAN_LOAD(0, 0); SCAN_LOAD(1, 1);
;               SCAN_PRODUCE(0, 0); SCAN_LOAD(2, 0);
;               WG_BAR();
;               static_assert((TT / TB) % PD == 0 && PD == 2, "block loop is unrolled by PD = 2");
;               for (int blk0 = 0; blk0 < TT / TB; blk0 += PD) {
;     ...
;                 SCAN_ITER(0, 1); SCAN_ITER(1, 0);
.Lp4a_clp:
	global_load_dwordx4 v[94:97], v0, s[56:57]
	global_load_dwordx4 v[98:101], v0, s[56:57] offset:2048
	global_load_dwordx4 v[102:105], v0, s[58:59]
	global_load_dwordx4 v[106:109], v155, s[56:57]
	global_load_dwordx4 v[110:113], v155, s[56:57] offset:2048
	global_load_dwordx4 v[114:117], v155, s[58:59]
	global_load_dwordx4 v[118:121], v197, s[60:61]
	global_load_dwordx4 v[122:125], v204, s[62:63]
	global_load_dwordx4 v[126:129], v204, s[62:63] offset:16
	s_add_u32 s56, s56, 0x48000
	s_addc_u32 s57, s57, 0
	s_add_u32 s58, s58, 0x48000
	s_addc_u32 s59, s59, 0
	s_add_u32 s60, s60, 0x10000
	s_addc_u32 s61, s61, 0
	s_add_u32 s62, s62, 0x20000
	s_addc_u32 s63, s63, 0
	s_waitcnt lgkmcnt(0)
	s_barrier
	s_add_i32 s14, s14, 1
.Lp4a_loopa:
	s_waitcnt vmcnt(28)
	v_mov_b32_e32 v134, 0
	v_mov_b32_e32 v135, 0
	v_mov_b32_e32 v148, 0
	v_mov_b32_e32 v149, 0
	v_mov_b32_e32 v192, 0
	v_mov_b32_e32 v193, 0
	v_mov_b32_e32 v194, 0
	v_mov_b32_e32 v195, 0
	v_lshlrev_b32_e32 v180, 16, v58
	v_and_b32_e32 v181, 0xffff0000, v58
	v_lshlrev_b32_e32 v182, 16, v59
	v_and_b32_e32 v183, 0xffff0000, v59
	v_lshlrev_b32_e32 v184, 16, v70
	v_and_b32_e32 v185, 0xffff0000, v70
	v_lshlrev_b32_e32 v186, 16, v71
	v_and_b32_e32 v187, 0xffff0000, v71
	v_pk_add_f32 v[184:185], v[184:185], v[180:181] neg_lo:[0,1] neg_hi:[0,1]
	v_pk_add_f32 v[186:187], v[186:187], v[182:183] neg_lo:[0,1] neg_hi:[0,1]
	v_pk_fma_f32 v[184:185], v[184:185], v[2:3], v[180:181]
	v_pk_fma_f32 v[186:187], v[186:187], v[4:5], v[182:183]
	v_lshlrev_b32_e32 v180, 16, v62
	v_and_b32_e32 v181, 0xffff0000, v62
	v_lshlrev_b32_e32 v182, 16, v63
	v_and_b32_e32 v183, 0xffff0000, v63
	v_lshlrev_b32_e32 v130, 16, v74
	v_and_b32_e32 v131, 0xffff0000, v74
	v_lshlrev_b32_e32 v132, 16, v75
	v_and_b32_e32 v133, 0xffff0000, v75
	v_pk_add_f32 v[130:131], v[130:131], v[180:181] neg_lo:[0,1] neg_hi:[0,1]
	v_pk_add_f32 v[132:133], v[132:133], v[182:183] neg_lo:[0,1] neg_hi:[0,1]
	v_pk_fma_f32 v[130:131], v[130:131], v[10:11], v[180:181]
	v_pk_fma_f32 v[132:133], v[132:133], v[12:13], v[182:183]
	v_lshlrev_b32_e32 v180, 16, v66
	v_and_b32_e32 v181, 0xffff0000, v66
	v_lshlrev_b32_e32 v182, 16, v67
	v_and_b32_e32 v183, 0xffff0000, v67
	v_lshlrev_b32_e32 v164, 16, v78
	v_and_b32_e32 v165, 0xffff0000, v78
	v_lshlrev_b32_e32 v166, 16, v79
	v_and_b32_e32 v167, 0xffff0000, v79
	v_pk_add_f32 v[164:165], v[164:165], v[180:181] neg_lo:[0,1] neg_hi:[0,1]
	v_pk_add_f32 v[166:167], v[166:167], v[182:183] neg_lo:[0,1] neg_hi:[0,1]
	v_pk_fma_f32 v[164:165], v[164:165], v[18:19], v[180:181]
	v_pk_fma_f32 v[166:167], v[166:167], v[20:21], v[182:183]
	ds_write_b128 v206, v[164:167] offset:1280
	v_lshlrev_b32_e32 v188, 16, v82
	v_and_b32_e32 v189, 0xffff0000, v82
	v_lshlrev_b32_e32 v190, 16, v83
	v_and_b32_e32 v191, 0xffff0000, v83
	v_pk_mul_f32 v[140:141], v[130:131], v[26:27]
	v_pk_mul_f32 v[142:143], v[132:133], v[28:29]
	v_pk_fma_f32 v[134:135], v[140:141], v[140:141], v[134:135]
	v_pk_fma_f32 v[134:135], v[142:143], v[142:143], v[134:135]
	v_pk_fma_f32 v[180:181], v[188:189], v[34:35], v[42:43]
	v_pk_fma_f32 v[182:183], v[190:191], v[36:37], v[44:45]
	v_pk_mul_f32 v[180:181], v[130:131], v[180:181]
	v_pk_mul_f32 v[182:183], v[132:133], v[182:183]
	ds_write_b128 v206, v[180:183] offset:768
	v_pk_mul_f32 v[130:131], v[180:181], v[184:185]
	v_pk_mul_f32 v[132:133], v[182:183], v[186:187]
	v_pk_add_f32 v[192:193], v[192:193], v[130:131]
	v_pk_add_f32 v[192:193], v[192:193], v[132:133]
	v_pk_fma_f32 v[194:195], v[130:131], v[50:51], v[194:195]
	v_pk_fma_f32 v[194:195], v[132:133], v[52:53], v[194:195]
	v_pk_mul_f32 v[156:157], v[140:141], v[188:189]
	v_pk_mul_f32 v[158:159], v[142:143], v[190:191]
	v_pk_fma_f32 v[148:149], v[156:157], v[184:185], v[148:149]
	v_pk_fma_f32 v[148:149], v[158:159], v[186:187], v[148:149]
	v_pk_mul_f32 v[172:173], v[86:87], v[184:185]
	v_pk_mul_f32 v[174:175], v[88:89], v[186:187]
	ds_write_b128 v206, v[86:89] offset:512
	v_lshlrev_b32_e32 v180, 16, v60
	v_and_b32_e32 v181, 0xffff0000, v60
	v_lshlrev_b32_e32 v182, 16, v61
	v_and_b32_e32 v183, 0xffff0000, v61
	v_lshlrev_b32_e32 v184, 16, v72
	v_and_b32_e32 v185, 0xffff0000, v72
	v_lshlrev_b32_e32 v186, 16, v73
	v_and_b32_e32 v187, 0xffff0000, v73
	v_pk_add_f32 v[184:185], v[184:185], v[180:181] neg_lo:[0,1] neg_hi:[0,1]
	v_pk_add_f32 v[186:187], v[186:187], v[182:183] neg_lo:[0,1] neg_hi:[0,1]
	v_pk_fma_f32 v[184:185], v[184:185], v[6:7], v[180:181]
	v_pk_fma_f32 v[186:187], v[186:187], v[8:9], v[182:183]
	v_lshlrev_b32_e32 v180, 16, v64
	v_and_b32_e32 v181, 0xffff0000, v64
	v_lshlrev_b32_e32 v182, 16, v65
	v_and_b32_e32 v183, 0xffff0000, v65
	v_lshlrev_b32_e32 v130, 16, v76
	v_and_b32_e32 v131, 0xffff0000, v76
	v_lshlrev_b32_e32 v132, 16, v77
	v_and_b32_e32 v133, 0xffff0000, v77
	v_pk_add_f32 v[130:131], v[130:131], v[180:181] neg_lo:[0,1] neg_hi:[0,1]
	v_pk_add_f32 v[132:133], v[132:133], v[182:183] neg_lo:[0,1] neg_hi:[0,1]
	v_pk_fma_f32 v[130:131], v[130:131], v[14:15], v[180:181]
	v_pk_fma_f32 v[132:133], v[132:133], v[16:17], v[182:183]
	v_lshlrev_b32_e32 v180, 16, v68
	v_and_b32_e32 v181, 0xffff0000, v68
	v_lshlrev_b32_e32 v182, 16, v69
	v_and_b32_e32 v183, 0xffff0000, v69
	v_lshlrev_b32_e32 v168, 16, v80
	v_and_b32_e32 v169, 0xffff0000, v80
	v_lshlrev_b32_e32 v170, 16, v81
	v_and_b32_e32 v171, 0xffff0000, v81
	v_pk_add_f32 v[168:169], v[168:169], v[180:181] neg_lo:[0,1] neg_hi:[0,1]
	v_pk_add_f32 v[170:171], v[170:171], v[182:183] neg_lo:[0,1] neg_hi:[0,1]
	v_pk_fma_f32 v[168:169], v[168:169], v[22:23], v[180:181]
	v_pk_fma_f32 v[170:171], v[170:171], v[24:25], v[182:183]
	ds_write_b128 v207, v[168:171] offset:1280
	v_lshlrev_b32_e32 v188, 16, v84
	v_and_b32_e32 v189, 0xffff0000, v84
	v_lshlrev_b32_e32 v190, 16, v85
	v_and_b32_e32 v191, 0xffff0000, v85
	v_pk_mul_f32 v[144:145], v[130:131], v[30:31]
	v_pk_mul_f32 v[146:147], v[132:133], v[32:33]
	v_pk_fma_f32 v[134:135], v[144:145], v[144:145], v[134:135]
	v_pk_fma_f32 v[134:135], v[146:147], v[146:147], v[134:135]
	v_pk_fma_f32 v[180:181], v[188:189], v[38:39], v[46:47]
	v_pk_fma_f32 v[182:183], v[190:191], v[40:41], v[48:49]
	v_pk_mul_f32 v[180:181], v[130:131], v[180:181]
	v_pk_mul_f32 v[182:183], v[132:133], v[182:183]
	ds_write_b128 v207, v[180:183] offset:768
	v_pk_mul_f32 v[130:131], v[180:181], v[184:185]
	v_pk_mul_f32 v[132:133], v[182:183], v[186:187]
	v_pk_add_f32 v[192:193], v[192:193], v[130:131]
	v_pk_add_f32 v[192:193], v[192:193], v[132:133]
	v_pk_fma_f32 v[194:195], v[130:131], v[54:55], v[194:195]
	v_pk_fma_f32 v[194:195], v[132:133], v[56:57], v[194:195]
	v_pk_mul_f32 v[160:161], v[144:145], v[188:189]
	v_pk_mul_f32 v[162:163], v[146:147], v[190:191]
	v_pk_fma_f32 v[148:149], v[160:161], v[184:185], v[148:149]
	v_pk_fma_f32 v[148:149], v[162:163], v[186:187], v[148:149]
	v_pk_mul_f32 v[176:177], v[90:91], v[184:185]
	v_pk_mul_f32 v[178:179], v[92:93], v[186:187]
	ds_write_b128 v207, v[90:93] offset:512
	v_add_f32_e32 v134, v134, v135
	v_add_f32_e32 v148, v148, v149
	v_add_f32_e32 v202, v192, v193
	v_add_f32_e32 v194, v194, v195
	v_add_f32_dpp v134, v134, v134 quad_perm:[1,0,3,2] row_mask:0xf bank_mask:0xf bound_ctrl:1
	v_add_f32_dpp v148, v148, v148 quad_perm:[1,0,3,2] row_mask:0xf bank_mask:0xf bound_ctrl:1
	v_add_f32_dpp v202, v202, v202 quad_perm:[1,0,3,2] row_mask:0xf bank_mask:0xf bound_ctrl:1
	v_add_f32_dpp v194, v194, v194 quad_perm:[1,0,3,2] row_mask:0xf bank_mask:0xf bound_ctrl:1
	v_add_f32_dpp v134, v134, v134 quad_perm:[2,3,0,1] row_mask:0xf bank_mask:0xf bound_ctrl:1
	v_add_f32_dpp v148, v148, v148 quad_perm:[2,3,0,1] row_mask:0xf bank_mask:0xf bound_ctrl:1
	v_add_f32_dpp v202, v202, v202 quad_perm:[2,3,0,1] row_mask:0xf bank_mask:0xf bound_ctrl:1
	v_add_f32_dpp v194, v194, v194 quad_perm:[2,3,0,1] row_mask:0xf bank_mask:0xf bound_ctrl:1
	v_add_f32_dpp v134, v134, v134 row_half_mirror row_mask:0xf bank_mask:0xf bound_ctrl:1
	v_add_f32_dpp v148, v148, v148 row_half_mirror row_mask:0xf bank_mask:0xf bound_ctrl:1
	v_add_f32_dpp v202, v202, v202 row_half_mirror row_mask:0xf bank_mask:0xf bound_ctrl:1
	v_add_f32_dpp v194, v194, v194 row_half_mirror row_mask:0xf bank_mask:0xf bound_ctrl:1
	v_max_f32_e32 v134, 0x179abe15, v134
	v_rsq_f32_e32 v198, v134
	s_nop 1
	v_mul_f32_e32 v200, v198, v148
	v_pk_mul_f32 v[180:181], v[140:141], v[198:199] op_sel_hi:[1,0] neg_lo:[0,1] neg_hi:[0,1]
	v_pk_mul_f32 v[182:183], v[142:143], v[198:199] op_sel_hi:[1,0] neg_lo:[0,1] neg_hi:[0,1]
	v_pk_mul_f32 v[184:185], v[144:145], v[198:199] op_sel_hi:[1,0] neg_lo:[0,1] neg_hi:[0,1]
	v_pk_mul_f32 v[186:187], v[146:147], v[198:199] op_sel_hi:[1,0] neg_lo:[0,1] neg_hi:[0,1]
	ds_write_b128 v206, v[180:183] offset:0
	ds_write_b128 v207, v[184:187] offset:0
	v_pk_fma_f32 v[172:173], v[180:181], v[200:201], v[172:173] op_sel_hi:[1,0,1]
	v_pk_fma_f32 v[174:175], v[182:183], v[200:201], v[174:175] op_sel_hi:[1,0,1]
	v_pk_fma_f32 v[176:177], v[184:185], v[200:201], v[176:177] op_sel_hi:[1,0,1]
	v_pk_fma_f32 v[178:179], v[186:187], v[200:201], v[178:179] op_sel_hi:[1,0,1]
	ds_write_b128 v206, v[172:175] offset:256
	ds_write_b128 v207, v[176:179] offset:256
	v_pk_mul_f32 v[156:157], v[156:157], v[198:199] op_sel_hi:[1,0]
	v_pk_mul_f32 v[158:159], v[158:159], v[198:199] op_sel_hi:[1,0]
	v_pk_mul_f32 v[160:161], v[160:161], v[198:199] op_sel_hi:[1,0]
	v_pk_mul_f32 v[162:163], v[162:163], v[198:199] op_sel_hi:[1,0]
	ds_write_b128 v206, v[156:159] offset:1024
	ds_write_b128 v207, v[160:163] offset:1024
	v_pk_mul_f32 v[164:165], v[164:165], v[202:203] op_sel_hi:[1,0]
	v_pk_mul_f32 v[166:167], v[166:167], v[202:203] op_sel_hi:[1,0]
	v_pk_mul_f32 v[168:169], v[168:169], v[202:203] op_sel_hi:[1,0]
	v_pk_mul_f32 v[170:171], v[170:171], v[202:203] op_sel_hi:[1,0]
	ds_write_b128 v206, v[164:167] offset:1536
	ds_write_b128 v207, v[168:171] offset:1536
	s_mov_b64 exec, s[52:53]
	global_store_dword v205, v194, s[64:65]
	s_mov_b64 exec, -1
	s_add_u32 s64, s64, 0x800
	s_addc_u32 s65, s65, 0
	s_cmp_eq_u32 s14, 0
	s_cbranch_scc1 .Lp4a_csa
	s_cmp_gt_u32 s14, 37
	s_cbranch_scc1 .Lp4a_csa
	s_waitcnt vmcnt(10)
	v_cvt_pk_bf16_f32 v180, v210, v211
	v_cvt_pk_bf16_f32 v181, v212, v213
	v_cvt_pk_bf16_f32 v182, v214, v215
	v_cvt_pk_bf16_f32 v183, v216, v217
	v_cvt_pk_bf16_f32 v184, v218, v219
	v_cvt_pk_bf16_f32 v185, v220, v221
	v_cvt_pk_bf16_f32 v186, v222, v223
	v_cvt_pk_bf16_f32 v187, v224, v225
	global_store_dwordx4 v228, v[180:183], s[6:7]
	global_store_dwordx4 v228, v[184:187], s[6:7] offset:16

.Lp4a_cla:
	global_load_dwordx4 v[58:61], v0, s[56:57]
	global_load_dwordx4 v[62:65], v0, s[56:57] offset:2048
	global_load_dwordx4 v[66:69], v0, s[58:59]
	global_load_dwordx4 v[70:73], v155, s[56:57]
	global_load_dwordx4 v[74:77], v155, s[56:57] offset:2048
	global_load_dwordx4 v[78:81], v155, s[58:59]
	global_load_dwordx4 v[82:85], v197, s[60:61]
	global_load_dwordx4 v[86:89], v204, s[62:63]
	global_load_dwordx4 v[90:93], v204, s[62:63] offset:16
	s_add_u32 s56, s56, 0x48000
	s_addc_u32 s57, s57, 0
	s_add_u32 s58, s58, 0x48000
	s_addc_u32 s59, s59, 0
	s_add_u32 s60, s60, 0x10000
	s_addc_u32 s61, s61, 0
	s_add_u32 s62, s62, 0x20000
	s_addc_u32 s63, s63, 0
	s_waitcnt lgkmcnt(0)
	s_barrier
	s_add_i32 s14, s14, 1
	s_waitcnt vmcnt(28)
	v_mov_b32_e32 v134, 0
	v_mov_b32_e32 v135, 0
	v_mov_b32_e32 v148, 0
	v_mov_b32_e32 v149, 0
	v_mov_b32_e32 v192, 0
	v_mov_b32_e32 v193, 0
	v_mov_b32_e32 v194, 0
	v_mov_b32_e32 v195, 0
	v_lshlrev_b32_e32 v180, 16, v94
	v_and_b32_e32 v181, 0xffff0000, v94
	v_lshlrev_b32_e32 v182, 16, v95
	v_and_b32_e32 v183, 0xffff0000, v95
	v_lshlrev_b32_e32 v184, 16, v106
	v_and_b32_e32 v185, 0xffff0000, v106
	v_lshlrev_b32_e32 v186, 16, v107
	v_and_b32_e32 v187, 0xffff0000, v107
	v_pk_add_f32 v[184:185], v[184:185], v[180:181] neg_lo:[0,1] neg_hi:[0,1]
	v_pk_add_f32 v[186:187], v[186:187], v[182:183] neg_lo:[0,1] neg_hi:[0,1]
	v_pk_fma_f32 v[184:185], v[184:185], v[2:3], v[180:181]
	v_pk_fma_f32 v[186:187], v[186:187], v[4:5], v[182:183]
	v_lshlrev_b32_e32 v180, 16, v98
	v_and_b32_e32 v181, 0xffff0000, v98
	v_lshlrev_b32_e32 v182, 16, v99
	v_and_b32_e32 v183, 0xffff0000, v99
	v_lshlrev_b32_e32 v130, 16, v110
	v_and_b32_e32 v131, 0xffff0000, v110
	v_lshlrev_b32_e32 v132, 16, v111
	v_and_b32_e32 v133, 0xffff0000, v111
	v_pk_add_f32 v[130:131], v[130:131], v[180:181] neg_lo:[0,1] neg_hi:[0,1]
	v_pk_add_f32 v[132:133], v[132:133], v[182:183] neg_lo:[0,1] neg_hi:[0,1]
	v_pk_fma_f32 v[130:131], v[130:131], v[10:11], v[180:181]
	v_pk_fma_f32 v[132:133], v[132:133], v[12:13], v[182:183]
	v_lshlrev_b32_e32 v180, 16, v102
	v_and_b32_e32 v181, 0xffff0000, v102
	v_lshlrev_b32_e32 v182, 16, v103
	v_and_b32_e32 v183, 0xffff0000, v103
	v_lshlrev_b32_e32 v164, 16, v114
	v_and_b32_e32 v165, 0xffff0000, v114
	v_lshlrev_b32_e32 v166, 16, v115
	v_and_b32_e32 v167, 0xffff0000, v115
	v_pk_add_f32 v[164:165], v[164:165], v[180:181] neg_lo:[0,1] neg_hi:[0,1]
	v_pk_add_f32 v[166:167], v[166:167], v[182:183] neg_lo:[0,1] neg_hi:[0,1]
	v_pk_fma_f32 v[164:165], v[164:165], v[18:19], v[180:181]
	v_pk_fma_f32 v[166:167], v[166:167], v[20:21], v[182:183]
	ds_write_b128 v208, v[164:167] offset:1280
	v_lshlrev_b32_e32 v188, 16, v118
	v_and_b32_e32 v189, 0xffff0000, v118
	v_lshlrev_b32_e32 v190, 16, v119
	v_and_b32_e32 v191, 0xffff0000, v119
	v_pk_mul_f32 v[140:141], v[130:131], v[26:27]
	v_pk_mul_f32 v[142:143], v[132:133], v[28:29]
	v_pk_fma_f32 v[134:135], v[140:141], v[140:141], v[134:135]
	v_pk_fma_f32 v[134:135], v[142:143], v[142:143], v[134:135]
	v_pk_fma_f32 v[180:181], v[188:189], v[34:35], v[42:43]
	v_pk_fma_f32 v[182:183], v[190:191], v[36:37], v[44:45]
	v_pk_mul_f32 v[180:181], v[130:131], v[180:181]
	v_pk_mul_f32 v[182:183], v[132:133], v[182:183]
	ds_write_b128 v208, v[180:183] offset:768
	v_pk_mul_f32 v[130:131], v[180:181], v[184:185]
	v_pk_mul_f32 v[132:133], v[182:183], v[186:187]
	v_pk_add_f32 v[192:193], v[192:193], v[130:131]
	v_pk_add_f32 v[192:193], v[192:193], v[132:133]
	v_pk_fma_f32 v[194:195], v[130:131], v[50:51], v[194:195]
	v_pk_fma_f32 v[194:195], v[132:133], v[52:53], v[194:195]
	v_pk_mul_f32 v[156:157], v[140:141], v[188:189]
	v_pk_mul_f32 v[158:159], v[142:143], v[190:191]
	v_pk_fma_f32 v[148:149], v[156:157], v[184:185], v[148:149]
	v_pk_fma_f32 v[148:149], v[158:159], v[186:187], v[148:149]
	v_pk_mul_f32 v[172:173], v[122:123], v[184:185]
	v_pk_mul_f32 v[174:175], v[124:125], v[186:187]
	ds_write_b128 v208, v[122:125] offset:512
	v_lshlrev_b32_e32 v180, 16, v96
	v_and_b32_e32 v181, 0xffff0000, v96
	v_lshlrev_b32_e32 v182, 16, v97
	v_and_b32_e32 v183, 0xffff0000, v97
	v_lshlrev_b32_e32 v184, 16, v108
	v_and_b32_e32 v185, 0xffff0000, v108
	v_lshlrev_b32_e32 v186, 16, v109
	v_and_b32_e32 v187, 0xffff0000, v109
	v_pk_add_f32 v[184:185], v[184:185], v[180:181] neg_lo:[0,1] neg_hi:[0,1]
	v_pk_add_f32 v[186:187], v[186:187], v[182:183] neg_lo:[0,1] neg_hi:[0,1]
	v_pk_fma_f32 v[184:185], v[184:185], v[6:7], v[180:181]
	v_pk_fma_f32 v[186:187], v[186:187], v[8:9], v[182:183]
	v_lshlrev_b32_e32 v180, 16, v100
	v_and_b32_e32 v181, 0xffff0000, v100
	v_lshlrev_b32_e32 v182, 16, v101
	v_and_b32_e32 v183, 0xffff0000, v101
	v_lshlrev_b32_e32 v130, 16, v112
	v_and_b32_e32 v131, 0xffff0000, v112
	v_lshlrev_b32_e32 v132, 16, v113
	v_and_b32_e32 v133, 0xffff0000, v113
	v_pk_add_f32 v[130:131], v[130:131], v[180:181] neg_lo:[0,1] neg_hi:[0,1]
	v_pk_add_f32 v[132:133], v[132:133], v[182:183] neg_lo:[0,1] neg_hi:[0,1]
	v_pk_fma_f32 v[130:131], v[130:131], v[14:15], v[180:181]
	v_pk_fma_f32 v[132:133], v[132:133], v[16:17], v[182:183]
	v_lshlrev_b32_e32 v180, 16, v104
	v_and_b32_e32 v181, 0xffff0000, v104
	v_lshlrev_b32_e32 v182, 16, v105
	v_and_b32_e32 v183, 0xffff0000, v105
	v_lshlrev_b32_e32 v168, 16, v116
	v_and_b32_e32 v169, 0xffff0000, v116
	v_lshlrev_b32_e32 v170, 16, v117
	v_and_b32_e32 v171, 0xffff0000, v117
	v_pk_add_f32 v[168:169], v[168:169], v[180:181] neg_lo:[0,1] neg_hi:[0,1]
	v_pk_add_f32 v[170:171], v[170:171], v[182:183] neg_lo:[0,1] neg_hi:[0,1]
	v_pk_fma_f32 v[168:169], v[168:169], v[22:23], v[180:181]
	v_pk_fma_f32 v[170:171], v[170:171], v[24:25], v[182:183]
	ds_write_b128 v209, v[168:171] offset:1280
	v_lshlrev_b32_e32 v188, 16, v120
	v_and_b32_e32 v189, 0xffff0000, v120
	v_lshlrev_b32_e32 v190, 16, v121
	v_and_b32_e32 v191, 0xffff0000, v121
	v_pk_mul_f32 v[144:145], v[130:131], v[30:31]
	v_pk_mul_f32 v[146:147], v[132:133], v[32:33]
	v_pk_fma_f32 v[134:135], v[144:145], v[144:145], v[134:135]
	v_pk_fma_f32 v[134:135], v[146:147], v[146:147], v[134:135]
	v_pk_fma_f32 v[180:181], v[188:189], v[38:39], v[46:47]
	v_pk_fma_f32 v[182:183], v[190:191], v[40:41], v[48:49]
	v_pk_mul_f32 v[180:181], v[130:131], v[180:181]
	v_pk_mul_f32 v[182:183], v[132:133], v[182:183]
	ds_write_b128 v209, v[180:183] offset:768
	v_pk_mul_f32 v[130:131], v[180:181], v[184:185]
	v_pk_mul_f32 v[132:133], v[182:183], v[186:187]
	v_pk_add_f32 v[192:193], v[192:193], v[130:131]
	v_pk_add_f32 v[192:193], v[192:193], v[132:133]
	v_pk_fma_f32 v[194:195], v[130:131], v[54:55], v[194:195]
	v_pk_fma_f32 v[194:195], v[132:133], v[56:57], v[194:195]
	v_pk_mul_f32 v[160:161], v[144:145], v[188:189]
	v_pk_mul_f32 v[162:163], v[146:147], v[190:191]
	v_pk_fma_f32 v[148:149], v[160:161], v[184:185], v[148:149]
	v_pk_fma_f32 v[148:149], v[162:163], v[186:187], v[148:149]
	v_pk_mul_f32 v[176:177], v[126:127], v[184:185]
	v_pk_mul_f32 v[178:179], v[128:129], v[186:187]
	ds_write_b128 v209, v[126:129] offset:512
	v_add_f32_e32 v134, v134, v135
	v_add_f32_e32 v148, v148, v149
	v_add_f32_e32 v202, v192, v193
	v_add_f32_e32 v194, v194, v195
	v_add_f32_dpp v134, v134, v134 quad_perm:[1,0,3,2] row_mask:0xf bank_mask:0xf bound_ctrl:1
	v_add_f32_dpp v148, v148, v148 quad_perm:[1,0,3,2] row_mask:0xf bank_mask:0xf bound_ctrl:1
	v_add_f32_dpp v202, v202, v202 quad_perm:[1,0,3,2] row_mask:0xf bank_mask:0xf bound_ctrl:1
	v_add_f32_dpp v194, v194, v194 quad_perm:[1,0,3,2] row_mask:0xf bank_mask:0xf bound_ctrl:1
	v_add_f32_dpp v134, v134, v134 quad_perm:[2,3,0,1] row_mask:0xf bank_mask:0xf bound_ctrl:1
	v_add_f32_dpp v148, v148, v148 quad_perm:[2,3,0,1] row_mask:0xf bank_mask:0xf bound_ctrl:1
	v_add_f32_dpp v202, v202, v202 quad_perm:[2,3,0,1] row_mask:0xf bank_mask:0xf bound_ctrl:1
	v_add_f32_dpp v194, v194, v194 quad_perm:[2,3,0,1] row_mask:0xf bank_mask:0xf bound_ctrl:1
	v_add_f32_dpp v134, v134, v134 row_half_mirror row_mask:0xf bank_mask:0xf bound_ctrl:1
	v_add_f32_dpp v148, v148, v148 row_half_mirror row_mask:0xf bank_mask:0xf bound_ctrl:1
	v_add_f32_dpp v202, v202, v202 row_half_mirror row_mask:0xf bank_mask:0xf bound_ctrl:1
	v_add_f32_dpp v194, v194, v194 row_half_mirror row_mask:0xf bank_mask:0xf bound_ctrl:1
	v_max_f32_e32 v134, 0x179abe15, v134
	v_rsq_f32_e32 v198, v134
	s_nop 1
	v_mul_f32_e32 v200, v198, v148
	v_pk_mul_f32 v[180:181], v[140:141], v[198:199] op_sel_hi:[1,0] neg_lo:[0,1] neg_hi:[0,1]
	v_pk_mul_f32 v[182:183], v[142:143], v[198:199] op_sel_hi:[1,0] neg_lo:[0,1] neg_hi:[0,1]
	v_pk_mul_f32 v[184:185], v[144:145], v[198:199] op_sel_hi:[1,0] neg_lo:[0,1] neg_hi:[0,1]
	v_pk_mul_f32 v[186:187], v[146:147], v[198:199] op_sel_hi:[1,0] neg_lo:[0,1] neg_hi:[0,1]
	ds_write_b128 v208, v[180:183] offset:0
	ds_write_b128 v209, v[184:187] offset:0
	v_pk_fma_f32 v[172:173], v[180:181], v[200:201], v[172:173] op_sel_hi:[1,0,1]
	v_pk_fma_f32 v[174:175], v[182:183], v[200:201], v[174:175] op_sel_hi:[1,0,1]
	v_pk_fma_f32 v[176:177], v[184:185], v[200:201], v[176:177] op_sel_hi:[1,0,1]
	v_pk_fma_f32 v[178:179], v[186:187], v[200:201], v[178:179] op_sel_hi:[1,0,1]
	ds_write_b128 v208, v[172:175] offset:256
	ds_write_b128 v209, v[176:179] offset:256
	v_pk_mul_f32 v[156:157], v[156:157], v[198:199] op_sel_hi:[1,0]
	v_pk_mul_f32 v[158:159], v[158:159], v[198:199] op_sel_hi:[1,0]
	v_pk_mul_f32 v[160:161], v[160:161], v[198:199] op_sel_hi:[1,0]
	v_pk_mul_f32 v[162:163], v[162:163], v[198:199] op_sel_hi:[1,0]
	ds_write_b128 v208, v[156:159] offset:1024
	ds_write_b128 v209, v[160:163] offset:1024
	v_pk_mul_f32 v[164:165], v[164:165], v[202:203] op_sel_hi:[1,0]
	v_pk_mul_f32 v[166:167], v[166:167], v[202:203] op_sel_hi:[1,0]
	v_pk_mul_f32 v[168:169], v[168:169], v[202:203] op_sel_hi:[1,0]
	v_pk_mul_f32 v[170:171], v[170:171], v[202:203] op_sel_hi:[1,0]
	ds_write_b128 v208, v[164:167] offset:1536
	ds_write_b128 v209, v[168:171] offset:1536
	s_mov_b64 exec, s[52:53]
	global_store_dword v205, v194, s[64:65]
	s_mov_b64 exec, -1
	s_add_u32 s64, s64, 0x800
	s_addc_u32 s65, s65, 0
	s_cmp_eq_u32 s14, 0
	s_cbranch_scc1 .Lp4a_csb
	s_cmp_gt_u32 s14, 37
	s_cbranch_scc1 .Lp4a_csb
	s_waitcnt vmcnt(10)
	v_cvt_pk_bf16_f32 v180, v210, v211
	v_cvt_pk_bf16_f32 v181, v212, v213
	v_cvt_pk_bf16_f32 v182, v214, v215
	v_cvt_pk_bf16_f32 v183, v216, v217
	v_cvt_pk_bf16_f32 v184, v218, v219
	v_cvt_pk_bf16_f32 v185, v220, v221
	v_cvt_pk_bf16_f32 v186, v222, v223
	v_cvt_pk_bf16_f32 v187, v224, v225
	global_store_dwordx4 v228, v[180:183], s[6:7]
	global_store_dwordx4 v228, v[184:187], s[6:7] offset:16

; #define WG_BAR() do { asm volatile("s_waitcnt lgkmcnt(0)" ::: "memory"); __builtin_amdgcn_s_barrier(); asm volatile("" ::: "memory"); } while (0)
; #define SCAN_ITER(D_, SET) do { const int blk = blk0 + (D_); if (blk + 1 < TT / TB) { SCAN_PRODUCE(blk + 1, SET); if (blk + 1 + PD < TT / TB) SCAN_LOAD(blk + 1 + PD, SET); } WG_BAR(); } while (0)
; __global__ void __launch_bounds__(NTHR) hymba_fwd(Params P) {
;     ...
;               SCAN_LOAD(0, 0); SCAN_LOAD(1, 1);
;               SCAN_PRODUCE(0, 0); SCAN_LOAD(2, 0);
;               WG_BAR();
;               static_assert((TT / TB) % PD == 0 && PD == 2, "block loop is unrolled by PD = 2");
;               for (int blk0 = 0; blk0 < TT / TB; blk0 += PD) {
;     ...
;                 SCAN_ITER(0, 1); SCAN_ITER(1, 0);
;     ...
;               }
.Lp4a_clb:
	global_load_dwordx4 v[94:97], v0, s[56:57]
	global_load_dwordx4 v[98:101], v0, s[56:57] offset:2048
	global_load_dwordx4 v[102:105], v0, s[58:59]
	global_load_dwordx4 v[106:109], v155, s[56:57]
	global_load_dwordx4 v[110:113], v155, s[56:57] offset:2048
	global_load_dwordx4 v[114:117], v155, s[58:59]
	global_load_dwordx4 v[118:121], v197, s[60:61]
	global_load_dwordx4 v[122:125], v204, s[62:63]
	global_load_dwordx4 v[126:129], v204, s[62:63] offset:16
	s_add_u32 s56, s56, 0x48000
	s_addc_u32 s57, s57, 0
	s_add_u32 s58, s58, 0x48000
	s_addc_u32 s59, s59, 0
	s_add_u32 s60, s60, 0x10000
	s_addc_u32 s61, s61, 0
	s_add_u32 s62, s62, 0x20000
	s_addc_u32 s63, s63, 0
	s_waitcnt lgkmcnt(0)
	s_barrier
	s_add_i32 s14, s14, 1
	s_cmp_lt_u32 s14, 38
	s_cbranch_scc1 .Lp4a_loopa
	s_waitcnt vmcnt(12)
	v_mov_b32_e32 v134, 0
	v_mov_b32_e32 v135, 0
	v_mov_b32_e32 v148, 0
	v_mov_b32_e32 v149, 0
	v_mov_b32_e32 v192, 0
	v_mov_b32_e32 v193, 0
	v_mov_b32_e32 v194, 0
	v_mov_b32_e32 v195, 0
	v_lshlrev_b32_e32 v180, 16, v58
	v_and_b32_e32 v181, 0xffff0000, v58
	v_lshlrev_b32_e32 v182, 16, v59
	v_and_b32_e32 v183, 0xffff0000, v59
	v_lshlrev_b32_e32 v184, 16, v70
	v_and_b32_e32 v185, 0xffff0000, v70
	v_lshlrev_b32_e32 v186, 16, v71
	v_and_b32_e32 v187, 0xffff0000, v71
	v_pk_add_f32 v[184:185], v[184:185], v[180:181] neg_lo:[0,1] neg_hi:[0,1]
	v_pk_add_f32 v[186:187], v[186:187], v[182:183] neg_lo:[0,1] neg_hi:[0,1]
	v_pk_fma_f32 v[184:185], v[184:185], v[2:3], v[180:181]
	v_pk_fma_f32 v[186:187], v[186:187], v[4:5], v[182:183]
	v_lshlrev_b32_e32 v180, 16, v62
	v_and_b32_e32 v181, 0xffff0000, v62
	v_lshlrev_b32_e32 v182, 16, v63
	v_and_b32_e32 v183, 0xffff0000, v63
	v_lshlrev_b32_e32 v130, 16, v74
	v_and_b32_e32 v131, 0xffff0000, v74
	v_lshlrev_b32_e32 v132, 16, v75
	v_and_b32_e32 v133, 0xffff0000, v75
	v_pk_add_f32 v[130:131], v[130:131], v[180:181] neg_lo:[0,1] neg_hi:[0,1]
	v_pk_add_f32 v[132:133], v[132:133], v[182:183] neg_lo:[0,1] neg_hi:[0,1]
	v_pk_fma_f32 v[130:131], v[130:131], v[10:11], v[180:181]
	v_pk_fma_f32 v[132:133], v[132:133], v[12:13], v[182:183]
	v_lshlrev_b32_e32 v180, 16, v66
	v_and_b32_e32 v181, 0xffff0000, v66
	v_lshlrev_b32_e32 v182, 16, v67
	v_and_b32_e32 v183, 0xffff0000, v67
	v_lshlrev_b32_e32 v164, 16, v78
	v_and_b32_e32 v165, 0xffff0000, v78
	v_lshlrev_b32_e32 v166, 16, v79
	v_and_b32_e32 v167, 0xffff0000, v79
	v_pk_add_f32 v[164:165], v[164:165], v[180:181] neg_lo:[0,1] neg_hi:[0,1]
	v_pk_add_f32 v[166:167], v[166:167], v[182:183] neg_lo:[0,1] neg_hi:[0,1]
	v_pk_fma_f32 v[164:165], v[164:165], v[18:19], v[180:181]
	v_pk_fma_f32 v[166:167], v[166:167], v[20:21], v[182:183]
	ds_write_b128 v206, v[164:167] offset:1280
	v_lshlrev_b32_e32 v188, 16, v82
	v_and_b32_e32 v189, 0xffff0000, v82
	v_lshlrev_b32_e32 v190, 16, v83
	v_and_b32_e32 v191, 0xffff0000, v83
	v_pk_mul_f32 v[140:141], v[130:131], v[26:27]
	v_pk_mul_f32 v[142:143], v[132:133], v[28:29]
	v_pk_fma_f32 v[134:135], v[140:141], v[140:141], v[134:135]
	v_pk_fma_f32 v[134:135], v[142:143], v[142:143], v[134:135]
	v_pk_fma_f32 v[180:181], v[188:189], v[34:35], v[42:43]
	v_pk_fma_f32 v[182:183], v[190:191], v[36:37], v[44:45]
	v_pk_mul_f32 v[180:181], v[130:131], v[180:181]
	v_pk_mul_f32 v[182:183], v[132:133], v[182:183]
	ds_write_b128 v206, v[180:183] offset:768
	v_pk_mul_f32 v[130:131], v[180:181], v[184:185]
	v_pk_mul_f32 v[132:133], v[182:183], v[186:187]
	v_pk_add_f32 v[192:193], v[192:193], v[130:131]
	v_pk_add_f32 v[192:193], v[192:193], v[132:133]
	v_pk_fma_f32 v[194:195], v[130:131], v[50:51], v[194:195]
	v_pk_fma_f32 v[194:195], v[132:133], v[52:53], v[194:195]
	v_pk_mul_f32 v[156:157], v[140:141], v[188:189]
	v_pk_mul_f32 v[158:159], v[142:143], v[190:191]
	v_pk_fma_f32 v[148:149], v[156:157], v[184:185], v[148:149]
	v_pk_fma_f32 v[148:149], v[158:159], v[186:187], v[148:149]
	v_pk_mul_f32 v[172:173], v[86:87], v[184:185]
	v_pk_mul_f32 v[174:175], v[88:89], v[186:187]
	ds_write_b128 v206, v[86:89] offset:512
	v_lshlrev_b32_e32 v180, 16, v60
	v_and_b32_e32 v181, 0xffff0000, v60
	v_lshlrev_b32_e32 v182, 16, v61
	v_and_b32_e32 v183, 0xffff0000, v61
	v_lshlrev_b32_e32 v184, 16, v72
	v_and_b32_e32 v185, 0xffff0000, v72
	v_lshlrev_b32_e32 v186, 16, v73
	v_and_b32_e32 v187, 0xffff0000, v73
	v_pk_add_f32 v[184:185], v[184:185], v[180:181] neg_lo:[0,1] neg_hi:[0,1]
	v_pk_add_f32 v[186:187], v[186:187], v[182:183] neg_lo:[0,1] neg_hi:[0,1]
	v_pk_fma_f32 v[184:185], v[184:185], v[6:7], v[180:181]
	v_pk_fma_f32 v[186:187], v[186:187], v[8:9], v[182:183]
	v_lshlrev_b32_e32 v180, 16, v64
	v_and_b32_e32 v181, 0xffff0000, v64
	v_lshlrev_b32_e32 v182, 16, v65
	v_and_b32_e32 v183, 0xffff0000, v65
	v_lshlrev_b32_e32 v130, 16, v76
	v_and_b32_e32 v131, 0xffff0000, v76
	v_lshlrev_b32_e32 v132, 16, v77
	v_and_b32_e32 v133, 0xffff0000, v77
	v_pk_add_f32 v[130:131], v[130:131], v[180:181] neg_lo:[0,1] neg_hi:[0,1]
	v_pk_add_f32 v[132:133], v[132:133], v[182:183] neg_lo:[0,1] neg_hi:[0,1]
	v_pk_fma_f32 v[130:131], v[130:131], v[14:15], v[180:181]
	v_pk_fma_f32 v[132:133], v[132:133], v[16:17], v[182:183]
	v_lshlrev_b32_e32 v180, 16, v68
	v_and_b32_e32 v181, 0xffff0000, v68
	v_lshlrev_b32_e32 v182, 16, v69
	v_and_b32_e32 v183, 0xffff0000, v69
	v_lshlrev_b32_e32 v168, 16, v80
	v_and_b32_e32 v169, 0xffff0000, v80
	v_lshlrev_b32_e32 v170, 16, v81
	v_and_b32_e32 v171, 0xffff0000, v81
	v_pk_add_f32 v[168:169], v[168:169], v[180:181] neg_lo:[0,1] neg_hi:[0,1]
	v_pk_add_f32 v[170:171], v[170:171], v[182:183] neg_lo:[0,1] neg_hi:[0,1]
	v_pk_fma_f32 v[168:169], v[168:169], v[22:23], v[180:181]
	v_pk_fma_f32 v[170:171], v[170:171], v[24:25], v[182:183]
	ds_write_b128 v207, v[168:171] offset:1280
; #define WG_BAR() do { asm volatile("s_waitcnt lgkmcnt(0)" ::: "memory"); __builtin_amdgcn_s_barrier(); asm volatile("" ::: "memory"); } while (0)
; #define SCAN_ITER(D_, SET) do { const int blk = blk0 + (D_); if (blk + 1 < TT / TB) { SCAN_PRODUCE(blk + 1, SET); if (blk + 1 + PD < TT / TB) SCAN_LOAD(blk + 1 + PD, SET); } WG_BAR(); } while (0)
; __global__ void __launch_bounds__(NTHR) hymba_fwd(Params P) {
;     ...
;               SCAN_LOAD(0, 0); SCAN_LOAD(1, 1);
;               SCAN_PRODUCE(0, 0); SCAN_LOAD(2, 0);
;               WG_BAR();
;               static_assert((TT / TB) % PD == 0 && PD == 2, "block loop is unrolled by PD = 2");
;               for (int blk0 = 0; blk0 < TT / TB; blk0 += PD) {
;     ...
;                 SCAN_ITER(0, 1); SCAN_ITER(1, 0);
	v_lshlrev_b32_e32 v188, 16, v84
	v_and_b32_e32 v189, 0xffff0000, v84
	v_lshlrev_b32_e32 v190, 16, v85
	v_and_b32_e32 v191, 0xffff0000, v85
	v_pk_mul_f32 v[144:145], v[130:131], v[30:31]
	v_pk_mul_f32 v[146:147], v[132:133], v[32:33]
	v_pk_fma_f32 v[134:135], v[144:145], v[144:145], v[134:135]
	v_pk_fma_f32 v[134:135], v[146:147], v[146:147], v[134:135]
	v_pk_fma_f32 v[180:181], v[188:189], v[38:39], v[46:47]
	v_pk_fma_f32 v[182:183], v[190:191], v[40:41], v[48:49]
	v_pk_mul_f32 v[180:181], v[130:131], v[180:181]
	v_pk_mul_f32 v[182:183], v[132:133], v[182:183]
	ds_write_b128 v207, v[180:183] offset:768
	v_pk_mul_f32 v[130:131], v[180:181], v[184:185]
	v_pk_mul_f32 v[132:133], v[182:183], v[186:187]
	v_pk_add_f32 v[192:193], v[192:193], v[130:131]
	v_pk_add_f32 v[192:193], v[192:193], v[132:133]
	v_pk_fma_f32 v[194:195], v[130:131], v[54:55], v[194:195]
	v_pk_fma_f32 v[194:195], v[132:133], v[56:57], v[194:195]
	v_pk_mul_f32 v[160:161], v[144:145], v[188:189]
	v_pk_mul_f32 v[162:163], v[146:147], v[190:191]
	v_pk_fma_f32 v[148:149], v[160:161], v[184:185], v[148:149]
	v_pk_fma_f32 v[148:149], v[162:163], v[186:187], v[148:149]
	v_pk_mul_f32 v[176:177], v[90:91], v[184:185]
	v_pk_mul_f32 v[178:179], v[92:93], v[186:187]
	ds_write_b128 v207, v[90:93] offset:512
	v_add_f32_e32 v134, v134, v135
	v_add_f32_e32 v148, v148, v149
	v_add_f32_e32 v202, v192, v193
	v_add_f32_e32 v194, v194, v195
	v_add_f32_dpp v134, v134, v134 quad_perm:[1,0,3,2] row_mask:0xf bank_mask:0xf bound_ctrl:1
	v_add_f32_dpp v148, v148, v148 quad_perm:[1,0,3,2] row_mask:0xf bank_mask:0xf bound_ctrl:1
	v_add_f32_dpp v202, v202, v202 quad_perm:[1,0,3,2] row_mask:0xf bank_mask:0xf bound_ctrl:1
	v_add_f32_dpp v194, v194, v194 quad_perm:[1,0,3,2] row_mask:0xf bank_mask:0xf bound_ctrl:1
	v_add_f32_dpp v134, v134, v134 quad_perm:[2,3,0,1] row_mask:0xf bank_mask:0xf bound_ctrl:1
	v_add_f32_dpp v148, v148, v148 quad_perm:[2,3,0,1] row_mask:0xf bank_mask:0xf bound_ctrl:1
	v_add_f32_dpp v202, v202, v202 quad_perm:[2,3,0,1] row_mask:0xf bank_mask:0xf bound_ctrl:1
	v_add_f32_dpp v194, v194, v194 quad_perm:[2,3,0,1] row_mask:0xf bank_mask:0xf bound_ctrl:1
	v_add_f32_dpp v134, v134, v134 row_half_mirror row_mask:0xf bank_mask:0xf bound_ctrl:1
	v_add_f32_dpp v148, v148, v148 row_half_mirror row_mask:0xf bank_mask:0xf bound_ctrl:1
	v_add_f32_dpp v202, v202, v202 row_half_mirror row_mask:0xf bank_mask:0xf bound_ctrl:1
	v_add_f32_dpp v194, v194, v194 row_half_mirror row_mask:0xf bank_mask:0xf bound_ctrl:1
	v_max_f32_e32 v134, 0x179abe15, v134
	v_rsq_f32_e32 v198, v134
	s_nop 1
	v_mul_f32_e32 v200, v198, v148
	v_pk_mul_f32 v[180:181], v[140:141], v[198:199] op_sel_hi:[1,0] neg_lo:[0,1] neg_hi:[0,1]
	v_pk_mul_f32 v[182:183], v[142:143], v[198:199] op_sel_hi:[1,0] neg_lo:[0,1] neg_hi:[0,1]
	v_pk_mul_f32 v[184:185], v[144:145], v[198:199] op_sel_hi:[1,0] neg_lo:[0,1] neg_hi:[0,1]
	v_pk_mul_f32 v[186:187], v[146:147], v[198:199] op_sel_hi:[1,0] neg_lo:[0,1] neg_hi:[0,1]
	ds_write_b128 v206, v[180:183] offset:0
	ds_write_b128 v207, v[184:187] offset:0
	v_pk_fma_f32 v[172:173], v[180:181], v[200:201], v[172:173] op_sel_hi:[1,0,1]
	v_pk_fma_f32 v[174:175], v[182:183], v[200:201], v[174:175] op_sel_hi:[1,0,1]
	v_pk_fma_f32 v[176:177], v[184:185], v[200:201], v[176:177] op_sel_hi:[1,0,1]
	v_pk_fma_f32 v[178:179], v[186:187], v[200:201], v[178:179] op_sel_hi:[1,0,1]
	ds_write_b128 v206, v[172:175] offset:256
	ds_write_b128 v207, v[176:179] offset:256
	v_pk_mul_f32 v[156:157], v[156:157], v[198:199] op_sel_hi:[1,0]
	v_pk_mul_f32 v[158:159], v[158:159], v[198:199] op_sel_hi:[1,0]
	v_pk_mul_f32 v[160:161], v[160:161], v[198:199] op_sel_hi:[1,0]
	v_pk_mul_f32 v[162:163], v[162:163], v[198:199] op_sel_hi:[1,0]
	ds_write_b128 v206, v[156:159] offset:1024
	ds_write_b128 v207, v[160:163] offset:1024
	v_pk_mul_f32 v[164:165], v[164:165], v[202:203] op_sel_hi:[1,0]
	v_pk_mul_f32 v[166:167], v[166:167], v[202:203] op_sel_hi:[1,0]
	v_pk_mul_f32 v[168:169], v[168:169], v[202:203] op_sel_hi:[1,0]
	v_pk_mul_f32 v[170:171], v[170:171], v[202:203] op_sel_hi:[1,0]
	ds_write_b128 v206, v[164:167] offset:1536
	ds_write_b128 v207, v[168:171] offset:1536
	s_mov_b64 exec, s[52:53]
	global_store_dword v205, v194, s[64:65]
	s_mov_b64 exec, -1
	s_add_u32 s64, s64, 0x800
	s_addc_u32 s65, s65, 0
	global_load_dwordx4 v[58:61], v0, s[56:57]
	global_load_dwordx4 v[62:65], v0, s[56:57] offset:2048
	global_load_dwordx4 v[66:69], v0, s[58:59]
	global_load_dwordx4 v[70:73], v155, s[56:57]
	global_load_dwordx4 v[74:77], v155, s[56:57] offset:2048
	global_load_dwordx4 v[78:81], v155, s[58:59]
	global_load_dwordx4 v[82:85], v197, s[60:61]
	global_load_dwordx4 v[86:89], v204, s[62:63]
	global_load_dwordx4 v[90:93], v204, s[62:63] offset:16
	s_add_u32 s56, s56, 0x48000
	s_addc_u32 s57, s57, 0
	s_add_u32 s58, s58, 0x48000
	s_addc_u32 s59, s59, 0
	s_add_u32 s60, s60, 0x10000
	s_addc_u32 s61, s61, 0
	s_add_u32 s62, s62, 0x20000
	s_addc_u32 s63, s63, 0
	s_waitcnt lgkmcnt(0)
	s_barrier
	s_add_i32 s14, s14, 1
; #define WG_BAR() do { asm volatile("s_waitcnt lgkmcnt(0)" ::: "memory"); __builtin_amdgcn_s_barrier(); asm volatile("" ::: "memory"); } while (0)
; #define SCAN_ITER(D_, SET) do { const int blk = blk0 + (D_); if (blk + 1 < TT / TB) { SCAN_PRODUCE(blk + 1, SET); if (blk + 1 + PD < TT / TB) SCAN_LOAD(blk + 1 + PD, SET); } WG_BAR(); } while (0)
; __global__ void __launch_bounds__(NTHR) hymba_fwd(Params P) {
;     ...
;               SCAN_LOAD(0, 0); SCAN_LOAD(1, 1);
;               SCAN_PRODUCE(0, 0); SCAN_LOAD(2, 0);
;               WG_BAR();
;               static_assert((TT / TB) % PD == 0 && PD == 2, "block loop is unrolled by PD = 2");
;               for (int blk0 = 0; blk0 < TT / TB; blk0 += PD) {
;     ...
;                 SCAN_ITER(0, 1); SCAN_ITER(1, 0);
.Lp4a_loopb:
	s_waitcnt vmcnt(10)
	v_mov_b32_e32 v134, 0
	v_mov_b32_e32 v135, 0
	v_mov_b32_e32 v148, 0
	v_mov_b32_e32 v149, 0
	v_mov_b32_e32 v192, 0
	v_mov_b32_e32 v193, 0
	v_mov_b32_e32 v194, 0
	v_mov_b32_e32 v195, 0
	v_lshlrev_b32_e32 v180, 16, v94
	v_and_b32_e32 v181, 0xffff0000, v94
	v_lshlrev_b32_e32 v182, 16, v95
	v_and_b32_e32 v183, 0xffff0000, v95
	v_lshlrev_b32_e32 v184, 16, v106
	v_and_b32_e32 v185, 0xffff0000, v106
	v_lshlrev_b32_e32 v186, 16, v107
	v_and_b32_e32 v187, 0xffff0000, v107
	v_pk_add_f32 v[184:185], v[184:185], v[180:181] neg_lo:[0,1] neg_hi:[0,1]
	v_pk_add_f32 v[186:187], v[186:187], v[182:183] neg_lo:[0,1] neg_hi:[0,1]
	v_pk_fma_f32 v[184:185], v[184:185], v[2:3], v[180:181]
	v_pk_fma_f32 v[186:187], v[186:187], v[4:5], v[182:183]
	v_lshlrev_b32_e32 v180, 16, v98
	v_and_b32_e32 v181, 0xffff0000, v98
	v_lshlrev_b32_e32 v182, 16, v99
	v_and_b32_e32 v183, 0xffff0000, v99
	v_lshlrev_b32_e32 v130, 16, v110
	v_and_b32_e32 v131, 0xffff0000, v110
	v_lshlrev_b32_e32 v132, 16, v111
	v_and_b32_e32 v133, 0xffff0000, v111
	v_pk_add_f32 v[130:131], v[130:131], v[180:181] neg_lo:[0,1] neg_hi:[0,1]
	v_pk_add_f32 v[132:133], v[132:133], v[182:183] neg_lo:[0,1] neg_hi:[0,1]
	v_pk_fma_f32 v[130:131], v[130:131], v[10:11], v[180:181]
	v_pk_fma_f32 v[132:133], v[132:133], v[12:13], v[182:183]
	v_lshlrev_b32_e32 v180, 16, v102
	v_and_b32_e32 v181, 0xffff0000, v102
	v_lshlrev_b32_e32 v182, 16, v103
	v_and_b32_e32 v183, 0xffff0000, v103
	v_lshlrev_b32_e32 v164, 16, v114
	v_and_b32_e32 v165, 0xffff0000, v114
	v_lshlrev_b32_e32 v166, 16, v115
	v_and_b32_e32 v167, 0xffff0000, v115
	v_pk_add_f32 v[164:165], v[164:165], v[180:181] neg_lo:[0,1] neg_hi:[0,1]
	v_pk_add_f32 v[166:167], v[166:167], v[182:183] neg_lo:[0,1] neg_hi:[0,1]
	v_pk_fma_f32 v[164:165], v[164:165], v[18:19], v[180:181]
	v_pk_fma_f32 v[166:167], v[166:167], v[20:21], v[182:183]
	ds_write_b128 v208, v[164:167] offset:1280
	v_lshlrev_b32_e32 v188, 16, v118
	v_and_b32_e32 v189, 0xffff0000, v118
	v_lshlrev_b32_e32 v190, 16, v119
	v_and_b32_e32 v191, 0xffff0000, v119
	v_pk_mul_f32 v[140:141], v[130:131], v[26:27]
	v_pk_mul_f32 v[142:143], v[132:133], v[28:29]
	v_pk_fma_f32 v[134:135], v[140:141], v[140:141], v[134:135]
	v_pk_fma_f32 v[134:135], v[142:143], v[142:143], v[134:135]
	v_pk_fma_f32 v[180:181], v[188:189], v[34:35], v[42:43]
	v_pk_fma_f32 v[182:183], v[190:191], v[36:37], v[44:45]
	v_pk_mul_f32 v[180:181], v[130:131], v[180:181]
	v_pk_mul_f32 v[182:183], v[132:133], v[182:183]
	ds_write_b128 v208, v[180:183] offset:768
	v_pk_mul_f32 v[130:131], v[180:181], v[184:185]
	v_pk_mul_f32 v[132:133], v[182:183], v[186:187]
	v_pk_add_f32 v[192:193], v[192:193], v[130:131]
	v_pk_add_f32 v[192:193], v[192:193], v[132:133]
	v_pk_fma_f32 v[194:195], v[130:131], v[50:51], v[194:195]
	v_pk_fma_f32 v[194:195], v[132:133], v[52:53], v[194:195]
	v_pk_mul_f32 v[156:157], v[140:141], v[188:189]
	v_pk_mul_f32 v[158:159], v[142:143], v[190:191]
	v_pk_fma_f32 v[148:149], v[156:157], v[184:185], v[148:149]
	v_pk_fma_f32 v[148:149], v[158:159], v[186:187], v[148:149]
	v_pk_mul_f32 v[172:173], v[122:123], v[184:185]
	v_pk_mul_f32 v[174:175], v[124:125], v[186:187]
	ds_write_b128 v208, v[122:125] offset:512
	v_lshlrev_b32_e32 v180, 16, v96
	v_and_b32_e32 v181, 0xffff0000, v96
	v_lshlrev_b32_e32 v182, 16, v97
	v_and_b32_e32 v183, 0xffff0000, v97
	v_lshlrev_b32_e32 v184, 16, v108
	v_and_b32_e32 v185, 0xffff0000, v108
	v_lshlrev_b32_e32 v186, 16, v109
	v_and_b32_e32 v187, 0xffff0000, v109
	v_pk_add_f32 v[184:185], v[184:185], v[180:181] neg_lo:[0,1] neg_hi:[0,1]
	v_pk_add_f32 v[186:187], v[186:187], v[182:183] neg_lo:[0,1] neg_hi:[0,1]
	v_pk_fma_f32 v[184:185], v[184:185], v[6:7], v[180:181]
	v_pk_fma_f32 v[186:187], v[186:187], v[8:9], v[182:183]
	v_lshlrev_b32_e32 v180, 16, v100
	v_and_b32_e32 v181, 0xffff0000, v100
	v_lshlrev_b32_e32 v182, 16, v101
	v_and_b32_e32 v183, 0xffff0000, v101
	v_lshlrev_b32_e32 v130, 16, v112
	v_and_b32_e32 v131, 0xffff0000, v112
	v_lshlrev_b32_e32 v132, 16, v113
	v_and_b32_e32 v133, 0xffff0000, v113
	v_pk_add_f32 v[130:131], v[130:131], v[180:181] neg_lo:[0,1] neg_hi:[0,1]
	v_pk_add_f32 v[132:133], v[132:133], v[182:183] neg_lo:[0,1] neg_hi:[0,1]
	v_pk_fma_f32 v[130:131], v[130:131], v[14:15], v[180:181]
	v_pk_fma_f32 v[132:133], v[132:133], v[16:17], v[182:183]
	v_lshlrev_b32_e32 v180, 16, v104
	v_and_b32_e32 v181, 0xffff0000, v104
	v_lshlrev_b32_e32 v182, 16, v105
	v_and_b32_e32 v183, 0xffff0000, v105
	v_lshlrev_b32_e32 v168, 16, v116
	v_and_b32_e32 v169, 0xffff0000, v116
	v_lshlrev_b32_e32 v170, 16, v117
	v_and_b32_e32 v171, 0xffff0000, v117
	v_pk_add_f32 v[168:169], v[168:169], v[180:181] neg_lo:[0,1] neg_hi:[0,1]
	v_pk_add_f32 v[170:171], v[170:171], v[182:183] neg_lo:[0,1] neg_hi:[0,1]
	v_pk_fma_f32 v[168:169], v[168:169], v[22:23], v[180:181]
	v_pk_fma_f32 v[170:171], v[170:171], v[24:25], v[182:183]
	ds_write_b128 v209, v[168:171] offset:1280
	v_lshlrev_b32_e32 v188, 16, v120
	v_and_b32_e32 v189, 0xffff0000, v120
	v_lshlrev_b32_e32 v190, 16, v121
	v_and_b32_e32 v191, 0xffff0000, v121
	v_pk_mul_f32 v[144:145], v[130:131], v[30:31]
	v_pk_mul_f32 v[146:147], v[132:133], v[32:33]
	v_pk_fma_f32 v[134:135], v[144:145], v[144:145], v[134:135]
	v_pk_fma_f32 v[134:135], v[146:147], v[146:147], v[134:135]
	v_pk_fma_f32 v[180:181], v[188:189], v[38:39], v[46:47]
	v_pk_fma_f32 v[182:183], v[190:191], v[40:41], v[48:49]
	v_pk_mul_f32 v[180:181], v[130:131], v[180:181]
	v_pk_mul_f32 v[182:183], v[132:133], v[182:183]
	ds_write_b128 v209, v[180:183] offset:768
	v_pk_mul_f32 v[130:131], v[180:181], v[184:185]
	v_pk_mul_f32 v[132:133], v[182:183], v[186:187]
; #define WG_BAR() do { asm volatile("s_waitcnt lgkmcnt(0)" ::: "memory"); __builtin_amdgcn_s_barrier(); asm volatile("" ::: "memory"); } while (0)
; #define SCAN_ITER(D_, SET) do { const int blk = blk0 + (D_); if (blk + 1 < TT / TB) { SCAN_PRODUCE(blk + 1, SET); if (blk + 1 + PD < TT / TB) SCAN_LOAD(blk + 1 + PD, SET); } WG_BAR(); } while (0)
; __global__ void __launch_bounds__(NTHR) hymba_fwd(Params P) {
;     ...
;               SCAN_LOAD(0, 0); SCAN_LOAD(1, 1);
;               SCAN_PRODUCE(0, 0); SCAN_LOAD(2, 0);
;               WG_BAR();
;               static_assert((TT / TB) % PD == 0 && PD == 2, "block loop is unrolled by PD = 2");
;               for (int blk0 = 0; blk0 < TT / TB; blk0 += PD) {
;     ...
;                 SCAN_ITER(0, 1); SCAN_ITER(1, 0);
	v_pk_add_f32 v[192:193], v[192:193], v[130:131]
	v_pk_add_f32 v[192:193], v[192:193], v[132:133]
	v_pk_fma_f32 v[194:195], v[130:131], v[54:55], v[194:195]
	v_pk_fma_f32 v[194:195], v[132:133], v[56:57], v[194:195]
	v_pk_mul_f32 v[160:161], v[144:145], v[188:189]
	v_pk_mul_f32 v[162:163], v[146:147], v[190:191]
	v_pk_fma_f32 v[148:149], v[160:161], v[184:185], v[148:149]
	v_pk_fma_f32 v[148:149], v[162:163], v[186:187], v[148:149]
	v_pk_mul_f32 v[176:177], v[126:127], v[184:185]
	v_pk_mul_f32 v[178:179], v[128:129], v[186:187]
	ds_write_b128 v209, v[126:129] offset:512
	v_add_f32_e32 v134, v134, v135
	v_add_f32_e32 v148, v148, v149
	v_add_f32_e32 v202, v192, v193
	v_add_f32_e32 v194, v194, v195
	v_add_f32_dpp v134, v134, v134 quad_perm:[1,0,3,2] row_mask:0xf bank_mask:0xf bound_ctrl:1
	v_add_f32_dpp v148, v148, v148 quad_perm:[1,0,3,2] row_mask:0xf bank_mask:0xf bound_ctrl:1
	v_add_f32_dpp v202, v202, v202 quad_perm:[1,0,3,2] row_mask:0xf bank_mask:0xf bound_ctrl:1
	v_add_f32_dpp v194, v194, v194 quad_perm:[1,0,3,2] row_mask:0xf bank_mask:0xf bound_ctrl:1
	v_add_f32_dpp v134, v134, v134 quad_perm:[2,3,0,1] row_mask:0xf bank_mask:0xf bound_ctrl:1
	v_add_f32_dpp v148, v148, v148 quad_perm:[2,3,0,1] row_mask:0xf bank_mask:0xf bound_ctrl:1
	v_add_f32_dpp v202, v202, v202 quad_perm:[2,3,0,1] row_mask:0xf bank_mask:0xf bound_ctrl:1
	v_add_f32_dpp v194, v194, v194 quad_perm:[2,3,0,1] row_mask:0xf bank_mask:0xf bound_ctrl:1
	v_add_f32_dpp v134, v134, v134 row_half_mirror row_mask:0xf bank_mask:0xf bound_ctrl:1
	v_add_f32_dpp v148, v148, v148 row_half_mirror row_mask:0xf bank_mask:0xf bound_ctrl:1
	v_add_f32_dpp v202, v202, v202 row_half_mirror row_mask:0xf bank_mask:0xf bound_ctrl:1
	v_add_f32_dpp v194, v194, v194 row_half_mirror row_mask:0xf bank_mask:0xf bound_ctrl:1
	v_max_f32_e32 v134, 0x179abe15, v134
	v_rsq_f32_e32 v198, v134
	s_nop 1
	v_mul_f32_e32 v200, v198, v148
	v_pk_mul_f32 v[180:181], v[140:141], v[198:199] op_sel_hi:[1,0] neg_lo:[0,1] neg_hi:[0,1]
	v_pk_mul_f32 v[182:183], v[142:143], v[198:199] op_sel_hi:[1,0] neg_lo:[0,1] neg_hi:[0,1]
	v_pk_mul_f32 v[184:185], v[144:145], v[198:199] op_sel_hi:[1,0] neg_lo:[0,1] neg_hi:[0,1]
	v_pk_mul_f32 v[186:187], v[146:147], v[198:199] op_sel_hi:[1,0] neg_lo:[0,1] neg_hi:[0,1]
	ds_write_b128 v208, v[180:183] offset:0
	ds_write_b128 v209, v[184:187] offset:0
	v_pk_fma_f32 v[172:173], v[180:181], v[200:201], v[172:173] op_sel_hi:[1,0,1]
	v_pk_fma_f32 v[174:175], v[182:183], v[200:201], v[174:175] op_sel_hi:[1,0,1]
	v_pk_fma_f32 v[176:177], v[184:185], v[200:201], v[176:177] op_sel_hi:[1,0,1]
	v_pk_fma_f32 v[178:179], v[186:187], v[200:201], v[178:179] op_sel_hi:[1,0,1]
	ds_write_b128 v208, v[172:175] offset:256
	ds_write_b128 v209, v[176:179] offset:256
	v_pk_mul_f32 v[156:157], v[156:157], v[198:199] op_sel_hi:[1,0]
	v_pk_mul_f32 v[158:159], v[158:159], v[198:199] op_sel_hi:[1,0]
	v_pk_mul_f32 v[160:161], v[160:161], v[198:199] op_sel_hi:[1,0]
	v_pk_mul_f32 v[162:163], v[162:163], v[198:199] op_sel_hi:[1,0]
	ds_write_b128 v208, v[156:159] offset:1024
	ds_write_b128 v209, v[160:163] offset:1024
	v_pk_mul_f32 v[164:165], v[164:165], v[202:203] op_sel_hi:[1,0]
	v_pk_mul_f32 v[166:167], v[166:167], v[202:203] op_sel_hi:[1,0]
	v_pk_mul_f32 v[168:169], v[168:169], v[202:203] op_sel_hi:[1,0]
	v_pk_mul_f32 v[170:171], v[170:171], v[202:203] op_sel_hi:[1,0]
	ds_write_b128 v208, v[164:167] offset:1536
	ds_write_b128 v209, v[168:171] offset:1536
	s_mov_b64 exec, s[52:53]
	global_store_dword v205, v194, s[64:65]
	s_mov_b64 exec, -1
	s_add_u32 s64, s64, 0x800
	s_addc_u32 s65, s65, 0
	global_load_dwordx4 v[94:97], v0, s[56:57]
	global_load_dwordx4 v[98:101], v0, s[56:57] offset:2048
	global_load_dwordx4 v[102:105], v0, s[58:59]
	global_load_dwordx4 v[106:109], v155, s[56:57]
	global_load_dwordx4 v[110:113], v155, s[56:57] offset:2048
	global_load_dwordx4 v[114:117], v155, s[58:59]
	global_load_dwordx4 v[118:121], v197, s[60:61]
	global_load_dwordx4 v[122:125], v204, s[62:63]
	global_load_dwordx4 v[126:129], v204, s[62:63] offset:16
	s_add_u32 s56, s56, 0x48000
	s_addc_u32 s57, s57, 0
	s_add_u32 s58, s58, 0x48000
	s_addc_u32 s59, s59, 0
	s_add_u32 s60, s60, 0x10000
	s_addc_u32 s61, s61, 0
	s_add_u32 s62, s62, 0x20000
	s_addc_u32 s63, s63, 0
	s_waitcnt lgkmcnt(0)
	s_barrier
; #define WG_BAR() do { asm volatile("s_waitcnt lgkmcnt(0)" ::: "memory"); __builtin_amdgcn_s_barrier(); asm volatile("" ::: "memory"); } while (0)
; #define SCAN_ITER(D_, SET) do { const int blk = blk0 + (D_); if (blk + 1 < TT / TB) { SCAN_PRODUCE(blk + 1, SET); if (blk + 1 + PD < TT / TB) SCAN_LOAD(blk + 1 + PD, SET); } WG_BAR(); } while (0)
; __global__ void __launch_bounds__(NTHR) hymba_fwd(Params P) {
;     ...
;               SCAN_LOAD(0, 0); SCAN_LOAD(1, 1);
;               SCAN_PRODUCE(0, 0); SCAN_LOAD(2, 0);
;               WG_BAR();
;               static_assert((TT / TB) % PD == 0 && PD == 2, "block loop is unrolled by PD = 2");
;               for (int blk0 = 0; blk0 < TT / TB; blk0 += PD) {
;     ...
;                 SCAN_ITER(0, 1); SCAN_ITER(1, 0);
	s_add_i32 s14, s14, 1
	s_waitcnt vmcnt(10)
	v_mov_b32_e32 v134, 0
	v_mov_b32_e32 v135, 0
	v_mov_b32_e32 v148, 0
	v_mov_b32_e32 v149, 0
	v_mov_b32_e32 v192, 0
	v_mov_b32_e32 v193, 0
	v_mov_b32_e32 v194, 0
	v_mov_b32_e32 v195, 0
	v_lshlrev_b32_e32 v180, 16, v58
	v_and_b32_e32 v181, 0xffff0000, v58
	v_lshlrev_b32_e32 v182, 16, v59
	v_and_b32_e32 v183, 0xffff0000, v59
	v_lshlrev_b32_e32 v184, 16, v70
	v_and_b32_e32 v185, 0xffff0000, v70
	v_lshlrev_b32_e32 v186, 16, v71
	v_and_b32_e32 v187, 0xffff0000, v71
	v_pk_add_f32 v[184:185], v[184:185], v[180:181] neg_lo:[0,1] neg_hi:[0,1]
	v_pk_add_f32 v[186:187], v[186:187], v[182:183] neg_lo:[0,1] neg_hi:[0,1]
	v_pk_fma_f32 v[184:185], v[184:185], v[2:3], v[180:181]
	v_pk_fma_f32 v[186:187], v[186:187], v[4:5], v[182:183]
	v_lshlrev_b32_e32 v180, 16, v62
	v_and_b32_e32 v181, 0xffff0000, v62
	v_lshlrev_b32_e32 v182, 16, v63
	v_and_b32_e32 v183, 0xffff0000, v63
	v_lshlrev_b32_e32 v130, 16, v74
	v_and_b32_e32 v131, 0xffff0000, v74
	v_lshlrev_b32_e32 v132, 16, v75
	v_and_b32_e32 v133, 0xffff0000, v75
	v_pk_add_f32 v[130:131], v[130:131], v[180:181] neg_lo:[0,1] neg_hi:[0,1]
	v_pk_add_f32 v[132:133], v[132:133], v[182:183] neg_lo:[0,1] neg_hi:[0,1]
	v_pk_fma_f32 v[130:131], v[130:131], v[10:11], v[180:181]
	v_pk_fma_f32 v[132:133], v[132:133], v[12:13], v[182:183]
	v_lshlrev_b32_e32 v180, 16, v66
	v_and_b32_e32 v181, 0xffff0000, v66
	v_lshlrev_b32_e32 v182, 16, v67
	v_and_b32_e32 v183, 0xffff0000, v67
	v_lshlrev_b32_e32 v164, 16, v78
	v_and_b32_e32 v165, 0xffff0000, v78
	v_lshlrev_b32_e32 v166, 16, v79
	v_and_b32_e32 v167, 0xffff0000, v79
	v_pk_add_f32 v[164:165], v[164:165], v[180:181] neg_lo:[0,1] neg_hi:[0,1]
	v_pk_add_f32 v[166:167], v[166:167], v[182:183] neg_lo:[0,1] neg_hi:[0,1]
	v_pk_fma_f32 v[164:165], v[164:165], v[18:19], v[180:181]
	v_pk_fma_f32 v[166:167], v[166:167], v[20:21], v[182:183]
	ds_write_b128 v206, v[164:167] offset:1280
	v_lshlrev_b32_e32 v188, 16, v82
	v_and_b32_e32 v189, 0xffff0000, v82
	v_lshlrev_b32_e32 v190, 16, v83
	v_and_b32_e32 v191, 0xffff0000, v83
	v_pk_mul_f32 v[140:141], v[130:131], v[26:27]
	v_pk_mul_f32 v[142:143], v[132:133], v[28:29]
	v_pk_fma_f32 v[134:135], v[140:141], v[140:141], v[134:135]
	v_pk_fma_f32 v[134:135], v[142:143], v[142:143], v[134:135]
	v_pk_fma_f32 v[180:181], v[188:189], v[34:35], v[42:43]
	v_pk_fma_f32 v[182:183], v[190:191], v[36:37], v[44:45]
	v_pk_mul_f32 v[180:181], v[130:131], v[180:181]
	v_pk_mul_f32 v[182:183], v[132:133], v[182:183]
	ds_write_b128 v206, v[180:183] offset:768
	v_pk_mul_f32 v[130:131], v[180:181], v[184:185]
	v_pk_mul_f32 v[132:133], v[182:183], v[186:187]
	v_pk_add_f32 v[192:193], v[192:193], v[130:131]
	v_pk_add_f32 v[192:193], v[192:193], v[132:133]
	v_pk_fma_f32 v[194:195], v[130:131], v[50:51], v[194:195]
	v_pk_fma_f32 v[194:195], v[132:133], v[52:53], v[194:195]
	v_pk_mul_f32 v[156:157], v[140:141], v[188:189]
	v_pk_mul_f32 v[158:159], v[142:143], v[190:191]
	v_pk_fma_f32 v[148:149], v[156:157], v[184:185], v[148:149]
	v_pk_fma_f32 v[148:149], v[158:159], v[186:187], v[148:149]
	v_pk_mul_f32 v[172:173], v[86:87], v[184:185]
	v_pk_mul_f32 v[174:175], v[88:89], v[186:187]
	ds_write_b128 v206, v[86:89] offset:512
	v_lshlrev_b32_e32 v180, 16, v60
	v_and_b32_e32 v181, 0xffff0000, v60
	v_lshlrev_b32_e32 v182, 16, v61
	v_and_b32_e32 v183, 0xffff0000, v61
	v_lshlrev_b32_e32 v184, 16, v72
	v_and_b32_e32 v185, 0xffff0000, v72
	v_lshlrev_b32_e32 v186, 16, v73
	v_and_b32_e32 v187, 0xffff0000, v73
	v_pk_add_f32 v[184:185], v[184:185], v[180:181] neg_lo:[0,1] neg_hi:[0,1]
	v_pk_add_f32 v[186:187], v[186:187], v[182:183] neg_lo:[0,1] neg_hi:[0,1]
	v_pk_fma_f32 v[184:185], v[184:185], v[6:7], v[180:181]
	v_pk_fma_f32 v[186:187], v[186:187], v[8:9], v[182:183]
	v_lshlrev_b32_e32 v180, 16, v64
	v_and_b32_e32 v181, 0xffff0000, v64
	v_lshlrev_b32_e32 v182, 16, v65
	v_and_b32_e32 v183, 0xffff0000, v65
	v_lshlrev_b32_e32 v130, 16, v76
	v_and_b32_e32 v131, 0xffff0000, v76
	v_lshlrev_b32_e32 v132, 16, v77
	v_and_b32_e32 v133, 0xffff0000, v77
	v_pk_add_f32 v[130:131], v[130:131], v[180:181] neg_lo:[0,1] neg_hi:[0,1]
	v_pk_add_f32 v[132:133], v[132:133], v[182:183] neg_lo:[0,1] neg_hi:[0,1]
	v_pk_fma_f32 v[130:131], v[130:131], v[14:15], v[180:181]
	v_pk_fma_f32 v[132:133], v[132:133], v[16:17], v[182:183]
	v_lshlrev_b32_e32 v180, 16, v68
	v_and_b32_e32 v181, 0xffff0000, v68
	v_lshlrev_b32_e32 v182, 16, v69
	v_and_b32_e32 v183, 0xffff0000, v69
	v_lshlrev_b32_e32 v168, 16, v80
	v_and_b32_e32 v169, 0xffff0000, v80
	v_lshlrev_b32_e32 v170, 16, v81
	v_and_b32_e32 v171, 0xffff0000, v81
	v_pk_add_f32 v[168:169], v[168:169], v[180:181] neg_lo:[0,1] neg_hi:[0,1]
	v_pk_add_f32 v[170:171], v[170:171], v[182:183] neg_lo:[0,1] neg_hi:[0,1]
	v_pk_fma_f32 v[168:169], v[168:169], v[22:23], v[180:181]
	v_pk_fma_f32 v[170:171], v[170:171], v[24:25], v[182:183]
	ds_write_b128 v207, v[168:171] offset:1280
	v_lshlrev_b32_e32 v188, 16, v84
	v_and_b32_e32 v189, 0xffff0000, v84
	v_lshlrev_b32_e32 v190, 16, v85
	v_and_b32_e32 v191, 0xffff0000, v85
	v_pk_mul_f32 v[144:145], v[130:131], v[30:31]
	v_pk_mul_f32 v[146:147], v[132:133], v[32:33]
	v_pk_fma_f32 v[134:135], v[144:145], v[144:145], v[134:135]
	v_pk_fma_f32 v[134:135], v[146:147], v[146:147], v[134:135]
	v_pk_fma_f32 v[180:181], v[188:189], v[38:39], v[46:47]
	v_pk_fma_f32 v[182:183], v[190:191], v[40:41], v[48:49]
	v_pk_mul_f32 v[180:181], v[130:131], v[180:181]
	v_pk_mul_f32 v[182:183], v[132:133], v[182:183]
	ds_write_b128 v207, v[180:183] offset:768
	v_pk_mul_f32 v[130:131], v[180:181], v[184:185]
	v_pk_mul_f32 v[132:133], v[182:183], v[186:187]
	v_pk_add_f32 v[192:193], v[192:193], v[130:131]
	v_pk_add_f32 v[192:193], v[192:193], v[132:133]
	v_pk_fma_f32 v[194:195], v[130:131], v[54:55], v[194:195]
	v_pk_fma_f32 v[194:195], v[132:133], v[56:57], v[194:195]
	v_pk_mul_f32 v[160:161], v[144:145], v[188:189]
	v_pk_mul_f32 v[162:163], v[146:147], v[190:191]
	v_pk_fma_f32 v[148:149], v[160:161], v[184:185], v[148:149]
	v_pk_fma_f32 v[148:149], v[162:163], v[186:187], v[148:149]
	v_pk_mul_f32 v[176:177], v[90:91], v[184:185]
	v_pk_mul_f32 v[178:179], v[92:93], v[186:187]
	ds_write_b128 v207, v[90:93] offset:512
	v_add_f32_e32 v134, v134, v135
	v_add_f32_e32 v148, v148, v149
	v_add_f32_e32 v202, v192, v193
	v_add_f32_e32 v194, v194, v195
	v_add_f32_dpp v134, v134, v134 quad_perm:[1,0,3,2] row_mask:0xf bank_mask:0xf bound_ctrl:1
	v_add_f32_dpp v148, v148, v148 quad_perm:[1,0,3,2] row_mask:0xf bank_mask:0xf bound_ctrl:1
	v_add_f32_dpp v202, v202, v202 quad_perm:[1,0,3,2] row_mask:0xf bank_mask:0xf bound_ctrl:1
	v_add_f32_dpp v194, v194, v194 quad_perm:[1,0,3,2] row_mask:0xf bank_mask:0xf bound_ctrl:1
	v_add_f32_dpp v134, v134, v134 quad_perm:[2,3,0,1] row_mask:0xf bank_mask:0xf bound_ctrl:1
	v_add_f32_dpp v148, v148, v148 quad_perm:[2,3,0,1] row_mask:0xf bank_mask:0xf bound_ctrl:1
	v_add_f32_dpp v202, v202, v202 quad_perm:[2,3,0,1] row_mask:0xf bank_mask:0xf bound_ctrl:1
	v_add_f32_dpp v194, v194, v194 quad_perm:[2,3,0,1] row_mask:0xf bank_mask:0xf bound_ctrl:1
	v_add_f32_dpp v134, v134, v134 row_half_mirror row_mask:0xf bank_mask:0xf bound_ctrl:1
	v_add_f32_dpp v148, v148, v148 row_half_mirror row_mask:0xf bank_mask:0xf bound_ctrl:1
	v_add_f32_dpp v202, v202, v202 row_half_mirror row_mask:0xf bank_mask:0xf bound_ctrl:1
	v_add_f32_dpp v194, v194, v194 row_half_mirror row_mask:0xf bank_mask:0xf bound_ctrl:1
	v_max_f32_e32 v134, 0x179abe15, v134
	v_rsq_f32_e32 v198, v134
	s_nop 1
	v_mul_f32_e32 v200, v198, v148
	v_pk_mul_f32 v[180:181], v[140:141], v[198:199] op_sel_hi:[1,0] neg_lo:[0,1] neg_hi:[0,1]
	v_pk_mul_f32 v[182:183], v[142:143], v[198:199] op_sel_hi:[1,0] neg_lo:[0,1] neg_hi:[0,1]
	v_pk_mul_f32 v[184:185], v[144:145], v[198:199] op_sel_hi:[1,0] neg_lo:[0,1] neg_hi:[0,1]
	v_pk_mul_f32 v[186:187], v[146:147], v[198:199] op_sel_hi:[1,0] neg_lo:[0,1] neg_hi:[0,1]
	ds_write_b128 v206, v[180:183] offset:0
	ds_write_b128 v207, v[184:187] offset:0
	v_pk_fma_f32 v[172:173], v[180:181], v[200:201], v[172:173] op_sel_hi:[1,0,1]
	v_pk_fma_f32 v[174:175], v[182:183], v[200:201], v[174:175] op_sel_hi:[1,0,1]
	v_pk_fma_f32 v[176:177], v[184:185], v[200:201], v[176:177] op_sel_hi:[1,0,1]
	v_pk_fma_f32 v[178:179], v[186:187], v[200:201], v[178:179] op_sel_hi:[1,0,1]
	ds_write_b128 v206, v[172:175] offset:256
	ds_write_b128 v207, v[176:179] offset:256
	v_pk_mul_f32 v[156:157], v[156:157], v[198:199] op_sel_hi:[1,0]
	v_pk_mul_f32 v[158:159], v[158:159], v[198:199] op_sel_hi:[1,0]
	v_pk_mul_f32 v[160:161], v[160:161], v[198:199] op_sel_hi:[1,0]
	v_pk_mul_f32 v[162:163], v[162:163], v[198:199] op_sel_hi:[1,0]
	ds_write_b128 v206, v[156:159] offset:1024
	ds_write_b128 v207, v[160:163] offset:1024
	v_pk_mul_f32 v[164:165], v[164:165], v[202:203] op_sel_hi:[1,0]
	v_pk_mul_f32 v[166:167], v[166:167], v[202:203] op_sel_hi:[1,0]
	v_pk_mul_f32 v[168:169], v[168:169], v[202:203] op_sel_hi:[1,0]
	v_pk_mul_f32 v[170:171], v[170:171], v[202:203] op_sel_hi:[1,0]
	ds_write_b128 v206, v[164:167] offset:1536
	ds_write_b128 v207, v[168:171] offset:1536
	s_mov_b64 exec, s[52:53]
	global_store_dword v205, v194, s[64:65]
	s_mov_b64 exec, -1
	s_add_u32 s64, s64, 0x800
	s_addc_u32 s65, s65, 0
	global_load_dwordx4 v[58:61], v0, s[56:57]
	global_load_dwordx4 v[62:65], v0, s[56:57] offset:2048
	global_load_dwordx4 v[66:69], v0, s[58:59]
	global_load_dwordx4 v[70:73], v155, s[56:57]
	global_load_dwordx4 v[74:77], v155, s[56:57] offset:2048
	global_load_dwordx4 v[78:81], v155, s[58:59]
	global_load_dwordx4 v[82:85], v197, s[60:61]
	global_load_dwordx4 v[86:89], v204, s[62:63]
	global_load_dwordx4 v[90:93], v204, s[62:63] offset:16
	s_add_u32 s56, s56, 0x48000
	s_addc_u32 s57, s57, 0
	s_add_u32 s58, s58, 0x48000
	s_addc_u32 s59, s59, 0
	s_add_u32 s60, s60, 0x10000
	s_addc_u32 s61, s61, 0
	s_add_u32 s62, s62, 0x20000
	s_addc_u32 s63, s63, 0
	s_waitcnt lgkmcnt(0)
	s_barrier
	s_add_i32 s14, s14, 1
	s_cmp_lt_u32 s14, 63
	s_cbranch_scc1 .Lp4a_loopb
	s_waitcnt vmcnt(10)
	v_mov_b32_e32 v134, 0
	v_mov_b32_e32 v135, 0
	v_mov_b32_e32 v148, 0
	v_mov_b32_e32 v149, 0
	v_mov_b32_e32 v192, 0
	v_mov_b32_e32 v193, 0
	v_mov_b32_e32 v194, 0
	v_mov_b32_e32 v195, 0
	v_lshlrev_b32_e32 v180, 16, v94
	v_and_b32_e32 v181, 0xffff0000, v94
	v_lshlrev_b32_e32 v182, 16, v95
	v_and_b32_e32 v183, 0xffff0000, v95
	v_lshlrev_b32_e32 v184, 16, v106
	v_and_b32_e32 v185, 0xffff0000, v106
	v_lshlrev_b32_e32 v186, 16, v107
	v_and_b32_e32 v187, 0xffff0000, v107
	v_pk_add_f32 v[184:185], v[184:185], v[180:181] neg_lo:[0,1] neg_hi:[0,1]
	v_pk_add_f32 v[186:187], v[186:187], v[182:183] neg_lo:[0,1] neg_hi:[0,1]
	v_pk_fma_f32 v[184:185], v[184:185], v[2:3], v[180:181]
	v_pk_fma_f32 v[186:187], v[186:187], v[4:5], v[182:183]
	v_lshlrev_b32_e32 v180, 16, v98
	v_and_b32_e32 v181, 0xffff0000, v98
	v_lshlrev_b32_e32 v182, 16, v99
	v_and_b32_e32 v183, 0xffff0000, v99
	v_lshlrev_b32_e32 v130, 16, v110
	v_and_b32_e32 v131, 0xffff0000, v110
	v_lshlrev_b32_e32 v132, 16, v111
	v_and_b32_e32 v133, 0xffff0000, v111
	v_pk_add_f32 v[130:131], v[130:131], v[180:181] neg_lo:[0,1] neg_hi:[0,1]
	v_pk_add_f32 v[132:133], v[132:133], v[182:183] neg_lo:[0,1] neg_hi:[0,1]
	v_pk_fma_f32 v[130:131], v[130:131], v[10:11], v[180:181]
	v_pk_fma_f32 v[132:133], v[132:133], v[12:13], v[182:183]
	v_lshlrev_b32_e32 v180, 16, v102
	v_and_b32_e32 v181, 0xffff0000, v102
	v_lshlrev_b32_e32 v182, 16, v103
	v_and_b32_e32 v183, 0xffff0000, v103
	v_lshlrev_b32_e32 v164, 16, v114
	v_and_b32_e32 v165, 0xffff0000, v114
	v_lshlrev_b32_e32 v166, 16, v115
	v_and_b32_e32 v167, 0xffff0000, v115
	v_pk_add_f32 v[164:165], v[164:165], v[180:181] neg_lo:[0,1] neg_hi:[0,1]
	v_pk_add_f32 v[166:167], v[166:167], v[182:183] neg_lo:[0,1] neg_hi:[0,1]
	v_pk_fma_f32 v[164:165], v[164:165], v[18:19], v[180:181]
	v_pk_fma_f32 v[166:167], v[166:167], v[20:21], v[182:183]
	ds_write_b128 v208, v[164:167] offset:1280
	v_lshlrev_b32_e32 v188, 16, v118
	v_and_b32_e32 v189, 0xffff0000, v118
	v_lshlrev_b32_e32 v190, 16, v119
	v_and_b32_e32 v191, 0xffff0000, v119
	v_pk_mul_f32 v[140:141], v[130:131], v[26:27]
	v_pk_mul_f32 v[142:143], v[132:133], v[28:29]
	v_pk_fma_f32 v[134:135], v[140:141], v[140:141], v[134:135]
	v_pk_fma_f32 v[134:135], v[142:143], v[142:143], v[134:135]
	v_pk_fma_f32 v[180:181], v[188:189], v[34:35], v[42:43]
	v_pk_fma_f32 v[182:183], v[190:191], v[36:37], v[44:45]
	v_pk_mul_f32 v[180:181], v[130:131], v[180:181]
	v_pk_mul_f32 v[182:183], v[132:133], v[182:183]
	ds_write_b128 v208, v[180:183] offset:768
	v_pk_mul_f32 v[130:131], v[180:181], v[184:185]
	v_pk_mul_f32 v[132:133], v[182:183], v[186:187]
	v_pk_add_f32 v[192:193], v[192:193], v[130:131]
	v_pk_add_f32 v[192:193], v[192:193], v[132:133]
	v_pk_fma_f32 v[194:195], v[130:131], v[50:51], v[194:195]
	v_pk_fma_f32 v[194:195], v[132:133], v[52:53], v[194:195]
	v_pk_mul_f32 v[156:157], v[140:141], v[188:189]
	v_pk_mul_f32 v[158:159], v[142:143], v[190:191]
	v_pk_fma_f32 v[148:149], v[156:157], v[184:185], v[148:149]
	v_pk_fma_f32 v[148:149], v[158:159], v[186:187], v[148:149]
	v_pk_mul_f32 v[172:173], v[122:123], v[184:185]
	v_pk_mul_f32 v[174:175], v[124:125], v[186:187]
	ds_write_b128 v208, v[122:125] offset:512
	v_lshlrev_b32_e32 v180, 16, v96
	v_and_b32_e32 v181, 0xffff0000, v96
	v_lshlrev_b32_e32 v182, 16, v97
	v_and_b32_e32 v183, 0xffff0000, v97
	v_lshlrev_b32_e32 v184, 16, v108
	v_and_b32_e32 v185, 0xffff0000, v108
	v_lshlrev_b32_e32 v186, 16, v109
	v_and_b32_e32 v187, 0xffff0000, v109
	v_pk_add_f32 v[184:185], v[184:185], v[180:181] neg_lo:[0,1] neg_hi:[0,1]
	v_pk_add_f32 v[186:187], v[186:187], v[182:183] neg_lo:[0,1] neg_hi:[0,1]
	v_pk_fma_f32 v[184:185], v[184:185], v[6:7], v[180:181]
	v_pk_fma_f32 v[186:187], v[186:187], v[8:9], v[182:183]
	v_lshlrev_b32_e32 v180, 16, v100
	v_and_b32_e32 v181, 0xffff0000, v100
	v_lshlrev_b32_e32 v182, 16, v101
	v_and_b32_e32 v183, 0xffff0000, v101
	v_lshlrev_b32_e32 v130, 16, v112
	v_and_b32_e32 v131, 0xffff0000, v112
	v_lshlrev_b32_e32 v132, 16, v113
	v_and_b32_e32 v133, 0xffff0000, v113
	v_pk_add_f32 v[130:131], v[130:131], v[180:181] neg_lo:[0,1] neg_hi:[0,1]
	v_pk_add_f32 v[132:133], v[132:133], v[182:183] neg_lo:[0,1] neg_hi:[0,1]
	v_pk_fma_f32 v[130:131], v[130:131], v[14:15], v[180:181]
	v_pk_fma_f32 v[132:133], v[132:133], v[16:17], v[182:183]
	v_lshlrev_b32_e32 v180, 16, v104
	v_and_b32_e32 v181, 0xffff0000, v104
	v_lshlrev_b32_e32 v182, 16, v105
	v_and_b32_e32 v183, 0xffff0000, v105
	v_lshlrev_b32_e32 v168, 16, v116
	v_and_b32_e32 v169, 0xffff0000, v116
	v_lshlrev_b32_e32 v170, 16, v117
	v_and_b32_e32 v171, 0xffff0000, v117
	v_pk_add_f32 v[168:169], v[168:169], v[180:181] neg_lo:[0,1] neg_hi:[0,1]
	v_pk_add_f32 v[170:171], v[170:171], v[182:183] neg_lo:[0,1] neg_hi:[0,1]
	v_pk_fma_f32 v[168:169], v[168:169], v[22:23], v[180:181]
	v_pk_fma_f32 v[170:171], v[170:171], v[24:25], v[182:183]
	ds_write_b128 v209, v[168:171] offset:1280
	v_lshlrev_b32_e32 v188, 16, v120
	v_and_b32_e32 v189, 0xffff0000, v120
; #define WG_BAR() do { asm volatile("s_waitcnt lgkmcnt(0)" ::: "memory"); __builtin_amdgcn_s_barrier(); asm volatile("" ::: "memory"); } while (0)
; #define SCAN_ITER(D_, SET) do { const int blk = blk0 + (D_); if (blk + 1 < TT / TB) { SCAN_PRODUCE(blk + 1, SET); if (blk + 1 + PD < TT / TB) SCAN_LOAD(blk + 1 + PD, SET); } WG_BAR(); } while (0)
; __global__ void __launch_bounds__(NTHR) hymba_fwd(Params P) {
;     ...
;               SCAN_LOAD(0, 0); SCAN_LOAD(1, 1);
;               SCAN_PRODUCE(0, 0); SCAN_LOAD(2, 0);
;               WG_BAR();
;               static_assert((TT / TB) % PD == 0 && PD == 2, "block loop is unrolled by PD = 2");
;               for (int blk0 = 0; blk0 < TT / TB; blk0 += PD) {
;     ...
;                 SCAN_ITER(0, 1); SCAN_ITER(1, 0);
	v_lshlrev_b32_e32 v190, 16, v121
	v_and_b32_e32 v191, 0xffff0000, v121
	v_pk_mul_f32 v[144:145], v[130:131], v[30:31]
	v_pk_mul_f32 v[146:147], v[132:133], v[32:33]
	v_pk_fma_f32 v[134:135], v[144:145], v[144:145], v[134:135]
	v_pk_fma_f32 v[134:135], v[146:147], v[146:147], v[134:135]
	v_pk_fma_f32 v[180:181], v[188:189], v[38:39], v[46:47]
	v_pk_fma_f32 v[182:183], v[190:191], v[40:41], v[48:49]
	v_pk_mul_f32 v[180:181], v[130:131], v[180:181]
	v_pk_mul_f32 v[182:183], v[132:133], v[182:183]
	ds_write_b128 v209, v[180:183] offset:768
	v_pk_mul_f32 v[130:131], v[180:181], v[184:185]
	v_pk_mul_f32 v[132:133], v[182:183], v[186:187]
	v_pk_add_f32 v[192:193], v[192:193], v[130:131]
	v_pk_add_f32 v[192:193], v[192:193], v[132:133]
	v_pk_fma_f32 v[194:195], v[130:131], v[54:55], v[194:195]
	v_pk_fma_f32 v[194:195], v[132:133], v[56:57], v[194:195]
	v_pk_mul_f32 v[160:161], v[144:145], v[188:189]
	v_pk_mul_f32 v[162:163], v[146:147], v[190:191]
	v_pk_fma_f32 v[148:149], v[160:161], v[184:185], v[148:149]
	v_pk_fma_f32 v[148:149], v[162:163], v[186:187], v[148:149]
	v_pk_mul_f32 v[176:177], v[126:127], v[184:185]
	v_pk_mul_f32 v[178:179], v[128:129], v[186:187]
	ds_write_b128 v209, v[126:129] offset:512
	v_add_f32_e32 v134, v134, v135
	v_add_f32_e32 v148, v148, v149
	v_add_f32_e32 v202, v192, v193
	v_add_f32_e32 v194, v194, v195
	v_add_f32_dpp v134, v134, v134 quad_perm:[1,0,3,2] row_mask:0xf bank_mask:0xf bound_ctrl:1
	v_add_f32_dpp v148, v148, v148 quad_perm:[1,0,3,2] row_mask:0xf bank_mask:0xf bound_ctrl:1
	v_add_f32_dpp v202, v202, v202 quad_perm:[1,0,3,2] row_mask:0xf bank_mask:0xf bound_ctrl:1
	v_add_f32_dpp v194, v194, v194 quad_perm:[1,0,3,2] row_mask:0xf bank_mask:0xf bound_ctrl:1
	v_add_f32_dpp v134, v134, v134 quad_perm:[2,3,0,1] row_mask:0xf bank_mask:0xf bound_ctrl:1
	v_add_f32_dpp v148, v148, v148 quad_perm:[2,3,0,1] row_mask:0xf bank_mask:0xf bound_ctrl:1
	v_add_f32_dpp v202, v202, v202 quad_perm:[2,3,0,1] row_mask:0xf bank_mask:0xf bound_ctrl:1
	v_add_f32_dpp v194, v194, v194 quad_perm:[2,3,0,1] row_mask:0xf bank_mask:0xf bound_ctrl:1
	v_add_f32_dpp v134, v134, v134 row_half_mirror row_mask:0xf bank_mask:0xf bound_ctrl:1
	v_add_f32_dpp v148, v148, v148 row_half_mirror row_mask:0xf bank_mask:0xf bound_ctrl:1
	v_add_f32_dpp v202, v202, v202 row_half_mirror row_mask:0xf bank_mask:0xf bound_ctrl:1
	v_add_f32_dpp v194, v194, v194 row_half_mirror row_mask:0xf bank_mask:0xf bound_ctrl:1
	v_max_f32_e32 v134, 0x179abe15, v134
	v_rsq_f32_e32 v198, v134
	s_nop 1
	v_mul_f32_e32 v200, v198, v148
	v_pk_mul_f32 v[180:181], v[140:141], v[198:199] op_sel_hi:[1,0] neg_lo:[0,1] neg_hi:[0,1]
	v_pk_mul_f32 v[182:183], v[142:143], v[198:199] op_sel_hi:[1,0] neg_lo:[0,1] neg_hi:[0,1]
	v_pk_mul_f32 v[184:185], v[144:145], v[198:199] op_sel_hi:[1,0] neg_lo:[0,1] neg_hi:[0,1]
	v_pk_mul_f32 v[186:187], v[146:147], v[198:199] op_sel_hi:[1,0] neg_lo:[0,1] neg_hi:[0,1]
	ds_write_b128 v208, v[180:183] offset:0
	ds_write_b128 v209, v[184:187] offset:0
	v_pk_fma_f32 v[172:173], v[180:181], v[200:201], v[172:173] op_sel_hi:[1,0,1]
	v_pk_fma_f32 v[174:175], v[182:183], v[200:201], v[174:175] op_sel_hi:[1,0,1]
	v_pk_fma_f32 v[176:177], v[184:185], v[200:201], v[176:177] op_sel_hi:[1,0,1]
	v_pk_fma_f32 v[178:179], v[186:187], v[200:201], v[178:179] op_sel_hi:[1,0,1]
	ds_write_b128 v208, v[172:175] offset:256
	ds_write_b128 v209, v[176:179] offset:256
	v_pk_mul_f32 v[156:157], v[156:157], v[198:199] op_sel_hi:[1,0]
	v_pk_mul_f32 v[158:159], v[158:159], v[198:199] op_sel_hi:[1,0]
	v_pk_mul_f32 v[160:161], v[160:161], v[198:199] op_sel_hi:[1,0]
	v_pk_mul_f32 v[162:163], v[162:163], v[198:199] op_sel_hi:[1,0]
	ds_write_b128 v208, v[156:159] offset:1024
	ds_write_b128 v209, v[160:163] offset:1024
	v_pk_mul_f32 v[164:165], v[164:165], v[202:203] op_sel_hi:[1,0]
	v_pk_mul_f32 v[166:167], v[166:167], v[202:203] op_sel_hi:[1,0]
	v_pk_mul_f32 v[168:169], v[168:169], v[202:203] op_sel_hi:[1,0]
	v_pk_mul_f32 v[170:171], v[170:171], v[202:203] op_sel_hi:[1,0]
	ds_write_b128 v208, v[164:167] offset:1536
	ds_write_b128 v209, v[168:171] offset:1536
	s_mov_b64 exec, s[52:53]
	global_store_dword v205, v194, s[64:65]
	s_mov_b64 exec, -1
	s_add_u32 s64, s64, 0x800
	s_addc_u32 s65, s65, 0
	global_load_dwordx4 v[94:97], v0, s[56:57]
	global_load_dwordx4 v[98:101], v0, s[56:57] offset:2048
	global_load_dwordx4 v[102:105], v0, s[58:59]
	global_load_dwordx4 v[106:109], v155, s[56:57]
	global_load_dwordx4 v[110:113], v155, s[56:57] offset:2048
	global_load_dwordx4 v[114:117], v155, s[58:59]
	global_load_dwordx4 v[118:121], v197, s[60:61]
	global_load_dwordx4 v[122:125], v204, s[62:63]
	global_load_dwordx4 v[126:129], v204, s[62:63] offset:16
	s_add_u32 s56, s56, 0x48000
	s_addc_u32 s57, s57, 0
	s_add_u32 s58, s58, 0x48000
	s_addc_u32 s59, s59, 0
	s_add_u32 s60, s60, 0x10000
	s_addc_u32 s61, s61, 0
	s_add_u32 s62, s62, 0x20000
	s_addc_u32 s63, s63, 0
	s_waitcnt lgkmcnt(0)
	s_barrier
	s_add_i32 s14, s14, 1
	s_waitcnt lgkmcnt(0)
	s_barrier

; __global__ void __launch_bounds__(NTHR) hymba_fwd(Params P) {
;     ...
;               const int crow = wv * 8 + (lane >> 3), kq = lane & 7; const bool first8 = kq == 0;
;               f32x2 S2[4];
; #pragma unroll
;               for (int e = 0; e < 4; ++e) S2[e] = (f32x2){0.f, 0.f};
;               const LAS float* recq0 = ldf + kq * 8; const LAS float* recv0 = ldf + 320 + q * 16 + crow;
;               float* yp = Yb + (size_t)(b * TT + 7 - kq) * CW + h * 64 + q * 16 + crow;
;               __builtin_amdgcn_s_setprio(3);
;               WG_BAR();
;               for (int blk = 0; blk < TT / TB; ++blk) {
;                     const int bo = (blk & 1) * (TB * REC);
;                     const LAS float* recq = recq0 + bo; const LAS float* recv = recv0 + bo; const LAS float* recs = ldf + bo + 384;
;     ...
;                     f32x4 av0, av1, bv0, bv1, dw0, dw1, kt0, kt1, wr0, wr1; float vv; f32x2 sc;
;                     f32x4 nav0, nav1, nbv0, nbv1, ndw0, ndw1, nkt0, nkt1, nwr0, nwr1; float nvv; f32x2 nsc;
;                     f32x4 a0, a1, b0, b1, d0, d1, k0, k1, w0_, w1_; float vv_; f32x2 sc_;
;                     LDSTEP(0, a0, a1, b0, b1, d0, d1, k0, k1, w0_, w1_, vv_, sc_);
;                     LDSTEP(REC, av0, av1, bv0, bv1, dw0, dw1, kt0, kt1, wr0, wr1, vv, sc);
;                     float yacc = 0.f;
; #pragma unroll
;                     for (int st = 0; st < TB; ++st) {
;                         if (st + 2 < TB) LDSTEP((st + 2) * REC, nav0, nav1, nbv0, nbv1, ndw0, ndw1, nkt0, nkt1, nwr0, nwr1, nvv, nsc);
;                         __builtin_amdgcn_sched_barrier(0);
;                         const f32x2 pa = pkfma_(S2[3], hi2(a1), pkfma_(S2[2], lo2(a1), pkfma_(S2[1], hi2(a0), pkmul_(S2[0], lo2(a0)))));
;                         const f32x2 py = pkfma_(S2[3], hi2(w1_), pkfma_(S2[2], lo2(w1_), pkfma_(S2[1], hi2(w0_), pkmul_(S2[0], lo2(w0_)))));
;                         float da = pa[0] + pa[1], dy = py[0] + py[1];
;                         da = red8(da); dy = red8(dy);
;                         const float y = dy + da * sc_[0] + vv_ * sc_[1];
;                         { f32x2 dab, vvb; dab[0] = da; dab[1] = da; vvb[0] = vv_; vvb[1] = vv_;
;                           S2[0] = pkfma_b(lo2(k0), vvb, pkfma_b(lo2(b0), dab, pkmul_(S2[0], lo2(d0)))); S2[1] = pkfma_b(hi2(k0), vvb, pkfma_b(hi2(b0), dab, pkmul_(S2[1], hi2(d0))));
.LBB0_851:
	s_andn2_b64 vcc, exec, s[4:5]
	s_cbranch_vccnz .LBB0_672
	v_and_b32_e32 v67, 15, v136
	v_lshrrev_b32_e32 v68, 4, v136
	s_lshl_b32 s4, s95, 2
	s_lshl_b32 s5, s93, 4
	s_add_i32 s4, s4, s5
	v_add_u32_e32 v69, s4, v68
	v_lshrrev_b32_e32 v0, 3, v67
	v_xor_b32_e32 v0, v0, v67
	v_lshlrev_b32_e32 v0, 4, v0
	v_lshrrev_b32_e32 v12, 2, v69
	v_lshrrev_b32_e32 v70, 3, v12
	v_xor_b32_e32 v12, v12, v70
	v_and_b32_e32 v70, 3, v69
	v_lshlrev_b32_e32 v70, 2, v70
	v_lshl_add_u32 v12, v12, 4, v70
	v_mov_b32_e32 v13, v12
	v_add_u32_e32 v12, 0x500, v12
	v_lshrrev_b32_e32 v71, 3, v67
	v_mul_u32_u24_e32 v70, 7, v71
	v_xor_b32_e32 v70, v70, v67
	v_lshlrev_b32_e32 v71, 3, v71
	v_bfe_u32 v14, v70, 1, 1
	v_lshl_or_b32 v71, v14, 2, v71
	v_and_b32_e32 v14, 1, v70
	v_lshl_or_b32 v71, v14, 1, v71
	v_bfe_u32 v14, v70, 2, 1
	v_or_b32_e32 v71, v14, v71
	v_mul_u32_u24_e32 v70, 0x700, v71
	v_add_u32_e32 v13, v13, v70
	v_add_u32_e32 v13, 0x600, v13
	s_lshl_b32 s5, s92, 8
	v_lshlrev_b32_e32 v14, 12, v71
	v_lshl_add_u32 v14, v69, 2, v14
	v_add_u32_e32 v14, s5, v14
	s_lshl_b32 s4, s35, 23
	s_add_u32 s8, s88, s4
	s_addc_u32 s9, s89, 0
	v_lshlrev_b32_e32 v15, 8, v69
	v_lshl_add_u32 v15, v67, 4, v15
	s_lshl_b32 s4, s35, 4
	s_add_i32 s4, s4, s92
	s_lshl_b32 s4, s4, 14
	s_add_u32 s58, s88, s4
	s_addc_u32 s59, s89, 0
	s_add_u32 s58, s58, 0x4149200
	s_addc_u32 s59, s59, 0
	v_mov_b32_e32 v2, 0
	v_mov_b32_e32 v3, 0
	v_mov_b32_e32 v4, 0
	v_mov_b32_e32 v5, 0
	s_mov_b32 s10, 0xff00ff0
	s_mov_b32 s11, 0xff00ff0
	s_mov_b32 s22, 0x55aa55aa
	s_mov_b32 s23, 0x55aa55aa
	s_mov_b32 s26, 0x33cc33cc
	s_mov_b32 s27, 0x33cc33cc
	s_mov_b32 s56, 0xff00ff00
	s_mov_b32 s57, 0xff00ff00
	s_mov_b32 s15, 0xe000
	s_movk_i32 s14, 64
	s_setprio 3
	s_waitcnt lgkmcnt(0)
	s_barrier
.Lp4c_blk:
	ds_read_b128 v[72:75], v0 offset:0
	ds_read_b128 v[76:79], v0 offset:256
	ds_read_b128 v[80:83], v0 offset:512
	ds_read_b128 v[84:87], v0 offset:768
	ds_read_b32 v92, v12 offset:0
	ds_read_b128 v[88:91], v0 offset:1024
	ds_read_b128 v[94:97], v0 offset:1792
	ds_read_b128 v[98:101], v0 offset:2048
	ds_read_b128 v[102:105], v0 offset:2304
	ds_read_b128 v[106:109], v0 offset:2560
	ds_read_b32 v114, v12 offset:1792
	ds_read_b128 v[110:113], v0 offset:2816
	s_waitcnt lgkmcnt(6)
	ds_read_b128 v[116:119], v0 offset:3584
	ds_read_b128 v[120:123], v0 offset:3840
	ds_read_b128 v[124:127], v0 offset:4096
	ds_read_b128 v[128:131], v0 offset:4352
	ds_read_b32 v140, v12 offset:3584
	ds_read_b128 v[132:135], v0 offset:4608
	ds_read_b32 v65, v13 offset:0
	v_pk_mul_f32 v[6:7], v[2:3], v[72:73]
	v_pk_mul_f32 v[8:9], v[2:3], v[76:77]
	v_pk_fma_f32 v[6:7], v[4:5], v[74:75], v[6:7]
	v_pk_fma_f32 v[8:9], v[4:5], v[78:79], v[8:9]
	v_add_f32_e32 v10, v6, v7
	v_add_f32_e32 v16, v8, v9
	v_pk_mul_f32 v[2:3], v[2:3], v[80:81]
	v_add_f32_dpp v10, v10, v10 quad_perm:[1,0,3,2] row_mask:0xf bank_mask:0xf bound_ctrl:1
	v_pk_mul_f32 v[4:5], v[4:5], v[82:83]
	v_pk_fma_f32 v[2:3], v[84:85], v[92:93], v[2:3] op_sel_hi:[1,0,1]
	v_add_f32_dpp v10, v10, v10 quad_perm:[2,3,0,1] row_mask:0xf bank_mask:0xf bound_ctrl:1
	v_pk_fma_f32 v[4:5], v[86:87], v[92:93], v[4:5] op_sel_hi:[1,0,1]
	v_add_f32_dpp v62, v32, v32 row_half_mirror row_mask:0xf bank_mask:0xf bound_ctrl:1
	v_add_f32_dpp v10, v10, v10 row_half_mirror row_mask:0xf bank_mask:0xf bound_ctrl:1
	v_add_f32_dpp v63, v33, v33 row_half_mirror row_mask:0xf bank_mask:0xf bound_ctrl:1
	v_cndmask_b32_e64 v48, v62, v63, s[10:11]
	v_add_f32_dpp v10, v10, v10 row_mirror row_mask:0xf bank_mask:0xf bound_ctrl:1
	v_pk_fma_f32 v[2:3], v[88:89], v[10:11], v[2:3] op_sel_hi:[1,0,1]
	v_pk_fma_f32 v[4:5], v[90:91], v[10:11], v[4:5] op_sel_hi:[1,0,1]
	s_waitcnt lgkmcnt(7)
	ds_read_b128 v[72:75], v0 offset:5376
	ds_read_b128 v[76:79], v0 offset:5632
	ds_read_b128 v[80:83], v0 offset:5888
	ds_read_b128 v[84:87], v0 offset:6144
	ds_read_b32 v92, v12 offset:5376
	ds_read_b128 v[88:91], v0 offset:6400
	v_pk_mul_f32 v[6:7], v[2:3], v[94:95]
	v_pk_mul_f32 v[8:9], v[2:3], v[98:99]
	v_pk_fma_f32 v[6:7], v[4:5], v[96:97], v[6:7]
	v_pk_fma_f32 v[8:9], v[4:5], v[100:101], v[8:9]
	v_add_f32_e32 v10, v6, v7
	v_add_f32_e32 v17, v8, v9
	v_pk_mul_f32 v[2:3], v[2:3], v[102:103]
	v_add_f32_dpp v10, v10, v10 quad_perm:[1,0,3,2] row_mask:0xf bank_mask:0xf bound_ctrl:1
	v_pk_mul_f32 v[4:5], v[4:5], v[104:105]
	v_pk_fma_f32 v[2:3], v[106:107], v[114:115], v[2:3] op_sel_hi:[1,0,1]
	v_add_f32_dpp v10, v10, v10 quad_perm:[2,3,0,1] row_mask:0xf bank_mask:0xf bound_ctrl:1
	v_pk_fma_f32 v[4:5], v[108:109], v[114:115], v[4:5] op_sel_hi:[1,0,1]
	v_add_f32_dpp v62, v34, v34 row_half_mirror row_mask:0xf bank_mask:0xf bound_ctrl:1
	v_add_f32_dpp v10, v10, v10 row_half_mirror row_mask:0xf bank_mask:0xf bound_ctrl:1
	v_add_f32_dpp v63, v35, v35 row_half_mirror row_mask:0xf bank_mask:0xf bound_ctrl:1
	v_cndmask_b32_e64 v49, v62, v63, s[10:11]
	v_add_f32_dpp v10, v10, v10 row_mirror row_mask:0xf bank_mask:0xf bound_ctrl:1
	v_pk_fma_f32 v[2:3], v[110:111], v[10:11], v[2:3] op_sel_hi:[1,0,1]
	v_pk_fma_f32 v[4:5], v[112:113], v[10:11], v[4:5] op_sel_hi:[1,0,1]
	s_waitcnt lgkmcnt(7)
; __device__ __forceinline__ f32x2 pkmul_(f32x2 a, f32x2 b) { f32x2 d; asm("v_pk_mul_f32 %0, %1, %2" : "=v"(d) : "v"(a), "v"(b)); return d; }
; __device__ __forceinline__ f32x2 pkfma_(f32x2 a, f32x2 b, f32x2 c) { f32x2 d; asm("v_pk_fma_f32 %0, %1, %2, %3" : "=v"(d) : "v"(a), "v"(b), "v"(c)); return d; }
; __device__ __forceinline__ f32x2 pkfma_b(f32x2 a, f32x2 s, f32x2 c) { f32x2 d; asm("v_pk_fma_f32 %0, %1, %2, %3 op_sel_hi:[1,0,1]" : "=v"(d) : "v"(a), "v"(s), "v"(c)); return d; }
; __device__ __forceinline__ f32x2 lo2(f32x4 v) { return __builtin_shufflevector(v, v, 0, 1); }
; __device__ __forceinline__ f32x2 hi2(f32x4 v) { return __builtin_shufflevector(v, v, 2, 3); }
; __device__ __forceinline__ float red8(float x) { x += dpp_<0x141>(x); x += dpp_<0xB1>(x); x += dpp_<0x4E>(x); return x; }
; __global__ void __launch_bounds__(NTHR) hymba_fwd(Params P) {
;     ...
;                     for (int st = 0; st < TB; ++st) {
;                         if (st + 2 < TB) LDSTEP((st + 2) * REC, nav0, nav1, nbv0, nbv1, ndw0, ndw1, nkt0, nkt1, nwr0, nwr1, nvv, nsc);
;                         __builtin_amdgcn_sched_barrier(0);
;                         const f32x2 pa = pkfma_(S2[3], hi2(a1), pkfma_(S2[2], lo2(a1), pkfma_(S2[1], hi2(a0), pkmul_(S2[0], lo2(a0)))));
;                         const f32x2 py = pkfma_(S2[3], hi2(w1_), pkfma_(S2[2], lo2(w1_), pkfma_(S2[1], hi2(w0_), pkmul_(S2[0], lo2(w0_)))));
;                         float da = pa[0] + pa[1], dy = py[0] + py[1];
;                         da = red8(da); dy = red8(dy);
;                         const float y = dy + da * sc_[0] + vv_ * sc_[1];
;                         { f32x2 dab, vvb; dab[0] = da; dab[1] = da; vvb[0] = vv_; vvb[1] = vv_;
;                           S2[0] = pkfma_b(lo2(k0), vvb, pkfma_b(lo2(b0), dab, pkmul_(S2[0], lo2(d0)))); S2[1] = pkfma_b(hi2(k0), vvb, pkfma_b(hi2(b0), dab, pkmul_(S2[1], hi2(d0))));
;                           S2[2] = pkfma_b(lo2(k1), vvb, pkfma_b(lo2(b1), dab, pkmul_(S2[2], lo2(d1)))); S2[3] = pkfma_b(hi2(k1), vvb, pkfma_b(hi2(b1), dab, pkmul_(S2[3], hi2(d1)))); }
;                         const float sh = __int_as_float(__builtin_amdgcn_update_dpp(__float_as_int(y), __float_as_int(yacc), 0x111, 0xF, 0xF, false));
;                         yacc = first8 ? y : sh;
;                         if ((st & 7) == 7) yp[(size_t)(blk * TB + (st - 7)) * CW] = yacc;
	ds_read_b128 v[94:97], v0 offset:7168
	ds_read_b128 v[98:101], v0 offset:7424
	ds_read_b128 v[102:105], v0 offset:7680
	ds_read_b128 v[106:109], v0 offset:7936
	ds_read_b32 v114, v12 offset:7168
	ds_read_b128 v[110:113], v0 offset:8192
	v_pk_mul_f32 v[6:7], v[2:3], v[116:117]
	v_pk_mul_f32 v[8:9], v[2:3], v[120:121]
	v_pk_fma_f32 v[6:7], v[4:5], v[118:119], v[6:7]
	v_pk_fma_f32 v[8:9], v[4:5], v[122:123], v[8:9]
	v_add_f32_e32 v10, v6, v7
	v_add_f32_e32 v18, v8, v9
	v_pk_mul_f32 v[2:3], v[2:3], v[124:125]
	v_add_f32_dpp v10, v10, v10 quad_perm:[1,0,3,2] row_mask:0xf bank_mask:0xf bound_ctrl:1
	v_pk_mul_f32 v[4:5], v[4:5], v[126:127]
	v_pk_fma_f32 v[2:3], v[128:129], v[140:141], v[2:3] op_sel_hi:[1,0,1]
	v_add_f32_dpp v10, v10, v10 quad_perm:[2,3,0,1] row_mask:0xf bank_mask:0xf bound_ctrl:1
	v_pk_fma_f32 v[4:5], v[130:131], v[140:141], v[4:5] op_sel_hi:[1,0,1]
	v_add_f32_dpp v62, v36, v36 row_half_mirror row_mask:0xf bank_mask:0xf bound_ctrl:1
	v_add_f32_dpp v10, v10, v10 row_half_mirror row_mask:0xf bank_mask:0xf bound_ctrl:1
	v_add_f32_dpp v63, v37, v37 row_half_mirror row_mask:0xf bank_mask:0xf bound_ctrl:1
	v_cndmask_b32_e64 v50, v62, v63, s[10:11]
	v_add_f32_dpp v10, v10, v10 row_mirror row_mask:0xf bank_mask:0xf bound_ctrl:1
	v_pk_fma_f32 v[2:3], v[132:133], v[10:11], v[2:3] op_sel_hi:[1,0,1]
	v_pk_fma_f32 v[4:5], v[134:135], v[10:11], v[4:5] op_sel_hi:[1,0,1]
	s_waitcnt lgkmcnt(6)
	ds_read_b128 v[116:119], v0 offset:8960
	ds_read_b128 v[120:123], v0 offset:9216
	ds_read_b128 v[124:127], v0 offset:9472
	ds_read_b128 v[128:131], v0 offset:9728
	ds_read_b32 v140, v12 offset:8960
	ds_read_b128 v[132:135], v0 offset:9984
	v_pk_mul_f32 v[6:7], v[2:3], v[72:73]
	v_pk_mul_f32 v[8:9], v[2:3], v[76:77]
	v_pk_fma_f32 v[6:7], v[4:5], v[74:75], v[6:7]
	v_pk_fma_f32 v[8:9], v[4:5], v[78:79], v[8:9]
	v_add_f32_e32 v10, v6, v7
	v_add_f32_e32 v19, v8, v9
	v_pk_mul_f32 v[2:3], v[2:3], v[80:81]
	v_add_f32_dpp v10, v10, v10 quad_perm:[1,0,3,2] row_mask:0xf bank_mask:0xf bound_ctrl:1
	v_pk_mul_f32 v[4:5], v[4:5], v[82:83]
	v_pk_fma_f32 v[2:3], v[84:85], v[92:93], v[2:3] op_sel_hi:[1,0,1]
	v_add_f32_dpp v10, v10, v10 quad_perm:[2,3,0,1] row_mask:0xf bank_mask:0xf bound_ctrl:1
	v_pk_fma_f32 v[4:5], v[86:87], v[92:93], v[4:5] op_sel_hi:[1,0,1]
	v_add_f32_dpp v62, v38, v38 row_half_mirror row_mask:0xf bank_mask:0xf bound_ctrl:1
	v_add_f32_dpp v10, v10, v10 row_half_mirror row_mask:0xf bank_mask:0xf bound_ctrl:1
	v_add_f32_dpp v63, v39, v39 row_half_mirror row_mask:0xf bank_mask:0xf bound_ctrl:1
	v_cndmask_b32_e64 v51, v62, v63, s[10:11]
	v_add_f32_dpp v10, v10, v10 row_mirror row_mask:0xf bank_mask:0xf bound_ctrl:1
	v_pk_fma_f32 v[2:3], v[88:89], v[10:11], v[2:3] op_sel_hi:[1,0,1]
	v_pk_fma_f32 v[4:5], v[90:91], v[10:11], v[4:5] op_sel_hi:[1,0,1]
	s_waitcnt lgkmcnt(6)
	ds_read_b128 v[72:75], v0 offset:10752
	ds_read_b128 v[76:79], v0 offset:11008
	ds_read_b128 v[80:83], v0 offset:11264
	ds_read_b128 v[84:87], v0 offset:11520
	ds_read_b32 v92, v12 offset:10752
	ds_read_b128 v[88:91], v0 offset:11776
	v_pk_mul_f32 v[6:7], v[2:3], v[94:95]
	v_pk_mul_f32 v[8:9], v[2:3], v[98:99]
	v_pk_fma_f32 v[6:7], v[4:5], v[96:97], v[6:7]
	v_pk_fma_f32 v[8:9], v[4:5], v[100:101], v[8:9]
	v_add_f32_e32 v10, v6, v7
	v_add_f32_e32 v20, v8, v9
	v_pk_mul_f32 v[2:3], v[2:3], v[102:103]
	v_add_f32_dpp v10, v10, v10 quad_perm:[1,0,3,2] row_mask:0xf bank_mask:0xf bound_ctrl:1
	v_pk_mul_f32 v[4:5], v[4:5], v[104:105]
	v_pk_fma_f32 v[2:3], v[106:107], v[114:115], v[2:3] op_sel_hi:[1,0,1]
	v_add_f32_dpp v10, v10, v10 quad_perm:[2,3,0,1] row_mask:0xf bank_mask:0xf bound_ctrl:1
	v_pk_fma_f32 v[4:5], v[108:109], v[114:115], v[4:5] op_sel_hi:[1,0,1]
	v_add_f32_dpp v62, v40, v40 row_half_mirror row_mask:0xf bank_mask:0xf bound_ctrl:1
	v_add_f32_dpp v10, v10, v10 row_half_mirror row_mask:0xf bank_mask:0xf bound_ctrl:1
	v_add_f32_dpp v63, v41, v41 row_half_mirror row_mask:0xf bank_mask:0xf bound_ctrl:1
	v_cndmask_b32_e64 v52, v62, v63, s[10:11]
	v_add_f32_dpp v10, v10, v10 row_mirror row_mask:0xf bank_mask:0xf bound_ctrl:1
	v_pk_fma_f32 v[2:3], v[110:111], v[10:11], v[2:3] op_sel_hi:[1,0,1]
	v_pk_fma_f32 v[4:5], v[112:113], v[10:11], v[4:5] op_sel_hi:[1,0,1]
	s_waitcnt lgkmcnt(6)
	ds_read_b128 v[94:97], v0 offset:12544
	ds_read_b128 v[98:101], v0 offset:12800
	ds_read_b128 v[102:105], v0 offset:13056
	ds_read_b128 v[106:109], v0 offset:13312
	ds_read_b32 v114, v12 offset:12544
	ds_read_b128 v[110:113], v0 offset:13568
	v_pk_mul_f32 v[6:7], v[2:3], v[116:117]
	v_pk_mul_f32 v[8:9], v[2:3], v[120:121]
	v_pk_fma_f32 v[6:7], v[4:5], v[118:119], v[6:7]
	v_pk_fma_f32 v[8:9], v[4:5], v[122:123], v[8:9]
	v_add_f32_e32 v10, v6, v7
	v_add_f32_e32 v21, v8, v9
	v_pk_mul_f32 v[2:3], v[2:3], v[124:125]
	v_add_f32_dpp v10, v10, v10 quad_perm:[1,0,3,2] row_mask:0xf bank_mask:0xf bound_ctrl:1
	v_pk_mul_f32 v[4:5], v[4:5], v[126:127]
	v_pk_fma_f32 v[2:3], v[128:129], v[140:141], v[2:3] op_sel_hi:[1,0,1]
	v_add_f32_dpp v10, v10, v10 quad_perm:[2,3,0,1] row_mask:0xf bank_mask:0xf bound_ctrl:1
	v_pk_fma_f32 v[4:5], v[130:131], v[140:141], v[4:5] op_sel_hi:[1,0,1]
	v_add_f32_dpp v62, v42, v42 row_half_mirror row_mask:0xf bank_mask:0xf bound_ctrl:1
	v_add_f32_dpp v10, v10, v10 row_half_mirror row_mask:0xf bank_mask:0xf bound_ctrl:1
	v_add_f32_dpp v63, v43, v43 row_half_mirror row_mask:0xf bank_mask:0xf bound_ctrl:1
	v_cndmask_b32_e64 v53, v62, v63, s[10:11]
	v_add_f32_dpp v10, v10, v10 row_mirror row_mask:0xf bank_mask:0xf bound_ctrl:1
	v_pk_fma_f32 v[2:3], v[132:133], v[10:11], v[2:3] op_sel_hi:[1,0,1]
	v_pk_fma_f32 v[4:5], v[134:135], v[10:11], v[4:5] op_sel_hi:[1,0,1]
	s_waitcnt lgkmcnt(6)
; __device__ __forceinline__ f32x2 pkmul_(f32x2 a, f32x2 b) { f32x2 d; asm("v_pk_mul_f32 %0, %1, %2" : "=v"(d) : "v"(a), "v"(b)); return d; }
; __device__ __forceinline__ f32x2 pkfma_(f32x2 a, f32x2 b, f32x2 c) { f32x2 d; asm("v_pk_fma_f32 %0, %1, %2, %3" : "=v"(d) : "v"(a), "v"(b), "v"(c)); return d; }
; __device__ __forceinline__ f32x2 pkfma_b(f32x2 a, f32x2 s, f32x2 c) { f32x2 d; asm("v_pk_fma_f32 %0, %1, %2, %3 op_sel_hi:[1,0,1]" : "=v"(d) : "v"(a), "v"(s), "v"(c)); return d; }
; __device__ __forceinline__ f32x2 lo2(f32x4 v) { return __builtin_shufflevector(v, v, 0, 1); }
; __device__ __forceinline__ f32x2 hi2(f32x4 v) { return __builtin_shufflevector(v, v, 2, 3); }
; __device__ __forceinline__ float red8(float x) { x += dpp_<0x141>(x); x += dpp_<0xB1>(x); x += dpp_<0x4E>(x); return x; }
; __global__ void __launch_bounds__(NTHR) hymba_fwd(Params P) {
;     ...
;                     for (int st = 0; st < TB; ++st) {
;                         if (st + 2 < TB) LDSTEP((st + 2) * REC, nav0, nav1, nbv0, nbv1, ndw0, ndw1, nkt0, nkt1, nwr0, nwr1, nvv, nsc);
;                         __builtin_amdgcn_sched_barrier(0);
;                         const f32x2 pa = pkfma_(S2[3], hi2(a1), pkfma_(S2[2], lo2(a1), pkfma_(S2[1], hi2(a0), pkmul_(S2[0], lo2(a0)))));
;                         const f32x2 py = pkfma_(S2[3], hi2(w1_), pkfma_(S2[2], lo2(w1_), pkfma_(S2[1], hi2(w0_), pkmul_(S2[0], lo2(w0_)))));
;                         float da = pa[0] + pa[1], dy = py[0] + py[1];
;                         da = red8(da); dy = red8(dy);
;                         const float y = dy + da * sc_[0] + vv_ * sc_[1];
;                         { f32x2 dab, vvb; dab[0] = da; dab[1] = da; vvb[0] = vv_; vvb[1] = vv_;
;                           S2[0] = pkfma_b(lo2(k0), vvb, pkfma_b(lo2(b0), dab, pkmul_(S2[0], lo2(d0)))); S2[1] = pkfma_b(hi2(k0), vvb, pkfma_b(hi2(b0), dab, pkmul_(S2[1], hi2(d0))));
;                           S2[2] = pkfma_b(lo2(k1), vvb, pkfma_b(lo2(b1), dab, pkmul_(S2[2], lo2(d1)))); S2[3] = pkfma_b(hi2(k1), vvb, pkfma_b(hi2(b1), dab, pkmul_(S2[3], hi2(d1)))); }
;                         const float sh = __int_as_float(__builtin_amdgcn_update_dpp(__float_as_int(y), __float_as_int(yacc), 0x111, 0xF, 0xF, false));
;                         yacc = first8 ? y : sh;
;                         if ((st & 7) == 7) yp[(size_t)(blk * TB + (st - 7)) * CW] = yacc;
	ds_read_b128 v[116:119], v0 offset:14336
	ds_read_b128 v[120:123], v0 offset:14592
	ds_read_b128 v[124:127], v0 offset:14848
	ds_read_b128 v[128:131], v0 offset:15104
	ds_read_b32 v140, v12 offset:14336
	ds_read_b128 v[132:135], v0 offset:15360
	v_pk_mul_f32 v[6:7], v[2:3], v[72:73]
	v_pk_mul_f32 v[8:9], v[2:3], v[76:77]
	v_pk_fma_f32 v[6:7], v[4:5], v[74:75], v[6:7]
	v_pk_fma_f32 v[8:9], v[4:5], v[78:79], v[8:9]
	v_add_f32_e32 v10, v6, v7
	v_add_f32_e32 v22, v8, v9
	v_pk_mul_f32 v[2:3], v[2:3], v[80:81]
	v_add_f32_dpp v10, v10, v10 quad_perm:[1,0,3,2] row_mask:0xf bank_mask:0xf bound_ctrl:1
	v_pk_mul_f32 v[4:5], v[4:5], v[82:83]
	v_pk_fma_f32 v[2:3], v[84:85], v[92:93], v[2:3] op_sel_hi:[1,0,1]
	v_add_f32_dpp v10, v10, v10 quad_perm:[2,3,0,1] row_mask:0xf bank_mask:0xf bound_ctrl:1
	v_pk_fma_f32 v[4:5], v[86:87], v[92:93], v[4:5] op_sel_hi:[1,0,1]
	v_add_f32_dpp v62, v44, v44 row_half_mirror row_mask:0xf bank_mask:0xf bound_ctrl:1
	v_add_f32_dpp v10, v10, v10 row_half_mirror row_mask:0xf bank_mask:0xf bound_ctrl:1
	v_add_f32_dpp v63, v45, v45 row_half_mirror row_mask:0xf bank_mask:0xf bound_ctrl:1
	v_cndmask_b32_e64 v54, v62, v63, s[10:11]
	v_add_f32_dpp v10, v10, v10 row_mirror row_mask:0xf bank_mask:0xf bound_ctrl:1
	v_pk_fma_f32 v[2:3], v[88:89], v[10:11], v[2:3] op_sel_hi:[1,0,1]
	v_pk_fma_f32 v[4:5], v[90:91], v[10:11], v[4:5] op_sel_hi:[1,0,1]
	s_waitcnt lgkmcnt(6)
	ds_read_b128 v[72:75], v0 offset:16128
	ds_read_b128 v[76:79], v0 offset:16384
	ds_read_b128 v[80:83], v0 offset:16640
	ds_read_b128 v[84:87], v0 offset:16896
	ds_read_b32 v92, v12 offset:16128
	ds_read_b128 v[88:91], v0 offset:17152
	v_pk_mul_f32 v[6:7], v[2:3], v[94:95]
	v_pk_mul_f32 v[8:9], v[2:3], v[98:99]
	v_pk_fma_f32 v[6:7], v[4:5], v[96:97], v[6:7]
	v_pk_fma_f32 v[8:9], v[4:5], v[100:101], v[8:9]
	v_add_f32_e32 v10, v6, v7
	v_add_f32_e32 v23, v8, v9
	v_pk_mul_f32 v[2:3], v[2:3], v[102:103]
	v_add_f32_dpp v10, v10, v10 quad_perm:[1,0,3,2] row_mask:0xf bank_mask:0xf bound_ctrl:1
	v_pk_mul_f32 v[4:5], v[4:5], v[104:105]
	v_pk_fma_f32 v[2:3], v[106:107], v[114:115], v[2:3] op_sel_hi:[1,0,1]
	v_add_f32_dpp v10, v10, v10 quad_perm:[2,3,0,1] row_mask:0xf bank_mask:0xf bound_ctrl:1
	v_pk_fma_f32 v[4:5], v[108:109], v[114:115], v[4:5] op_sel_hi:[1,0,1]
	v_add_f32_dpp v62, v46, v46 row_half_mirror row_mask:0xf bank_mask:0xf bound_ctrl:1
	v_add_f32_dpp v10, v10, v10 row_half_mirror row_mask:0xf bank_mask:0xf bound_ctrl:1
	v_add_f32_dpp v63, v47, v47 row_half_mirror row_mask:0xf bank_mask:0xf bound_ctrl:1
	v_cndmask_b32_e64 v55, v62, v63, s[10:11]
	v_add_f32_dpp v10, v10, v10 row_mirror row_mask:0xf bank_mask:0xf bound_ctrl:1
	v_pk_fma_f32 v[2:3], v[110:111], v[10:11], v[2:3] op_sel_hi:[1,0,1]
	v_pk_fma_f32 v[4:5], v[112:113], v[10:11], v[4:5] op_sel_hi:[1,0,1]
	s_waitcnt lgkmcnt(6)
	ds_read_b128 v[94:97], v0 offset:17920
	ds_read_b128 v[98:101], v0 offset:18176
	ds_read_b128 v[102:105], v0 offset:18432
	ds_read_b128 v[106:109], v0 offset:18688
	ds_read_b32 v114, v12 offset:17920
	ds_read_b128 v[110:113], v0 offset:18944
	v_pk_mul_f32 v[6:7], v[2:3], v[116:117]
	v_pk_mul_f32 v[8:9], v[2:3], v[120:121]
	v_pk_fma_f32 v[6:7], v[4:5], v[118:119], v[6:7]
	v_pk_fma_f32 v[8:9], v[4:5], v[122:123], v[8:9]
	v_add_f32_e32 v10, v6, v7
	v_add_f32_e32 v24, v8, v9
	v_pk_mul_f32 v[2:3], v[2:3], v[124:125]
	v_add_f32_dpp v10, v10, v10 quad_perm:[1,0,3,2] row_mask:0xf bank_mask:0xf bound_ctrl:1
	v_pk_mul_f32 v[4:5], v[4:5], v[126:127]
	v_pk_fma_f32 v[2:3], v[128:129], v[140:141], v[2:3] op_sel_hi:[1,0,1]
	v_add_f32_dpp v10, v10, v10 quad_perm:[2,3,0,1] row_mask:0xf bank_mask:0xf bound_ctrl:1
	v_pk_fma_f32 v[4:5], v[130:131], v[140:141], v[4:5] op_sel_hi:[1,0,1]
	v_add_f32_dpp v62, v48, v48 quad_perm:[1,0,3,2] row_mask:0xf bank_mask:0xf bound_ctrl:1
	v_add_f32_dpp v10, v10, v10 row_half_mirror row_mask:0xf bank_mask:0xf bound_ctrl:1
	v_add_f32_dpp v63, v49, v49 quad_perm:[1,0,3,2] row_mask:0xf bank_mask:0xf bound_ctrl:1
	v_cndmask_b32_e64 v56, v62, v63, s[22:23]
	v_add_f32_dpp v10, v10, v10 row_mirror row_mask:0xf bank_mask:0xf bound_ctrl:1
	v_pk_fma_f32 v[2:3], v[132:133], v[10:11], v[2:3] op_sel_hi:[1,0,1]
	v_pk_fma_f32 v[4:5], v[134:135], v[10:11], v[4:5] op_sel_hi:[1,0,1]
	s_waitcnt lgkmcnt(6)
	ds_read_b128 v[116:119], v0 offset:19712
	ds_read_b128 v[120:123], v0 offset:19968
	ds_read_b128 v[124:127], v0 offset:20224
	ds_read_b128 v[128:131], v0 offset:20480
	ds_read_b32 v140, v12 offset:19712
	ds_read_b128 v[132:135], v0 offset:20736
	v_pk_mul_f32 v[6:7], v[2:3], v[72:73]
	v_pk_mul_f32 v[8:9], v[2:3], v[76:77]
	v_pk_fma_f32 v[6:7], v[4:5], v[74:75], v[6:7]
	v_pk_fma_f32 v[8:9], v[4:5], v[78:79], v[8:9]
	v_add_f32_e32 v10, v6, v7
	v_add_f32_e32 v25, v8, v9
	v_pk_mul_f32 v[2:3], v[2:3], v[80:81]
	v_add_f32_dpp v10, v10, v10 quad_perm:[1,0,3,2] row_mask:0xf bank_mask:0xf bound_ctrl:1
	v_pk_mul_f32 v[4:5], v[4:5], v[82:83]
	v_pk_fma_f32 v[2:3], v[84:85], v[92:93], v[2:3] op_sel_hi:[1,0,1]
	v_add_f32_dpp v10, v10, v10 quad_perm:[2,3,0,1] row_mask:0xf bank_mask:0xf bound_ctrl:1
	v_pk_fma_f32 v[4:5], v[86:87], v[92:93], v[4:5] op_sel_hi:[1,0,1]
	v_add_f32_dpp v62, v50, v50 quad_perm:[1,0,3,2] row_mask:0xf bank_mask:0xf bound_ctrl:1
	v_add_f32_dpp v10, v10, v10 row_half_mirror row_mask:0xf bank_mask:0xf bound_ctrl:1
	v_add_f32_dpp v63, v51, v51 quad_perm:[1,0,3,2] row_mask:0xf bank_mask:0xf bound_ctrl:1
	v_cndmask_b32_e64 v57, v62, v63, s[22:23]
	v_add_f32_dpp v10, v10, v10 row_mirror row_mask:0xf bank_mask:0xf bound_ctrl:1
	v_pk_fma_f32 v[2:3], v[88:89], v[10:11], v[2:3] op_sel_hi:[1,0,1]
	v_pk_fma_f32 v[4:5], v[90:91], v[10:11], v[4:5] op_sel_hi:[1,0,1]
	s_waitcnt lgkmcnt(6)
; __device__ __forceinline__ f32x2 pkmul_(f32x2 a, f32x2 b) { f32x2 d; asm("v_pk_mul_f32 %0, %1, %2" : "=v"(d) : "v"(a), "v"(b)); return d; }
; __device__ __forceinline__ f32x2 pkfma_(f32x2 a, f32x2 b, f32x2 c) { f32x2 d; asm("v_pk_fma_f32 %0, %1, %2, %3" : "=v"(d) : "v"(a), "v"(b), "v"(c)); return d; }
; __device__ __forceinline__ f32x2 pkfma_b(f32x2 a, f32x2 s, f32x2 c) { f32x2 d; asm("v_pk_fma_f32 %0, %1, %2, %3 op_sel_hi:[1,0,1]" : "=v"(d) : "v"(a), "v"(s), "v"(c)); return d; }
; __device__ __forceinline__ f32x2 lo2(f32x4 v) { return __builtin_shufflevector(v, v, 0, 1); }
; __device__ __forceinline__ f32x2 hi2(f32x4 v) { return __builtin_shufflevector(v, v, 2, 3); }
; __device__ __forceinline__ float red8(float x) { x += dpp_<0x141>(x); x += dpp_<0xB1>(x); x += dpp_<0x4E>(x); return x; }
; __global__ void __launch_bounds__(NTHR) hymba_fwd(Params P) {
;     ...
;                     for (int st = 0; st < TB; ++st) {
;                         if (st + 2 < TB) LDSTEP((st + 2) * REC, nav0, nav1, nbv0, nbv1, ndw0, ndw1, nkt0, nkt1, nwr0, nwr1, nvv, nsc);
;                         __builtin_amdgcn_sched_barrier(0);
;                         const f32x2 pa = pkfma_(S2[3], hi2(a1), pkfma_(S2[2], lo2(a1), pkfma_(S2[1], hi2(a0), pkmul_(S2[0], lo2(a0)))));
;                         const f32x2 py = pkfma_(S2[3], hi2(w1_), pkfma_(S2[2], lo2(w1_), pkfma_(S2[1], hi2(w0_), pkmul_(S2[0], lo2(w0_)))));
;                         float da = pa[0] + pa[1], dy = py[0] + py[1];
;                         da = red8(da); dy = red8(dy);
;                         const float y = dy + da * sc_[0] + vv_ * sc_[1];
;                         { f32x2 dab, vvb; dab[0] = da; dab[1] = da; vvb[0] = vv_; vvb[1] = vv_;
;                           S2[0] = pkfma_b(lo2(k0), vvb, pkfma_b(lo2(b0), dab, pkmul_(S2[0], lo2(d0)))); S2[1] = pkfma_b(hi2(k0), vvb, pkfma_b(hi2(b0), dab, pkmul_(S2[1], hi2(d0))));
;                           S2[2] = pkfma_b(lo2(k1), vvb, pkfma_b(lo2(b1), dab, pkmul_(S2[2], lo2(d1)))); S2[3] = pkfma_b(hi2(k1), vvb, pkfma_b(hi2(b1), dab, pkmul_(S2[3], hi2(d1)))); }
;                         const float sh = __int_as_float(__builtin_amdgcn_update_dpp(__float_as_int(y), __float_as_int(yacc), 0x111, 0xF, 0xF, false));
;                         yacc = first8 ? y : sh;
;                         if ((st & 7) == 7) yp[(size_t)(blk * TB + (st - 7)) * CW] = yacc;
	ds_read_b128 v[72:75], v0 offset:21504
	ds_read_b128 v[76:79], v0 offset:21760
	ds_read_b128 v[80:83], v0 offset:22016
	ds_read_b128 v[84:87], v0 offset:22272
	ds_read_b32 v92, v12 offset:21504
	ds_read_b128 v[88:91], v0 offset:22528
	v_pk_mul_f32 v[6:7], v[2:3], v[94:95]
	v_pk_mul_f32 v[8:9], v[2:3], v[98:99]
	v_pk_fma_f32 v[6:7], v[4:5], v[96:97], v[6:7]
	v_pk_fma_f32 v[8:9], v[4:5], v[100:101], v[8:9]
	v_add_f32_e32 v10, v6, v7
	v_add_f32_e32 v26, v8, v9
	v_pk_mul_f32 v[2:3], v[2:3], v[102:103]
	v_add_f32_dpp v10, v10, v10 quad_perm:[1,0,3,2] row_mask:0xf bank_mask:0xf bound_ctrl:1
	v_pk_mul_f32 v[4:5], v[4:5], v[104:105]
	v_pk_fma_f32 v[2:3], v[106:107], v[114:115], v[2:3] op_sel_hi:[1,0,1]
	v_add_f32_dpp v10, v10, v10 quad_perm:[2,3,0,1] row_mask:0xf bank_mask:0xf bound_ctrl:1
	v_pk_fma_f32 v[4:5], v[108:109], v[114:115], v[4:5] op_sel_hi:[1,0,1]
	v_add_f32_dpp v62, v52, v52 quad_perm:[1,0,3,2] row_mask:0xf bank_mask:0xf bound_ctrl:1
	v_add_f32_dpp v10, v10, v10 row_half_mirror row_mask:0xf bank_mask:0xf bound_ctrl:1
	v_add_f32_dpp v63, v53, v53 quad_perm:[1,0,3,2] row_mask:0xf bank_mask:0xf bound_ctrl:1
	v_cndmask_b32_e64 v58, v62, v63, s[22:23]
	v_add_f32_dpp v10, v10, v10 row_mirror row_mask:0xf bank_mask:0xf bound_ctrl:1
	v_pk_fma_f32 v[2:3], v[110:111], v[10:11], v[2:3] op_sel_hi:[1,0,1]
	v_pk_fma_f32 v[4:5], v[112:113], v[10:11], v[4:5] op_sel_hi:[1,0,1]
	s_waitcnt lgkmcnt(6)
	ds_read_b128 v[94:97], v0 offset:23296
	ds_read_b128 v[98:101], v0 offset:23552
	ds_read_b128 v[102:105], v0 offset:23808
	ds_read_b128 v[106:109], v0 offset:24064
	ds_read_b32 v114, v12 offset:23296
	ds_read_b128 v[110:113], v0 offset:24320
	v_pk_mul_f32 v[6:7], v[2:3], v[116:117]
	v_pk_mul_f32 v[8:9], v[2:3], v[120:121]
	v_pk_fma_f32 v[6:7], v[4:5], v[118:119], v[6:7]
	v_pk_fma_f32 v[8:9], v[4:5], v[122:123], v[8:9]
	v_add_f32_e32 v10, v6, v7
	v_add_f32_e32 v27, v8, v9
	v_pk_mul_f32 v[2:3], v[2:3], v[124:125]
	v_add_f32_dpp v10, v10, v10 quad_perm:[1,0,3,2] row_mask:0xf bank_mask:0xf bound_ctrl:1
	v_pk_mul_f32 v[4:5], v[4:5], v[126:127]
	v_pk_fma_f32 v[2:3], v[128:129], v[140:141], v[2:3] op_sel_hi:[1,0,1]
	v_add_f32_dpp v10, v10, v10 quad_perm:[2,3,0,1] row_mask:0xf bank_mask:0xf bound_ctrl:1
	v_pk_fma_f32 v[4:5], v[130:131], v[140:141], v[4:5] op_sel_hi:[1,0,1]
	v_add_f32_dpp v62, v54, v54 quad_perm:[1,0,3,2] row_mask:0xf bank_mask:0xf bound_ctrl:1
	v_add_f32_dpp v10, v10, v10 row_half_mirror row_mask:0xf bank_mask:0xf bound_ctrl:1
	v_add_f32_dpp v63, v55, v55 quad_perm:[1,0,3,2] row_mask:0xf bank_mask:0xf bound_ctrl:1
	v_cndmask_b32_e64 v59, v62, v63, s[22:23]
	v_add_f32_dpp v10, v10, v10 row_mirror row_mask:0xf bank_mask:0xf bound_ctrl:1
	v_pk_fma_f32 v[2:3], v[132:133], v[10:11], v[2:3] op_sel_hi:[1,0,1]
	v_pk_fma_f32 v[4:5], v[134:135], v[10:11], v[4:5] op_sel_hi:[1,0,1]
	s_waitcnt lgkmcnt(6)
	ds_read_b128 v[116:119], v0 offset:25088
	ds_read_b128 v[120:123], v0 offset:25344
	ds_read_b128 v[124:127], v0 offset:25600
	ds_read_b128 v[128:131], v0 offset:25856
	ds_read_b32 v140, v12 offset:25088
	ds_read_b128 v[132:135], v0 offset:26112
	v_pk_mul_f32 v[6:7], v[2:3], v[72:73]
	v_pk_mul_f32 v[8:9], v[2:3], v[76:77]
	v_pk_fma_f32 v[6:7], v[4:5], v[74:75], v[6:7]
	v_pk_fma_f32 v[8:9], v[4:5], v[78:79], v[8:9]
	v_add_f32_e32 v10, v6, v7
	v_add_f32_e32 v28, v8, v9
	v_pk_mul_f32 v[2:3], v[2:3], v[80:81]
	v_add_f32_dpp v10, v10, v10 quad_perm:[1,0,3,2] row_mask:0xf bank_mask:0xf bound_ctrl:1
	v_pk_mul_f32 v[4:5], v[4:5], v[82:83]
	v_pk_fma_f32 v[2:3], v[84:85], v[92:93], v[2:3] op_sel_hi:[1,0,1]
	v_add_f32_dpp v10, v10, v10 quad_perm:[2,3,0,1] row_mask:0xf bank_mask:0xf bound_ctrl:1
	v_pk_fma_f32 v[4:5], v[86:87], v[92:93], v[4:5] op_sel_hi:[1,0,1]
	v_add_f32_dpp v62, v56, v56 quad_perm:[2,3,0,1] row_mask:0xf bank_mask:0xf bound_ctrl:1
	v_add_f32_dpp v10, v10, v10 row_half_mirror row_mask:0xf bank_mask:0xf bound_ctrl:1
	v_add_f32_dpp v63, v57, v57 quad_perm:[2,3,0,1] row_mask:0xf bank_mask:0xf bound_ctrl:1
	v_cndmask_b32_e64 v60, v62, v63, s[26:27]
	v_add_f32_dpp v10, v10, v10 row_mirror row_mask:0xf bank_mask:0xf bound_ctrl:1
	v_pk_fma_f32 v[2:3], v[88:89], v[10:11], v[2:3] op_sel_hi:[1,0,1]
	v_pk_fma_f32 v[4:5], v[90:91], v[10:11], v[4:5] op_sel_hi:[1,0,1]
	s_waitcnt lgkmcnt(6)
	ds_read_b128 v[72:75], v0 offset:26880
	ds_read_b128 v[76:79], v0 offset:27136
	ds_read_b128 v[80:83], v0 offset:27392
	ds_read_b128 v[84:87], v0 offset:27648
	ds_read_b32 v92, v12 offset:26880
	ds_read_b128 v[88:91], v0 offset:27904
	v_pk_mul_f32 v[6:7], v[2:3], v[94:95]
	v_pk_mul_f32 v[8:9], v[2:3], v[98:99]
	v_pk_fma_f32 v[6:7], v[4:5], v[96:97], v[6:7]
	v_pk_fma_f32 v[8:9], v[4:5], v[100:101], v[8:9]
	v_add_f32_e32 v10, v6, v7
	v_add_f32_e32 v29, v8, v9
	v_pk_mul_f32 v[2:3], v[2:3], v[102:103]
	v_add_f32_dpp v10, v10, v10 quad_perm:[1,0,3,2] row_mask:0xf bank_mask:0xf bound_ctrl:1
	v_pk_mul_f32 v[4:5], v[4:5], v[104:105]
	v_pk_fma_f32 v[2:3], v[106:107], v[114:115], v[2:3] op_sel_hi:[1,0,1]
	v_add_f32_dpp v10, v10, v10 quad_perm:[2,3,0,1] row_mask:0xf bank_mask:0xf bound_ctrl:1
	v_pk_fma_f32 v[4:5], v[108:109], v[114:115], v[4:5] op_sel_hi:[1,0,1]
	v_add_f32_dpp v62, v58, v58 quad_perm:[2,3,0,1] row_mask:0xf bank_mask:0xf bound_ctrl:1
	v_add_f32_dpp v10, v10, v10 row_half_mirror row_mask:0xf bank_mask:0xf bound_ctrl:1
	v_add_f32_dpp v63, v59, v59 quad_perm:[2,3,0,1] row_mask:0xf bank_mask:0xf bound_ctrl:1
	v_cndmask_b32_e64 v61, v62, v63, s[26:27]
	v_add_f32_dpp v10, v10, v10 row_mirror row_mask:0xf bank_mask:0xf bound_ctrl:1
	v_pk_fma_f32 v[2:3], v[110:111], v[10:11], v[2:3] op_sel_hi:[1,0,1]
	v_pk_fma_f32 v[4:5], v[112:113], v[10:11], v[4:5] op_sel_hi:[1,0,1]
	s_waitcnt lgkmcnt(6)
; __device__ __forceinline__ f32x2 pkmul_(f32x2 a, f32x2 b) { f32x2 d; asm("v_pk_mul_f32 %0, %1, %2" : "=v"(d) : "v"(a), "v"(b)); return d; }
; __device__ __forceinline__ f32x2 pkfma_(f32x2 a, f32x2 b, f32x2 c) { f32x2 d; asm("v_pk_fma_f32 %0, %1, %2, %3" : "=v"(d) : "v"(a), "v"(b), "v"(c)); return d; }
; __device__ __forceinline__ f32x2 pkfma_b(f32x2 a, f32x2 s, f32x2 c) { f32x2 d; asm("v_pk_fma_f32 %0, %1, %2, %3 op_sel_hi:[1,0,1]" : "=v"(d) : "v"(a), "v"(s), "v"(c)); return d; }
; __device__ __forceinline__ f32x2 lo2(f32x4 v) { return __builtin_shufflevector(v, v, 0, 1); }
; __device__ __forceinline__ f32x2 hi2(f32x4 v) { return __builtin_shufflevector(v, v, 2, 3); }
; __device__ __forceinline__ float red8(float x) { x += dpp_<0x141>(x); x += dpp_<0xB1>(x); x += dpp_<0x4E>(x); return x; }
; __global__ void __launch_bounds__(NTHR) hymba_fwd(Params P) {
;     ...
;                     for (int st = 0; st < TB; ++st) {
;                         if (st + 2 < TB) LDSTEP((st + 2) * REC, nav0, nav1, nbv0, nbv1, ndw0, ndw1, nkt0, nkt1, nwr0, nwr1, nvv, nsc);
;                         __builtin_amdgcn_sched_barrier(0);
;                         const f32x2 pa = pkfma_(S2[3], hi2(a1), pkfma_(S2[2], lo2(a1), pkfma_(S2[1], hi2(a0), pkmul_(S2[0], lo2(a0)))));
;                         const f32x2 py = pkfma_(S2[3], hi2(w1_), pkfma_(S2[2], lo2(w1_), pkfma_(S2[1], hi2(w0_), pkmul_(S2[0], lo2(w0_)))));
;                         float da = pa[0] + pa[1], dy = py[0] + py[1];
;                         da = red8(da); dy = red8(dy);
;                         const float y = dy + da * sc_[0] + vv_ * sc_[1];
;                         { f32x2 dab, vvb; dab[0] = da; dab[1] = da; vvb[0] = vv_; vvb[1] = vv_;
;                           S2[0] = pkfma_b(lo2(k0), vvb, pkfma_b(lo2(b0), dab, pkmul_(S2[0], lo2(d0)))); S2[1] = pkfma_b(hi2(k0), vvb, pkfma_b(hi2(b0), dab, pkmul_(S2[1], hi2(d0))));
;                           S2[2] = pkfma_b(lo2(k1), vvb, pkfma_b(lo2(b1), dab, pkmul_(S2[2], lo2(d1)))); S2[3] = pkfma_b(hi2(k1), vvb, pkfma_b(hi2(b1), dab, pkmul_(S2[3], hi2(d1)))); }
;                         const float sh = __int_as_float(__builtin_amdgcn_update_dpp(__float_as_int(y), __float_as_int(yacc), 0x111, 0xF, 0xF, false));
;                         yacc = first8 ? y : sh;
;                         if ((st & 7) == 7) yp[(size_t)(blk * TB + (st - 7)) * CW] = yacc;
	ds_read_b128 v[94:97], v0 offset:28672
	ds_read_b128 v[98:101], v0 offset:28928
	ds_read_b128 v[102:105], v0 offset:29184
	ds_read_b128 v[106:109], v0 offset:29440
	ds_read_b32 v114, v12 offset:28672
	ds_read_b128 v[110:113], v0 offset:29696
	v_pk_mul_f32 v[6:7], v[2:3], v[116:117]
	v_pk_mul_f32 v[8:9], v[2:3], v[120:121]
	v_pk_fma_f32 v[6:7], v[4:5], v[118:119], v[6:7]
	v_pk_fma_f32 v[8:9], v[4:5], v[122:123], v[8:9]
	v_add_f32_e32 v10, v6, v7
	v_add_f32_e32 v30, v8, v9
	v_pk_mul_f32 v[2:3], v[2:3], v[124:125]
	v_add_f32_dpp v10, v10, v10 quad_perm:[1,0,3,2] row_mask:0xf bank_mask:0xf bound_ctrl:1
	v_pk_mul_f32 v[4:5], v[4:5], v[126:127]
	v_pk_fma_f32 v[2:3], v[128:129], v[140:141], v[2:3] op_sel_hi:[1,0,1]
	v_add_f32_dpp v10, v10, v10 quad_perm:[2,3,0,1] row_mask:0xf bank_mask:0xf bound_ctrl:1
	v_pk_fma_f32 v[4:5], v[130:131], v[140:141], v[4:5] op_sel_hi:[1,0,1]
	v_add_f32_dpp v62, v60, v60 row_mirror row_mask:0xf bank_mask:0xf bound_ctrl:1
	v_add_f32_dpp v10, v10, v10 row_half_mirror row_mask:0xf bank_mask:0xf bound_ctrl:1
	v_add_f32_dpp v63, v61, v61 row_mirror row_mask:0xf bank_mask:0xf bound_ctrl:1
	v_cndmask_b32_e64 v64, v62, v63, s[56:57]
	v_add_f32_dpp v10, v10, v10 row_mirror row_mask:0xf bank_mask:0xf bound_ctrl:1
	v_pk_fma_f32 v[2:3], v[132:133], v[10:11], v[2:3] op_sel_hi:[1,0,1]
	v_pk_fma_f32 v[4:5], v[134:135], v[10:11], v[4:5] op_sel_hi:[1,0,1]
	s_waitcnt lgkmcnt(6)
	ds_read_b128 v[116:119], v0 offset:30464
	ds_read_b128 v[120:123], v0 offset:30720
	ds_read_b128 v[124:127], v0 offset:30976
	ds_read_b128 v[128:131], v0 offset:31232
	ds_read_b32 v140, v12 offset:30464
	ds_read_b128 v[132:135], v0 offset:31488
	v_pk_mul_f32 v[6:7], v[2:3], v[72:73]
	v_pk_mul_f32 v[8:9], v[2:3], v[76:77]
	v_pk_fma_f32 v[6:7], v[4:5], v[74:75], v[6:7]
	v_pk_fma_f32 v[8:9], v[4:5], v[78:79], v[8:9]
	v_add_f32_e32 v10, v6, v7
	v_add_f32_e32 v31, v8, v9
	v_pk_mul_f32 v[2:3], v[2:3], v[80:81]
	v_add_f32_dpp v10, v10, v10 quad_perm:[1,0,3,2] row_mask:0xf bank_mask:0xf bound_ctrl:1
	v_pk_mul_f32 v[4:5], v[4:5], v[82:83]
	v_pk_fma_f32 v[2:3], v[84:85], v[92:93], v[2:3] op_sel_hi:[1,0,1]
	v_add_f32_dpp v10, v10, v10 quad_perm:[2,3,0,1] row_mask:0xf bank_mask:0xf bound_ctrl:1
	v_pk_fma_f32 v[4:5], v[86:87], v[92:93], v[4:5] op_sel_hi:[1,0,1]
	v_add_f32_e32 v64, v64, v66
	v_add_f32_dpp v10, v10, v10 row_half_mirror row_mask:0xf bank_mask:0xf bound_ctrl:1
	s_cmp_eq_u32 s14, 64
	s_cbranch_scc1 .Lp4c_skipst
	global_store_dword v14, v64, s[8:9]
	s_add_u32 s8, s8, 0x10000
	s_addc_u32 s9, s9, 0
.Lp4c_skipst:
	v_add_f32_dpp v10, v10, v10 row_mirror row_mask:0xf bank_mask:0xf bound_ctrl:1
	v_pk_fma_f32 v[2:3], v[88:89], v[10:11], v[2:3] op_sel_hi:[1,0,1]
	v_pk_fma_f32 v[4:5], v[90:91], v[10:11], v[4:5] op_sel_hi:[1,0,1]
	s_waitcnt lgkmcnt(6)
	ds_read_b128 v[72:75], v0 offset:32256
	ds_read_b128 v[76:79], v0 offset:32512
	ds_read_b128 v[80:83], v0 offset:32768
	ds_read_b128 v[84:87], v0 offset:33024
	ds_read_b32 v92, v12 offset:32256
	ds_read_b128 v[88:91], v0 offset:33280
	ds_read_b32 v66, v13 offset:28672
	v_pk_mul_f32 v[6:7], v[2:3], v[94:95]
	v_pk_mul_f32 v[8:9], v[2:3], v[98:99]
	v_pk_fma_f32 v[6:7], v[4:5], v[96:97], v[6:7]
	v_pk_fma_f32 v[8:9], v[4:5], v[100:101], v[8:9]
	v_add_f32_e32 v10, v6, v7
	v_add_f32_e32 v32, v8, v9
	v_pk_mul_f32 v[2:3], v[2:3], v[102:103]
	v_add_f32_dpp v10, v10, v10 quad_perm:[1,0,3,2] row_mask:0xf bank_mask:0xf bound_ctrl:1
	v_pk_mul_f32 v[4:5], v[4:5], v[104:105]
	v_pk_fma_f32 v[2:3], v[106:107], v[114:115], v[2:3] op_sel_hi:[1,0,1]
	v_add_f32_dpp v10, v10, v10 quad_perm:[2,3,0,1] row_mask:0xf bank_mask:0xf bound_ctrl:1
	v_pk_fma_f32 v[4:5], v[108:109], v[114:115], v[4:5] op_sel_hi:[1,0,1]
	v_add_f32_dpp v62, v16, v16 row_half_mirror row_mask:0xf bank_mask:0xf bound_ctrl:1
	v_add_f32_dpp v10, v10, v10 row_half_mirror row_mask:0xf bank_mask:0xf bound_ctrl:1
	v_add_f32_dpp v63, v17, v17 row_half_mirror row_mask:0xf bank_mask:0xf bound_ctrl:1
	v_cndmask_b32_e64 v48, v62, v63, s[10:11]
	v_add_f32_dpp v10, v10, v10 row_mirror row_mask:0xf bank_mask:0xf bound_ctrl:1
	v_pk_fma_f32 v[2:3], v[110:111], v[10:11], v[2:3] op_sel_hi:[1,0,1]
	v_pk_fma_f32 v[4:5], v[112:113], v[10:11], v[4:5] op_sel_hi:[1,0,1]
	s_waitcnt lgkmcnt(7)
	ds_read_b128 v[94:97], v0 offset:34048
	ds_read_b128 v[98:101], v0 offset:34304
	ds_read_b128 v[102:105], v0 offset:34560
	ds_read_b128 v[106:109], v0 offset:34816
	ds_read_b32 v114, v12 offset:34048
	ds_read_b128 v[110:113], v0 offset:35072
	v_pk_mul_f32 v[6:7], v[2:3], v[116:117]
	v_pk_mul_f32 v[8:9], v[2:3], v[120:121]
	v_pk_fma_f32 v[6:7], v[4:5], v[118:119], v[6:7]
	v_pk_fma_f32 v[8:9], v[4:5], v[122:123], v[8:9]
	v_add_f32_e32 v10, v6, v7
	v_add_f32_e32 v33, v8, v9
	v_pk_mul_f32 v[2:3], v[2:3], v[124:125]
	v_add_f32_dpp v10, v10, v10 quad_perm:[1,0,3,2] row_mask:0xf bank_mask:0xf bound_ctrl:1
	v_pk_mul_f32 v[4:5], v[4:5], v[126:127]
	v_pk_fma_f32 v[2:3], v[128:129], v[140:141], v[2:3] op_sel_hi:[1,0,1]
	v_add_f32_dpp v10, v10, v10 quad_perm:[2,3,0,1] row_mask:0xf bank_mask:0xf bound_ctrl:1
	v_pk_fma_f32 v[4:5], v[130:131], v[140:141], v[4:5] op_sel_hi:[1,0,1]
	v_add_f32_dpp v62, v18, v18 row_half_mirror row_mask:0xf bank_mask:0xf bound_ctrl:1
	v_add_f32_dpp v10, v10, v10 row_half_mirror row_mask:0xf bank_mask:0xf bound_ctrl:1
	v_add_f32_dpp v63, v19, v19 row_half_mirror row_mask:0xf bank_mask:0xf bound_ctrl:1
	v_cndmask_b32_e64 v49, v62, v63, s[10:11]
	v_add_f32_dpp v10, v10, v10 row_mirror row_mask:0xf bank_mask:0xf bound_ctrl:1
	v_pk_fma_f32 v[2:3], v[132:133], v[10:11], v[2:3] op_sel_hi:[1,0,1]
	v_pk_fma_f32 v[4:5], v[134:135], v[10:11], v[4:5] op_sel_hi:[1,0,1]
	s_waitcnt lgkmcnt(7)
; __device__ __forceinline__ f32x2 pkmul_(f32x2 a, f32x2 b) { f32x2 d; asm("v_pk_mul_f32 %0, %1, %2" : "=v"(d) : "v"(a), "v"(b)); return d; }
; __device__ __forceinline__ f32x2 pkfma_(f32x2 a, f32x2 b, f32x2 c) { f32x2 d; asm("v_pk_fma_f32 %0, %1, %2, %3" : "=v"(d) : "v"(a), "v"(b), "v"(c)); return d; }
; __device__ __forceinline__ f32x2 pkfma_b(f32x2 a, f32x2 s, f32x2 c) { f32x2 d; asm("v_pk_fma_f32 %0, %1, %2, %3 op_sel_hi:[1,0,1]" : "=v"(d) : "v"(a), "v"(s), "v"(c)); return d; }
; __device__ __forceinline__ f32x2 lo2(f32x4 v) { return __builtin_shufflevector(v, v, 0, 1); }
; __device__ __forceinline__ f32x2 hi2(f32x4 v) { return __builtin_shufflevector(v, v, 2, 3); }
; __device__ __forceinline__ float red8(float x) { x += dpp_<0x141>(x); x += dpp_<0xB1>(x); x += dpp_<0x4E>(x); return x; }
; __global__ void __launch_bounds__(NTHR) hymba_fwd(Params P) {
;     ...
;                     for (int st = 0; st < TB; ++st) {
;                         if (st + 2 < TB) LDSTEP((st + 2) * REC, nav0, nav1, nbv0, nbv1, ndw0, ndw1, nkt0, nkt1, nwr0, nwr1, nvv, nsc);
;                         __builtin_amdgcn_sched_barrier(0);
;                         const f32x2 pa = pkfma_(S2[3], hi2(a1), pkfma_(S2[2], lo2(a1), pkfma_(S2[1], hi2(a0), pkmul_(S2[0], lo2(a0)))));
;                         const f32x2 py = pkfma_(S2[3], hi2(w1_), pkfma_(S2[2], lo2(w1_), pkfma_(S2[1], hi2(w0_), pkmul_(S2[0], lo2(w0_)))));
;                         float da = pa[0] + pa[1], dy = py[0] + py[1];
;                         da = red8(da); dy = red8(dy);
;                         const float y = dy + da * sc_[0] + vv_ * sc_[1];
;                         { f32x2 dab, vvb; dab[0] = da; dab[1] = da; vvb[0] = vv_; vvb[1] = vv_;
;                           S2[0] = pkfma_b(lo2(k0), vvb, pkfma_b(lo2(b0), dab, pkmul_(S2[0], lo2(d0)))); S2[1] = pkfma_b(hi2(k0), vvb, pkfma_b(hi2(b0), dab, pkmul_(S2[1], hi2(d0))));
;                           S2[2] = pkfma_b(lo2(k1), vvb, pkfma_b(lo2(b1), dab, pkmul_(S2[2], lo2(d1)))); S2[3] = pkfma_b(hi2(k1), vvb, pkfma_b(hi2(b1), dab, pkmul_(S2[3], hi2(d1)))); }
;                         const float sh = __int_as_float(__builtin_amdgcn_update_dpp(__float_as_int(y), __float_as_int(yacc), 0x111, 0xF, 0xF, false));
;                         yacc = first8 ? y : sh;
;                         if ((st & 7) == 7) yp[(size_t)(blk * TB + (st - 7)) * CW] = yacc;
	ds_read_b128 v[116:119], v0 offset:35840
	ds_read_b128 v[120:123], v0 offset:36096
	ds_read_b128 v[124:127], v0 offset:36352
	ds_read_b128 v[128:131], v0 offset:36608
	ds_read_b32 v140, v12 offset:35840
	ds_read_b128 v[132:135], v0 offset:36864
	v_pk_mul_f32 v[6:7], v[2:3], v[72:73]
	v_pk_mul_f32 v[8:9], v[2:3], v[76:77]
	v_pk_fma_f32 v[6:7], v[4:5], v[74:75], v[6:7]
	v_pk_fma_f32 v[8:9], v[4:5], v[78:79], v[8:9]
	v_add_f32_e32 v10, v6, v7
	v_add_f32_e32 v34, v8, v9
	v_pk_mul_f32 v[2:3], v[2:3], v[80:81]
	v_add_f32_dpp v10, v10, v10 quad_perm:[1,0,3,2] row_mask:0xf bank_mask:0xf bound_ctrl:1
	v_pk_mul_f32 v[4:5], v[4:5], v[82:83]
	v_pk_fma_f32 v[2:3], v[84:85], v[92:93], v[2:3] op_sel_hi:[1,0,1]
	v_add_f32_dpp v10, v10, v10 quad_perm:[2,3,0,1] row_mask:0xf bank_mask:0xf bound_ctrl:1
	v_pk_fma_f32 v[4:5], v[86:87], v[92:93], v[4:5] op_sel_hi:[1,0,1]
	v_add_f32_dpp v62, v20, v20 row_half_mirror row_mask:0xf bank_mask:0xf bound_ctrl:1
	v_add_f32_dpp v10, v10, v10 row_half_mirror row_mask:0xf bank_mask:0xf bound_ctrl:1
	v_add_f32_dpp v63, v21, v21 row_half_mirror row_mask:0xf bank_mask:0xf bound_ctrl:1
	v_cndmask_b32_e64 v50, v62, v63, s[10:11]
	v_add_f32_dpp v10, v10, v10 row_mirror row_mask:0xf bank_mask:0xf bound_ctrl:1
	v_pk_fma_f32 v[2:3], v[88:89], v[10:11], v[2:3] op_sel_hi:[1,0,1]
	v_pk_fma_f32 v[4:5], v[90:91], v[10:11], v[4:5] op_sel_hi:[1,0,1]
	s_waitcnt lgkmcnt(6)
	ds_read_b128 v[72:75], v0 offset:37632
	ds_read_b128 v[76:79], v0 offset:37888
	ds_read_b128 v[80:83], v0 offset:38144
	ds_read_b128 v[84:87], v0 offset:38400
	ds_read_b32 v92, v12 offset:37632
	ds_read_b128 v[88:91], v0 offset:38656
	v_pk_mul_f32 v[6:7], v[2:3], v[94:95]
	v_pk_mul_f32 v[8:9], v[2:3], v[98:99]
	v_pk_fma_f32 v[6:7], v[4:5], v[96:97], v[6:7]
	v_pk_fma_f32 v[8:9], v[4:5], v[100:101], v[8:9]
	v_add_f32_e32 v10, v6, v7
	v_add_f32_e32 v35, v8, v9
	v_pk_mul_f32 v[2:3], v[2:3], v[102:103]
	v_add_f32_dpp v10, v10, v10 quad_perm:[1,0,3,2] row_mask:0xf bank_mask:0xf bound_ctrl:1
	v_pk_mul_f32 v[4:5], v[4:5], v[104:105]
	v_pk_fma_f32 v[2:3], v[106:107], v[114:115], v[2:3] op_sel_hi:[1,0,1]
	v_add_f32_dpp v10, v10, v10 quad_perm:[2,3,0,1] row_mask:0xf bank_mask:0xf bound_ctrl:1
	v_pk_fma_f32 v[4:5], v[108:109], v[114:115], v[4:5] op_sel_hi:[1,0,1]
	v_add_f32_dpp v62, v22, v22 row_half_mirror row_mask:0xf bank_mask:0xf bound_ctrl:1
	v_add_f32_dpp v10, v10, v10 row_half_mirror row_mask:0xf bank_mask:0xf bound_ctrl:1
	v_add_f32_dpp v63, v23, v23 row_half_mirror row_mask:0xf bank_mask:0xf bound_ctrl:1
	v_cndmask_b32_e64 v51, v62, v63, s[10:11]
	v_add_f32_dpp v10, v10, v10 row_mirror row_mask:0xf bank_mask:0xf bound_ctrl:1
	v_pk_fma_f32 v[2:3], v[110:111], v[10:11], v[2:3] op_sel_hi:[1,0,1]
	v_pk_fma_f32 v[4:5], v[112:113], v[10:11], v[4:5] op_sel_hi:[1,0,1]
	s_waitcnt lgkmcnt(6)
	ds_read_b128 v[94:97], v0 offset:39424
	ds_read_b128 v[98:101], v0 offset:39680
	ds_read_b128 v[102:105], v0 offset:39936
	ds_read_b128 v[106:109], v0 offset:40192
	ds_read_b32 v114, v12 offset:39424
	ds_read_b128 v[110:113], v0 offset:40448
	v_pk_mul_f32 v[6:7], v[2:3], v[116:117]
	v_pk_mul_f32 v[8:9], v[2:3], v[120:121]
	v_pk_fma_f32 v[6:7], v[4:5], v[118:119], v[6:7]
	v_pk_fma_f32 v[8:9], v[4:5], v[122:123], v[8:9]
	v_add_f32_e32 v10, v6, v7
	v_add_f32_e32 v36, v8, v9
	v_pk_mul_f32 v[2:3], v[2:3], v[124:125]
	v_add_f32_dpp v10, v10, v10 quad_perm:[1,0,3,2] row_mask:0xf bank_mask:0xf bound_ctrl:1
	v_pk_mul_f32 v[4:5], v[4:5], v[126:127]
	v_pk_fma_f32 v[2:3], v[128:129], v[140:141], v[2:3] op_sel_hi:[1,0,1]
	v_add_f32_dpp v10, v10, v10 quad_perm:[2,3,0,1] row_mask:0xf bank_mask:0xf bound_ctrl:1
	v_pk_fma_f32 v[4:5], v[130:131], v[140:141], v[4:5] op_sel_hi:[1,0,1]
	v_add_f32_dpp v62, v24, v24 row_half_mirror row_mask:0xf bank_mask:0xf bound_ctrl:1
	v_add_f32_dpp v10, v10, v10 row_half_mirror row_mask:0xf bank_mask:0xf bound_ctrl:1
	v_add_f32_dpp v63, v25, v25 row_half_mirror row_mask:0xf bank_mask:0xf bound_ctrl:1
	v_cndmask_b32_e64 v52, v62, v63, s[10:11]
	v_add_f32_dpp v10, v10, v10 row_mirror row_mask:0xf bank_mask:0xf bound_ctrl:1
	v_pk_fma_f32 v[2:3], v[132:133], v[10:11], v[2:3] op_sel_hi:[1,0,1]
	v_pk_fma_f32 v[4:5], v[134:135], v[10:11], v[4:5] op_sel_hi:[1,0,1]
	s_waitcnt lgkmcnt(6)
	ds_read_b128 v[116:119], v0 offset:41216
	ds_read_b128 v[120:123], v0 offset:41472
	ds_read_b128 v[124:127], v0 offset:41728
	ds_read_b128 v[128:131], v0 offset:41984
	ds_read_b32 v140, v12 offset:41216
	ds_read_b128 v[132:135], v0 offset:42240
	v_pk_mul_f32 v[6:7], v[2:3], v[72:73]
	v_pk_mul_f32 v[8:9], v[2:3], v[76:77]
	v_pk_fma_f32 v[6:7], v[4:5], v[74:75], v[6:7]
	v_pk_fma_f32 v[8:9], v[4:5], v[78:79], v[8:9]
	v_add_f32_e32 v10, v6, v7
	v_add_f32_e32 v37, v8, v9
	v_pk_mul_f32 v[2:3], v[2:3], v[80:81]
	v_add_f32_dpp v10, v10, v10 quad_perm:[1,0,3,2] row_mask:0xf bank_mask:0xf bound_ctrl:1
	v_pk_mul_f32 v[4:5], v[4:5], v[82:83]
	v_pk_fma_f32 v[2:3], v[84:85], v[92:93], v[2:3] op_sel_hi:[1,0,1]
	v_add_f32_dpp v10, v10, v10 quad_perm:[2,3,0,1] row_mask:0xf bank_mask:0xf bound_ctrl:1
	v_pk_fma_f32 v[4:5], v[86:87], v[92:93], v[4:5] op_sel_hi:[1,0,1]
	v_add_f32_dpp v62, v26, v26 row_half_mirror row_mask:0xf bank_mask:0xf bound_ctrl:1
	v_add_f32_dpp v10, v10, v10 row_half_mirror row_mask:0xf bank_mask:0xf bound_ctrl:1
	v_add_f32_dpp v63, v27, v27 row_half_mirror row_mask:0xf bank_mask:0xf bound_ctrl:1
	v_cndmask_b32_e64 v53, v62, v63, s[10:11]
	v_add_f32_dpp v10, v10, v10 row_mirror row_mask:0xf bank_mask:0xf bound_ctrl:1
	v_pk_fma_f32 v[2:3], v[88:89], v[10:11], v[2:3] op_sel_hi:[1,0,1]
	v_pk_fma_f32 v[4:5], v[90:91], v[10:11], v[4:5] op_sel_hi:[1,0,1]
	s_waitcnt lgkmcnt(6)
; __device__ __forceinline__ f32x2 pkmul_(f32x2 a, f32x2 b) { f32x2 d; asm("v_pk_mul_f32 %0, %1, %2" : "=v"(d) : "v"(a), "v"(b)); return d; }
; __device__ __forceinline__ f32x2 pkfma_(f32x2 a, f32x2 b, f32x2 c) { f32x2 d; asm("v_pk_fma_f32 %0, %1, %2, %3" : "=v"(d) : "v"(a), "v"(b), "v"(c)); return d; }
; __device__ __forceinline__ f32x2 pkfma_b(f32x2 a, f32x2 s, f32x2 c) { f32x2 d; asm("v_pk_fma_f32 %0, %1, %2, %3 op_sel_hi:[1,0,1]" : "=v"(d) : "v"(a), "v"(s), "v"(c)); return d; }
; __device__ __forceinline__ f32x2 lo2(f32x4 v) { return __builtin_shufflevector(v, v, 0, 1); }
; __device__ __forceinline__ f32x2 hi2(f32x4 v) { return __builtin_shufflevector(v, v, 2, 3); }
; __device__ __forceinline__ float red8(float x) { x += dpp_<0x141>(x); x += dpp_<0xB1>(x); x += dpp_<0x4E>(x); return x; }
; __global__ void __launch_bounds__(NTHR) hymba_fwd(Params P) {
;     ...
;                     for (int st = 0; st < TB; ++st) {
;                         if (st + 2 < TB) LDSTEP((st + 2) * REC, nav0, nav1, nbv0, nbv1, ndw0, ndw1, nkt0, nkt1, nwr0, nwr1, nvv, nsc);
;                         __builtin_amdgcn_sched_barrier(0);
;                         const f32x2 pa = pkfma_(S2[3], hi2(a1), pkfma_(S2[2], lo2(a1), pkfma_(S2[1], hi2(a0), pkmul_(S2[0], lo2(a0)))));
;                         const f32x2 py = pkfma_(S2[3], hi2(w1_), pkfma_(S2[2], lo2(w1_), pkfma_(S2[1], hi2(w0_), pkmul_(S2[0], lo2(w0_)))));
;                         float da = pa[0] + pa[1], dy = py[0] + py[1];
;                         da = red8(da); dy = red8(dy);
;                         const float y = dy + da * sc_[0] + vv_ * sc_[1];
;                         { f32x2 dab, vvb; dab[0] = da; dab[1] = da; vvb[0] = vv_; vvb[1] = vv_;
;                           S2[0] = pkfma_b(lo2(k0), vvb, pkfma_b(lo2(b0), dab, pkmul_(S2[0], lo2(d0)))); S2[1] = pkfma_b(hi2(k0), vvb, pkfma_b(hi2(b0), dab, pkmul_(S2[1], hi2(d0))));
;                           S2[2] = pkfma_b(lo2(k1), vvb, pkfma_b(lo2(b1), dab, pkmul_(S2[2], lo2(d1)))); S2[3] = pkfma_b(hi2(k1), vvb, pkfma_b(hi2(b1), dab, pkmul_(S2[3], hi2(d1)))); }
;                         const float sh = __int_as_float(__builtin_amdgcn_update_dpp(__float_as_int(y), __float_as_int(yacc), 0x111, 0xF, 0xF, false));
;                         yacc = first8 ? y : sh;
;                         if ((st & 7) == 7) yp[(size_t)(blk * TB + (st - 7)) * CW] = yacc;
	ds_read_b128 v[72:75], v0 offset:43008
	ds_read_b128 v[76:79], v0 offset:43264
	ds_read_b128 v[80:83], v0 offset:43520
	ds_read_b128 v[84:87], v0 offset:43776
	ds_read_b32 v92, v12 offset:43008
	ds_read_b128 v[88:91], v0 offset:44032
	v_pk_mul_f32 v[6:7], v[2:3], v[94:95]
	v_pk_mul_f32 v[8:9], v[2:3], v[98:99]
	v_pk_fma_f32 v[6:7], v[4:5], v[96:97], v[6:7]
	v_pk_fma_f32 v[8:9], v[4:5], v[100:101], v[8:9]
	v_add_f32_e32 v10, v6, v7
	v_add_f32_e32 v38, v8, v9
	v_pk_mul_f32 v[2:3], v[2:3], v[102:103]
	v_add_f32_dpp v10, v10, v10 quad_perm:[1,0,3,2] row_mask:0xf bank_mask:0xf bound_ctrl:1
	v_pk_mul_f32 v[4:5], v[4:5], v[104:105]
	v_pk_fma_f32 v[2:3], v[106:107], v[114:115], v[2:3] op_sel_hi:[1,0,1]
	v_add_f32_dpp v10, v10, v10 quad_perm:[2,3,0,1] row_mask:0xf bank_mask:0xf bound_ctrl:1
	v_pk_fma_f32 v[4:5], v[108:109], v[114:115], v[4:5] op_sel_hi:[1,0,1]
	v_add_f32_dpp v62, v28, v28 row_half_mirror row_mask:0xf bank_mask:0xf bound_ctrl:1
	v_add_f32_dpp v10, v10, v10 row_half_mirror row_mask:0xf bank_mask:0xf bound_ctrl:1
	v_add_f32_dpp v63, v29, v29 row_half_mirror row_mask:0xf bank_mask:0xf bound_ctrl:1
	v_cndmask_b32_e64 v54, v62, v63, s[10:11]
	v_add_f32_dpp v10, v10, v10 row_mirror row_mask:0xf bank_mask:0xf bound_ctrl:1
	v_pk_fma_f32 v[2:3], v[110:111], v[10:11], v[2:3] op_sel_hi:[1,0,1]
	v_pk_fma_f32 v[4:5], v[112:113], v[10:11], v[4:5] op_sel_hi:[1,0,1]
	s_waitcnt lgkmcnt(6)
	ds_read_b128 v[94:97], v0 offset:44800
	ds_read_b128 v[98:101], v0 offset:45056
	ds_read_b128 v[102:105], v0 offset:45312
	ds_read_b128 v[106:109], v0 offset:45568
	ds_read_b32 v114, v12 offset:44800
	ds_read_b128 v[110:113], v0 offset:45824
	v_pk_mul_f32 v[6:7], v[2:3], v[116:117]
	v_pk_mul_f32 v[8:9], v[2:3], v[120:121]
	v_pk_fma_f32 v[6:7], v[4:5], v[118:119], v[6:7]
	v_pk_fma_f32 v[8:9], v[4:5], v[122:123], v[8:9]
	v_add_f32_e32 v10, v6, v7
	v_add_f32_e32 v39, v8, v9
	v_pk_mul_f32 v[2:3], v[2:3], v[124:125]
	v_add_f32_dpp v10, v10, v10 quad_perm:[1,0,3,2] row_mask:0xf bank_mask:0xf bound_ctrl:1
	v_pk_mul_f32 v[4:5], v[4:5], v[126:127]
	v_pk_fma_f32 v[2:3], v[128:129], v[140:141], v[2:3] op_sel_hi:[1,0,1]
	v_add_f32_dpp v10, v10, v10 quad_perm:[2,3,0,1] row_mask:0xf bank_mask:0xf bound_ctrl:1
	v_pk_fma_f32 v[4:5], v[130:131], v[140:141], v[4:5] op_sel_hi:[1,0,1]
	v_add_f32_dpp v62, v30, v30 row_half_mirror row_mask:0xf bank_mask:0xf bound_ctrl:1
	v_add_f32_dpp v10, v10, v10 row_half_mirror row_mask:0xf bank_mask:0xf bound_ctrl:1
	v_add_f32_dpp v63, v31, v31 row_half_mirror row_mask:0xf bank_mask:0xf bound_ctrl:1
	v_cndmask_b32_e64 v55, v62, v63, s[10:11]
	v_add_f32_dpp v10, v10, v10 row_mirror row_mask:0xf bank_mask:0xf bound_ctrl:1
	v_pk_fma_f32 v[2:3], v[132:133], v[10:11], v[2:3] op_sel_hi:[1,0,1]
	v_pk_fma_f32 v[4:5], v[134:135], v[10:11], v[4:5] op_sel_hi:[1,0,1]
	s_waitcnt lgkmcnt(6)
	ds_read_b128 v[116:119], v0 offset:46592
	ds_read_b128 v[120:123], v0 offset:46848
	ds_read_b128 v[124:127], v0 offset:47104
	ds_read_b128 v[128:131], v0 offset:47360
	ds_read_b32 v140, v12 offset:46592
	ds_read_b128 v[132:135], v0 offset:47616
	v_pk_mul_f32 v[6:7], v[2:3], v[72:73]
	v_pk_mul_f32 v[8:9], v[2:3], v[76:77]
	v_pk_fma_f32 v[6:7], v[4:5], v[74:75], v[6:7]
	v_pk_fma_f32 v[8:9], v[4:5], v[78:79], v[8:9]
	v_add_f32_e32 v10, v6, v7
	v_add_f32_e32 v40, v8, v9
	v_pk_mul_f32 v[2:3], v[2:3], v[80:81]
	v_add_f32_dpp v10, v10, v10 quad_perm:[1,0,3,2] row_mask:0xf bank_mask:0xf bound_ctrl:1
	v_pk_mul_f32 v[4:5], v[4:5], v[82:83]
	v_pk_fma_f32 v[2:3], v[84:85], v[92:93], v[2:3] op_sel_hi:[1,0,1]
	v_add_f32_dpp v10, v10, v10 quad_perm:[2,3,0,1] row_mask:0xf bank_mask:0xf bound_ctrl:1
	v_pk_fma_f32 v[4:5], v[86:87], v[92:93], v[4:5] op_sel_hi:[1,0,1]
	v_add_f32_dpp v62, v48, v48 quad_perm:[1,0,3,2] row_mask:0xf bank_mask:0xf bound_ctrl:1
	v_add_f32_dpp v10, v10, v10 row_half_mirror row_mask:0xf bank_mask:0xf bound_ctrl:1
	v_add_f32_dpp v63, v49, v49 quad_perm:[1,0,3,2] row_mask:0xf bank_mask:0xf bound_ctrl:1
	v_cndmask_b32_e64 v56, v62, v63, s[22:23]
	v_add_f32_dpp v10, v10, v10 row_mirror row_mask:0xf bank_mask:0xf bound_ctrl:1
	v_pk_fma_f32 v[2:3], v[88:89], v[10:11], v[2:3] op_sel_hi:[1,0,1]
	v_pk_fma_f32 v[4:5], v[90:91], v[10:11], v[4:5] op_sel_hi:[1,0,1]
	s_waitcnt lgkmcnt(6)
	ds_read_b128 v[72:75], v0 offset:48384
	ds_read_b128 v[76:79], v0 offset:48640
	ds_read_b128 v[80:83], v0 offset:48896
	ds_read_b128 v[84:87], v0 offset:49152
	ds_read_b32 v92, v12 offset:48384
	ds_read_b128 v[88:91], v0 offset:49408
	v_pk_mul_f32 v[6:7], v[2:3], v[94:95]
	v_pk_mul_f32 v[8:9], v[2:3], v[98:99]
	v_pk_fma_f32 v[6:7], v[4:5], v[96:97], v[6:7]
	v_pk_fma_f32 v[8:9], v[4:5], v[100:101], v[8:9]
	v_add_f32_e32 v10, v6, v7
	v_add_f32_e32 v41, v8, v9
	v_pk_mul_f32 v[2:3], v[2:3], v[102:103]
	v_add_f32_dpp v10, v10, v10 quad_perm:[1,0,3,2] row_mask:0xf bank_mask:0xf bound_ctrl:1
	v_pk_mul_f32 v[4:5], v[4:5], v[104:105]
	v_pk_fma_f32 v[2:3], v[106:107], v[114:115], v[2:3] op_sel_hi:[1,0,1]
	v_add_f32_dpp v10, v10, v10 quad_perm:[2,3,0,1] row_mask:0xf bank_mask:0xf bound_ctrl:1
	v_pk_fma_f32 v[4:5], v[108:109], v[114:115], v[4:5] op_sel_hi:[1,0,1]
	v_add_f32_dpp v62, v50, v50 quad_perm:[1,0,3,2] row_mask:0xf bank_mask:0xf bound_ctrl:1
	v_add_f32_dpp v10, v10, v10 row_half_mirror row_mask:0xf bank_mask:0xf bound_ctrl:1
	v_add_f32_dpp v63, v51, v51 quad_perm:[1,0,3,2] row_mask:0xf bank_mask:0xf bound_ctrl:1
	v_cndmask_b32_e64 v57, v62, v63, s[22:23]
	v_add_f32_dpp v10, v10, v10 row_mirror row_mask:0xf bank_mask:0xf bound_ctrl:1
	v_pk_fma_f32 v[2:3], v[110:111], v[10:11], v[2:3] op_sel_hi:[1,0,1]
	v_pk_fma_f32 v[4:5], v[112:113], v[10:11], v[4:5] op_sel_hi:[1,0,1]
	s_waitcnt lgkmcnt(6)
; __device__ __forceinline__ f32x2 pkmul_(f32x2 a, f32x2 b) { f32x2 d; asm("v_pk_mul_f32 %0, %1, %2" : "=v"(d) : "v"(a), "v"(b)); return d; }
; __device__ __forceinline__ f32x2 pkfma_(f32x2 a, f32x2 b, f32x2 c) { f32x2 d; asm("v_pk_fma_f32 %0, %1, %2, %3" : "=v"(d) : "v"(a), "v"(b), "v"(c)); return d; }
; __device__ __forceinline__ f32x2 pkfma_b(f32x2 a, f32x2 s, f32x2 c) { f32x2 d; asm("v_pk_fma_f32 %0, %1, %2, %3 op_sel_hi:[1,0,1]" : "=v"(d) : "v"(a), "v"(s), "v"(c)); return d; }
; __device__ __forceinline__ f32x2 lo2(f32x4 v) { return __builtin_shufflevector(v, v, 0, 1); }
; __device__ __forceinline__ f32x2 hi2(f32x4 v) { return __builtin_shufflevector(v, v, 2, 3); }
; __device__ __forceinline__ float red8(float x) { x += dpp_<0x141>(x); x += dpp_<0xB1>(x); x += dpp_<0x4E>(x); return x; }
; __global__ void __launch_bounds__(NTHR) hymba_fwd(Params P) {
;     ...
;                     for (int st = 0; st < TB; ++st) {
;                         if (st + 2 < TB) LDSTEP((st + 2) * REC, nav0, nav1, nbv0, nbv1, ndw0, ndw1, nkt0, nkt1, nwr0, nwr1, nvv, nsc);
;                         __builtin_amdgcn_sched_barrier(0);
;                         const f32x2 pa = pkfma_(S2[3], hi2(a1), pkfma_(S2[2], lo2(a1), pkfma_(S2[1], hi2(a0), pkmul_(S2[0], lo2(a0)))));
;                         const f32x2 py = pkfma_(S2[3], hi2(w1_), pkfma_(S2[2], lo2(w1_), pkfma_(S2[1], hi2(w0_), pkmul_(S2[0], lo2(w0_)))));
;                         float da = pa[0] + pa[1], dy = py[0] + py[1];
;                         da = red8(da); dy = red8(dy);
;                         const float y = dy + da * sc_[0] + vv_ * sc_[1];
;                         { f32x2 dab, vvb; dab[0] = da; dab[1] = da; vvb[0] = vv_; vvb[1] = vv_;
;                           S2[0] = pkfma_b(lo2(k0), vvb, pkfma_b(lo2(b0), dab, pkmul_(S2[0], lo2(d0)))); S2[1] = pkfma_b(hi2(k0), vvb, pkfma_b(hi2(b0), dab, pkmul_(S2[1], hi2(d0))));
;                           S2[2] = pkfma_b(lo2(k1), vvb, pkfma_b(lo2(b1), dab, pkmul_(S2[2], lo2(d1)))); S2[3] = pkfma_b(hi2(k1), vvb, pkfma_b(hi2(b1), dab, pkmul_(S2[3], hi2(d1)))); }
;                         const float sh = __int_as_float(__builtin_amdgcn_update_dpp(__float_as_int(y), __float_as_int(yacc), 0x111, 0xF, 0xF, false));
;                         yacc = first8 ? y : sh;
;                         if ((st & 7) == 7) yp[(size_t)(blk * TB + (st - 7)) * CW] = yacc;
	ds_read_b128 v[94:97], v0 offset:50176
	ds_read_b128 v[98:101], v0 offset:50432
	ds_read_b128 v[102:105], v0 offset:50688
	ds_read_b128 v[106:109], v0 offset:50944
	ds_read_b32 v114, v12 offset:50176
	ds_read_b128 v[110:113], v0 offset:51200
	v_pk_mul_f32 v[6:7], v[2:3], v[116:117]
	v_pk_mul_f32 v[8:9], v[2:3], v[120:121]
	v_pk_fma_f32 v[6:7], v[4:5], v[118:119], v[6:7]
	v_pk_fma_f32 v[8:9], v[4:5], v[122:123], v[8:9]
	v_add_f32_e32 v10, v6, v7
	v_add_f32_e32 v42, v8, v9
	v_pk_mul_f32 v[2:3], v[2:3], v[124:125]
	v_add_f32_dpp v10, v10, v10 quad_perm:[1,0,3,2] row_mask:0xf bank_mask:0xf bound_ctrl:1
	v_pk_mul_f32 v[4:5], v[4:5], v[126:127]
	v_pk_fma_f32 v[2:3], v[128:129], v[140:141], v[2:3] op_sel_hi:[1,0,1]
	v_add_f32_dpp v10, v10, v10 quad_perm:[2,3,0,1] row_mask:0xf bank_mask:0xf bound_ctrl:1
	v_pk_fma_f32 v[4:5], v[130:131], v[140:141], v[4:5] op_sel_hi:[1,0,1]
	v_add_f32_dpp v62, v52, v52 quad_perm:[1,0,3,2] row_mask:0xf bank_mask:0xf bound_ctrl:1
	v_add_f32_dpp v10, v10, v10 row_half_mirror row_mask:0xf bank_mask:0xf bound_ctrl:1
	v_add_f32_dpp v63, v53, v53 quad_perm:[1,0,3,2] row_mask:0xf bank_mask:0xf bound_ctrl:1
	v_cndmask_b32_e64 v58, v62, v63, s[22:23]
	v_add_f32_dpp v10, v10, v10 row_mirror row_mask:0xf bank_mask:0xf bound_ctrl:1
	v_pk_fma_f32 v[2:3], v[132:133], v[10:11], v[2:3] op_sel_hi:[1,0,1]
	v_pk_fma_f32 v[4:5], v[134:135], v[10:11], v[4:5] op_sel_hi:[1,0,1]
	s_waitcnt lgkmcnt(6)
	ds_read_b128 v[116:119], v0 offset:51968
	ds_read_b128 v[120:123], v0 offset:52224
	ds_read_b128 v[124:127], v0 offset:52480
	ds_read_b128 v[128:131], v0 offset:52736
	ds_read_b32 v140, v12 offset:51968
	ds_read_b128 v[132:135], v0 offset:52992
	v_pk_mul_f32 v[6:7], v[2:3], v[72:73]
	v_pk_mul_f32 v[8:9], v[2:3], v[76:77]
	v_pk_fma_f32 v[6:7], v[4:5], v[74:75], v[6:7]
	v_pk_fma_f32 v[8:9], v[4:5], v[78:79], v[8:9]
	v_add_f32_e32 v10, v6, v7
	v_add_f32_e32 v43, v8, v9
	v_pk_mul_f32 v[2:3], v[2:3], v[80:81]
	v_add_f32_dpp v10, v10, v10 quad_perm:[1,0,3,2] row_mask:0xf bank_mask:0xf bound_ctrl:1
	v_pk_mul_f32 v[4:5], v[4:5], v[82:83]
	v_pk_fma_f32 v[2:3], v[84:85], v[92:93], v[2:3] op_sel_hi:[1,0,1]
	v_add_f32_dpp v10, v10, v10 quad_perm:[2,3,0,1] row_mask:0xf bank_mask:0xf bound_ctrl:1
	v_pk_fma_f32 v[4:5], v[86:87], v[92:93], v[4:5] op_sel_hi:[1,0,1]
	v_add_f32_dpp v62, v54, v54 quad_perm:[1,0,3,2] row_mask:0xf bank_mask:0xf bound_ctrl:1
	v_add_f32_dpp v10, v10, v10 row_half_mirror row_mask:0xf bank_mask:0xf bound_ctrl:1
	v_add_f32_dpp v63, v55, v55 quad_perm:[1,0,3,2] row_mask:0xf bank_mask:0xf bound_ctrl:1
	v_cndmask_b32_e64 v59, v62, v63, s[22:23]
	v_add_f32_dpp v10, v10, v10 row_mirror row_mask:0xf bank_mask:0xf bound_ctrl:1
	v_pk_fma_f32 v[2:3], v[88:89], v[10:11], v[2:3] op_sel_hi:[1,0,1]
	v_pk_fma_f32 v[4:5], v[90:91], v[10:11], v[4:5] op_sel_hi:[1,0,1]
	s_waitcnt lgkmcnt(6)
	ds_read_b128 v[72:75], v0 offset:53760
	ds_read_b128 v[76:79], v0 offset:54016
	ds_read_b128 v[80:83], v0 offset:54272
	ds_read_b128 v[84:87], v0 offset:54528
	ds_read_b32 v92, v12 offset:53760
	ds_read_b128 v[88:91], v0 offset:54784
	v_pk_mul_f32 v[6:7], v[2:3], v[94:95]
	v_pk_mul_f32 v[8:9], v[2:3], v[98:99]
	v_pk_fma_f32 v[6:7], v[4:5], v[96:97], v[6:7]
	v_pk_fma_f32 v[8:9], v[4:5], v[100:101], v[8:9]
	v_add_f32_e32 v10, v6, v7
	v_add_f32_e32 v44, v8, v9
	v_pk_mul_f32 v[2:3], v[2:3], v[102:103]
	v_add_f32_dpp v10, v10, v10 quad_perm:[1,0,3,2] row_mask:0xf bank_mask:0xf bound_ctrl:1
	v_pk_mul_f32 v[4:5], v[4:5], v[104:105]
	v_pk_fma_f32 v[2:3], v[106:107], v[114:115], v[2:3] op_sel_hi:[1,0,1]
	v_add_f32_dpp v10, v10, v10 quad_perm:[2,3,0,1] row_mask:0xf bank_mask:0xf bound_ctrl:1
	v_pk_fma_f32 v[4:5], v[108:109], v[114:115], v[4:5] op_sel_hi:[1,0,1]
	v_add_f32_dpp v62, v56, v56 quad_perm:[2,3,0,1] row_mask:0xf bank_mask:0xf bound_ctrl:1
	v_add_f32_dpp v10, v10, v10 row_half_mirror row_mask:0xf bank_mask:0xf bound_ctrl:1
	v_add_f32_dpp v63, v57, v57 quad_perm:[2,3,0,1] row_mask:0xf bank_mask:0xf bound_ctrl:1
	v_cndmask_b32_e64 v60, v62, v63, s[26:27]
	v_add_f32_dpp v10, v10, v10 row_mirror row_mask:0xf bank_mask:0xf bound_ctrl:1
	v_pk_fma_f32 v[2:3], v[110:111], v[10:11], v[2:3] op_sel_hi:[1,0,1]
	v_pk_fma_f32 v[4:5], v[112:113], v[10:11], v[4:5] op_sel_hi:[1,0,1]
	s_waitcnt lgkmcnt(6)
	ds_read_b128 v[94:97], v0 offset:55552
	ds_read_b128 v[98:101], v0 offset:55808
	ds_read_b128 v[102:105], v0 offset:56064
	ds_read_b128 v[106:109], v0 offset:56320
	ds_read_b32 v114, v12 offset:55552
	ds_read_b128 v[110:113], v0 offset:56576
	v_pk_mul_f32 v[6:7], v[2:3], v[116:117]
	v_pk_mul_f32 v[8:9], v[2:3], v[120:121]
	v_pk_fma_f32 v[6:7], v[4:5], v[118:119], v[6:7]
	v_pk_fma_f32 v[8:9], v[4:5], v[122:123], v[8:9]
	v_add_f32_e32 v10, v6, v7
	v_add_f32_e32 v45, v8, v9
	v_pk_mul_f32 v[2:3], v[2:3], v[124:125]
	v_add_f32_dpp v10, v10, v10 quad_perm:[1,0,3,2] row_mask:0xf bank_mask:0xf bound_ctrl:1
	v_pk_mul_f32 v[4:5], v[4:5], v[126:127]
	v_pk_fma_f32 v[2:3], v[128:129], v[140:141], v[2:3] op_sel_hi:[1,0,1]
	v_add_f32_dpp v10, v10, v10 quad_perm:[2,3,0,1] row_mask:0xf bank_mask:0xf bound_ctrl:1
	v_pk_fma_f32 v[4:5], v[130:131], v[140:141], v[4:5] op_sel_hi:[1,0,1]
	v_add_f32_dpp v62, v58, v58 quad_perm:[2,3,0,1] row_mask:0xf bank_mask:0xf bound_ctrl:1
	v_add_f32_dpp v10, v10, v10 row_half_mirror row_mask:0xf bank_mask:0xf bound_ctrl:1
	v_add_f32_dpp v63, v59, v59 quad_perm:[2,3,0,1] row_mask:0xf bank_mask:0xf bound_ctrl:1
	v_cndmask_b32_e64 v61, v62, v63, s[26:27]
	v_add_f32_dpp v10, v10, v10 row_mirror row_mask:0xf bank_mask:0xf bound_ctrl:1
	v_pk_fma_f32 v[2:3], v[132:133], v[10:11], v[2:3] op_sel_hi:[1,0,1]
	v_pk_fma_f32 v[4:5], v[134:135], v[10:11], v[4:5] op_sel_hi:[1,0,1]
	s_waitcnt lgkmcnt(6)
; __global__ void __launch_bounds__(NTHR) hymba_fwd(Params P) {
;     ...
;                     for (int st = 0; st < TB; ++st) {
;                         if (st + 2 < TB) LDSTEP((st + 2) * REC, nav0, nav1, nbv0, nbv1, ndw0, ndw1, nkt0, nkt1, nwr0, nwr1, nvv, nsc);
;                         __builtin_amdgcn_sched_barrier(0);
;                         const f32x2 pa = pkfma_(S2[3], hi2(a1), pkfma_(S2[2], lo2(a1), pkfma_(S2[1], hi2(a0), pkmul_(S2[0], lo2(a0)))));
;                         const f32x2 py = pkfma_(S2[3], hi2(w1_), pkfma_(S2[2], lo2(w1_), pkfma_(S2[1], hi2(w0_), pkmul_(S2[0], lo2(w0_)))));
;                         float da = pa[0] + pa[1], dy = py[0] + py[1];
;                         da = red8(da); dy = red8(dy);
;                         const float y = dy + da * sc_[0] + vv_ * sc_[1];
;                         { f32x2 dab, vvb; dab[0] = da; dab[1] = da; vvb[0] = vv_; vvb[1] = vv_;
;                           S2[0] = pkfma_b(lo2(k0), vvb, pkfma_b(lo2(b0), dab, pkmul_(S2[0], lo2(d0)))); S2[1] = pkfma_b(hi2(k0), vvb, pkfma_b(hi2(b0), dab, pkmul_(S2[1], hi2(d0))));
;                           S2[2] = pkfma_b(lo2(k1), vvb, pkfma_b(lo2(b1), dab, pkmul_(S2[2], lo2(d1)))); S2[3] = pkfma_b(hi2(k1), vvb, pkfma_b(hi2(b1), dab, pkmul_(S2[3], hi2(d1)))); }
;                         const float sh = __int_as_float(__builtin_amdgcn_update_dpp(__float_as_int(y), __float_as_int(yacc), 0x111, 0xF, 0xF, false));
;                         yacc = first8 ? y : sh;
;                         if ((st & 7) == 7) yp[(size_t)(blk * TB + (st - 7)) * CW] = yacc;
;                         a0 = av0; a1 = av1; b0 = bv0; b1 = bv1; d0 = dw0; d1 = dw1; k0 = kt0; k1 = kt1; w0_ = wr0; w1_ = wr1; vv_ = vv; sc_ = sc;
;                         av0 = nav0; av1 = nav1; bv0 = nbv0; bv1 = nbv1; dw0 = ndw0; dw1 = ndw1; kt0 = nkt0; kt1 = nkt1; wr0 = nwr0; wr1 = nwr1; vv = nvv; sc = nsc;
;                         asm volatile("" ::: "memory");
;                     }
;     ...
;                     WG_BAR();
;               }
;               __builtin_amdgcn_s_setprio(0);
;               float* so = out + OUT_WKVP + ((size_t)(b * NH + h) * 64 + q * 16 + crow) * 64 + kq * 8;
;               *(f32x4*)so = (f32x4){S2[0][0], S2[0][1], S2[1][0], S2[1][1]}; *(f32x4*)(so + 4) = (f32x4){S2[2][0], S2[2][1], S2[3][0], S2[3][1]};
	v_pk_mul_f32 v[6:7], v[2:3], v[72:73]
	v_pk_mul_f32 v[8:9], v[2:3], v[76:77]
	v_pk_fma_f32 v[6:7], v[4:5], v[74:75], v[6:7]
	v_pk_fma_f32 v[8:9], v[4:5], v[78:79], v[8:9]
	v_add_f32_e32 v10, v6, v7
	v_add_f32_e32 v46, v8, v9
	v_pk_mul_f32 v[2:3], v[2:3], v[80:81]
	v_add_f32_dpp v10, v10, v10 quad_perm:[1,0,3,2] row_mask:0xf bank_mask:0xf bound_ctrl:1
	v_pk_mul_f32 v[4:5], v[4:5], v[82:83]
	v_pk_fma_f32 v[2:3], v[84:85], v[92:93], v[2:3] op_sel_hi:[1,0,1]
	v_add_f32_dpp v10, v10, v10 quad_perm:[2,3,0,1] row_mask:0xf bank_mask:0xf bound_ctrl:1
	v_pk_fma_f32 v[4:5], v[86:87], v[92:93], v[4:5] op_sel_hi:[1,0,1]
	v_add_f32_dpp v62, v60, v60 row_mirror row_mask:0xf bank_mask:0xf bound_ctrl:1
	v_add_f32_dpp v10, v10, v10 row_half_mirror row_mask:0xf bank_mask:0xf bound_ctrl:1
	v_add_f32_dpp v63, v61, v61 row_mirror row_mask:0xf bank_mask:0xf bound_ctrl:1
	v_cndmask_b32_e64 v64, v62, v63, s[56:57]
	v_add_f32_dpp v10, v10, v10 row_mirror row_mask:0xf bank_mask:0xf bound_ctrl:1
	v_pk_fma_f32 v[2:3], v[88:89], v[10:11], v[2:3] op_sel_hi:[1,0,1]
	v_pk_fma_f32 v[4:5], v[90:91], v[10:11], v[4:5] op_sel_hi:[1,0,1]
	s_waitcnt lgkmcnt(0)
	v_pk_mul_f32 v[6:7], v[2:3], v[94:95]
	v_pk_mul_f32 v[8:9], v[2:3], v[98:99]
	v_pk_fma_f32 v[6:7], v[4:5], v[96:97], v[6:7]
	v_pk_fma_f32 v[8:9], v[4:5], v[100:101], v[8:9]
	v_add_f32_e32 v10, v6, v7
	v_add_f32_e32 v47, v8, v9
	v_pk_mul_f32 v[2:3], v[2:3], v[102:103]
	v_add_f32_dpp v10, v10, v10 quad_perm:[1,0,3,2] row_mask:0xf bank_mask:0xf bound_ctrl:1
	v_pk_mul_f32 v[4:5], v[4:5], v[104:105]
	v_pk_fma_f32 v[2:3], v[106:107], v[114:115], v[2:3] op_sel_hi:[1,0,1]
	v_add_f32_dpp v10, v10, v10 quad_perm:[2,3,0,1] row_mask:0xf bank_mask:0xf bound_ctrl:1
	v_pk_fma_f32 v[4:5], v[108:109], v[114:115], v[4:5] op_sel_hi:[1,0,1]
	v_add_f32_e32 v64, v64, v65
	v_add_f32_dpp v10, v10, v10 row_half_mirror row_mask:0xf bank_mask:0xf bound_ctrl:1
	global_store_dword v14, v64, s[8:9]
	s_add_u32 s8, s8, 0x10000
	s_addc_u32 s9, s9, 0
	v_add_f32_dpp v10, v10, v10 row_mirror row_mask:0xf bank_mask:0xf bound_ctrl:1
	v_pk_fma_f32 v[2:3], v[110:111], v[10:11], v[2:3] op_sel_hi:[1,0,1]
	v_pk_fma_f32 v[4:5], v[112:113], v[10:11], v[4:5] op_sel_hi:[1,0,1]
	v_add_u32_e32 v0, s15, v0
	v_add_u32_e32 v12, s15, v12
	v_add_u32_e32 v13, s15, v13
	s_sub_i32 s15, 0, s15
	s_add_i32 s14, s14, -1
	s_waitcnt lgkmcnt(0)
	s_barrier
	s_cmp_lg_u32 s14, 0
	s_cbranch_scc1 .Lp4c_blk
	v_add_f32_dpp v62, v32, v32 row_half_mirror row_mask:0xf bank_mask:0xf bound_ctrl:1
	v_add_f32_dpp v63, v33, v33 row_half_mirror row_mask:0xf bank_mask:0xf bound_ctrl:1
	v_cndmask_b32_e64 v48, v62, v63, s[10:11]
	v_add_f32_dpp v62, v34, v34 row_half_mirror row_mask:0xf bank_mask:0xf bound_ctrl:1
	v_add_f32_dpp v63, v35, v35 row_half_mirror row_mask:0xf bank_mask:0xf bound_ctrl:1
	v_cndmask_b32_e64 v49, v62, v63, s[10:11]
	v_add_f32_dpp v62, v36, v36 row_half_mirror row_mask:0xf bank_mask:0xf bound_ctrl:1
	v_add_f32_dpp v63, v37, v37 row_half_mirror row_mask:0xf bank_mask:0xf bound_ctrl:1
	v_cndmask_b32_e64 v50, v62, v63, s[10:11]
	v_add_f32_dpp v62, v38, v38 row_half_mirror row_mask:0xf bank_mask:0xf bound_ctrl:1
	v_add_f32_dpp v63, v39, v39 row_half_mirror row_mask:0xf bank_mask:0xf bound_ctrl:1
	v_cndmask_b32_e64 v51, v62, v63, s[10:11]
	v_add_f32_dpp v62, v40, v40 row_half_mirror row_mask:0xf bank_mask:0xf bound_ctrl:1
	v_add_f32_dpp v63, v41, v41 row_half_mirror row_mask:0xf bank_mask:0xf bound_ctrl:1
	v_cndmask_b32_e64 v52, v62, v63, s[10:11]
	v_add_f32_dpp v62, v42, v42 row_half_mirror row_mask:0xf bank_mask:0xf bound_ctrl:1
	v_add_f32_dpp v63, v43, v43 row_half_mirror row_mask:0xf bank_mask:0xf bound_ctrl:1
	v_cndmask_b32_e64 v53, v62, v63, s[10:11]
	v_add_f32_dpp v62, v44, v44 row_half_mirror row_mask:0xf bank_mask:0xf bound_ctrl:1
	v_add_f32_dpp v63, v45, v45 row_half_mirror row_mask:0xf bank_mask:0xf bound_ctrl:1
	v_cndmask_b32_e64 v54, v62, v63, s[10:11]
	v_add_f32_dpp v62, v46, v46 row_half_mirror row_mask:0xf bank_mask:0xf bound_ctrl:1
	v_add_f32_dpp v63, v47, v47 row_half_mirror row_mask:0xf bank_mask:0xf bound_ctrl:1
	v_cndmask_b32_e64 v55, v62, v63, s[10:11]
	v_add_f32_dpp v62, v48, v48 quad_perm:[1,0,3,2] row_mask:0xf bank_mask:0xf bound_ctrl:1
	v_add_f32_dpp v63, v49, v49 quad_perm:[1,0,3,2] row_mask:0xf bank_mask:0xf bound_ctrl:1
	v_cndmask_b32_e64 v56, v62, v63, s[22:23]
	v_add_f32_dpp v62, v50, v50 quad_perm:[1,0,3,2] row_mask:0xf bank_mask:0xf bound_ctrl:1
	v_add_f32_dpp v63, v51, v51 quad_perm:[1,0,3,2] row_mask:0xf bank_mask:0xf bound_ctrl:1
	v_cndmask_b32_e64 v57, v62, v63, s[22:23]
	v_add_f32_dpp v62, v52, v52 quad_perm:[1,0,3,2] row_mask:0xf bank_mask:0xf bound_ctrl:1
	v_add_f32_dpp v63, v53, v53 quad_perm:[1,0,3,2] row_mask:0xf bank_mask:0xf bound_ctrl:1
	v_cndmask_b32_e64 v58, v62, v63, s[22:23]
	v_add_f32_dpp v62, v54, v54 quad_perm:[1,0,3,2] row_mask:0xf bank_mask:0xf bound_ctrl:1
	v_add_f32_dpp v63, v55, v55 quad_perm:[1,0,3,2] row_mask:0xf bank_mask:0xf bound_ctrl:1
	v_cndmask_b32_e64 v59, v62, v63, s[22:23]
	v_add_f32_dpp v62, v56, v56 quad_perm:[2,3,0,1] row_mask:0xf bank_mask:0xf bound_ctrl:1
	v_add_f32_dpp v63, v57, v57 quad_perm:[2,3,0,1] row_mask:0xf bank_mask:0xf bound_ctrl:1
	v_cndmask_b32_e64 v60, v62, v63, s[26:27]
	v_add_f32_dpp v62, v58, v58 quad_perm:[2,3,0,1] row_mask:0xf bank_mask:0xf bound_ctrl:1
	v_add_f32_dpp v63, v59, v59 quad_perm:[2,3,0,1] row_mask:0xf bank_mask:0xf bound_ctrl:1
	v_cndmask_b32_e64 v61, v62, v63, s[26:27]
	v_add_f32_dpp v62, v60, v60 row_mirror row_mask:0xf bank_mask:0xf bound_ctrl:1
	s_nop 0
	v_add_f32_dpp v63, v61, v61 row_mirror row_mask:0xf bank_mask:0xf bound_ctrl:1
	v_cndmask_b32_e64 v64, v62, v63, s[56:57]
	v_add_f32_e32 v64, v64, v66
	global_store_dword v14, v64, s[8:9]
	s_setprio 0
	global_store_dwordx4 v15, v[2:5], s[58:59]
	s_branch .LBB0_672
